# barsink 3 instead of 2 on the v111 stack (pre-MFMA barrier sunk below the segment's first three MFMAs)
# baseline (speedup 1.0000x reference)
.LBB0_200:
	s_add_u32 s46, s6, 0x200
	s_addc_u32 s47, s7, 0
	s_ashr_i32 s91, s90, 31
	s_lshl_b64 s[2:3], s[90:91], 19
	v_readlane_b32 s8, v254, 62
	v_readlane_b32 s9, v254, 63
	s_add_u32 s94, s8, s2
	s_addc_u32 s95, s9, s3
	s_and_b64 s[2:3], s[0:1], exec
	s_cselect_b32 s48, s95, s25
	s_cselect_b32 s49, s94, s24
	s_ashr_i32 s89, s88, 31
	s_lshl_b64 s[2:3], s[88:89], 19
	s_add_u32 s92, s68, s2
	s_addc_u32 s93, s69, s3
	s_and_b64 s[2:3], s[0:1], exec
	s_cselect_b32 s89, s93, s7
	s_cselect_b32 s91, s92, s6
	v_lshl_add_u64 v[140:141], s[24:25], 0, v[130:131]
	s_add_i32 vcc_lo, s11, 0xc000
	v_lshl_add_u64 v[66:67], v[140:141], 0, s[42:43]
	s_mov_b32 m0, vcc_lo
	s_add_i32 vcc_hi, s11, 0xe000
	global_load_lds_dwordx4 v[66:67], off
	v_lshl_add_u64 v[66:67], v[140:141], 0, s[44:45]
	s_mov_b32 m0, vcc_hi
	s_nop 0
	global_load_lds_dwordx4 v[66:67], off
	s_waitcnt vmcnt(8)
	s_waitcnt lgkmcnt(0)
	s_waitcnt lgkmcnt(0)
	v_mfma_f32_16x16x32_bf16 v[86:89], v[10:13], v[50:53], 0
	v_mfma_f32_16x16x32_bf16 v[90:93], v[14:17], v[54:57], v[86:89]
	v_mfma_f32_16x16x32_bf16 v[86:89], v[2:5], v[58:61], 0
	s_barrier
	s_setprio 1
	v_mfma_f32_16x16x32_bf16 v[66:69], v[2:5], v[34:37], 0
	v_mfma_f32_16x16x32_bf16 v[70:73], v[10:13], v[34:37], 0
	v_mfma_f32_16x16x32_bf16 v[74:77], v[2:5], v[42:45], 0
	v_mfma_f32_16x16x32_bf16 v[78:81], v[10:13], v[42:45], 0
	v_mfma_f32_16x16x32_bf16 v[82:85], v[2:5], v[50:53], 0
	v_mfma_f32_16x16x32_bf16 v[94:97], v[6:9], v[62:65], v[86:89]
	v_mfma_f32_16x16x32_bf16 v[86:89], v[10:13], v[58:61], 0
	v_mfma_f32_16x16x32_bf16 v[66:69], v[6:9], v[38:41], v[66:69]
	v_mfma_f32_16x16x32_bf16 v[70:73], v[14:17], v[38:41], v[70:73]
	v_mfma_f32_16x16x32_bf16 v[74:77], v[6:9], v[46:49], v[74:77]
	v_mfma_f32_16x16x32_bf16 v[78:81], v[14:17], v[46:49], v[78:81]
	v_mfma_f32_16x16x32_bf16 v[82:85], v[6:9], v[54:57], v[82:85]
	v_mfma_f32_16x16x32_bf16 v[106:109], v[14:17], v[62:65], v[86:89]
	s_setprio 0
	s_setprio 1
	v_mfma_f32_16x16x32_bf16 v[86:89], v[18:21], v[34:37], 0
	v_mfma_f32_16x16x32_bf16 v[34:37], v[26:29], v[34:37], 0
	v_mfma_f32_16x16x32_bf16 v[110:113], v[22:25], v[38:41], v[86:89]
	v_mfma_f32_16x16x32_bf16 v[34:37], v[30:33], v[38:41], v[34:37]
	v_mfma_f32_16x16x32_bf16 v[38:41], v[18:21], v[42:45], 0
	v_mfma_f32_16x16x32_bf16 v[42:45], v[26:29], v[42:45], 0
	v_mfma_f32_16x16x32_bf16 v[38:41], v[22:25], v[46:49], v[38:41]
	v_mfma_f32_16x16x32_bf16 v[42:45], v[30:33], v[46:49], v[42:45]
	v_mfma_f32_16x16x32_bf16 v[46:49], v[18:21], v[50:53], 0
	v_mfma_f32_16x16x32_bf16 v[50:53], v[26:29], v[50:53], 0
	v_mfma_f32_16x16x32_bf16 v[46:49], v[22:25], v[54:57], v[46:49]
	v_mfma_f32_16x16x32_bf16 v[50:53], v[30:33], v[54:57], v[50:53]
	v_mfma_f32_16x16x32_bf16 v[54:57], v[18:21], v[58:61], 0
	v_mfma_f32_16x16x32_bf16 v[58:61], v[26:29], v[58:61], 0
	v_mfma_f32_16x16x32_bf16 v[54:57], v[22:25], v[62:65], v[54:57]
	v_mfma_f32_16x16x32_bf16 v[58:61], v[30:33], v[62:65], v[58:61]
	s_setprio 0
	s_barrier
	v_lshl_add_u64 v[184:185], s[6:7], 0, v[132:133]
	s_add_i32 s8, s96, s51
	v_lshl_add_u64 v[150:151], v[184:185], 0, s[64:65]
	s_mov_b32 m0, s8
	s_add_i32 s9, s8, 0x2000
	ds_read_b128 v[62:65], v147 offset:16384
	ds_read_b128 v[86:89], v147 offset:17408
	ds_read_b128 v[98:101], v147 offset:18432
	ds_read_b128 v[102:105], v147 offset:19456
	ds_read_b128 v[114:117], v147 offset:20480
	ds_read_b128 v[118:121], v147 offset:21504
	ds_read_b128 v[122:125], v147 offset:22528
	ds_read_b128 v[126:129], v147 offset:23552
	global_load_lds_dwordx4 v[150:151], off
	v_lshl_add_u64 v[150:151], v[184:185], 0, s[66:67]
	s_mov_b32 m0, s9
	s_add_i32 s33, s97, s51
	global_load_lds_dwordx4 v[150:151], off
	v_lshl_add_u64 v[150:151], v[184:185], 0, s[72:73]
	s_mov_b32 m0, s33
	s_add_i32 s2, s33, 0x2000
	global_load_lds_dwordx4 v[150:151], off
	v_lshl_add_u64 v[150:151], v[184:185], 0, s[74:75]
	s_mov_b32 m0, s2
	s_nop 0
	global_load_lds_dwordx4 v[150:151], off
	v_lshl_add_u64 v[150:151], v[140:141], 0, s[64:65]
	s_mov_b32 m0, s11
	s_nop 0
	global_load_lds_dwordx4 v[150:151], off
	v_lshl_add_u64 v[150:151], v[140:141], 0, s[66:67]
	s_mov_b32 m0, s54
	s_nop 0
	global_load_lds_dwordx4 v[150:151], off
	s_waitcnt vmcnt(8)
	s_waitcnt lgkmcnt(0)
	s_waitcnt lgkmcnt(0)
	v_mfma_f32_16x16x32_bf16 v[150:153], v[2:5], v[62:65], 0
	v_mfma_f32_16x16x32_bf16 v[160:163], v[2:5], v[98:101], 0
	v_mfma_f32_16x16x32_bf16 v[168:171], v[2:5], v[114:117], 0
	s_barrier
	s_setprio 1
	v_mfma_f32_16x16x32_bf16 v[2:5], v[2:5], v[122:125], 0
	v_mfma_f32_16x16x32_bf16 v[152:155], v[6:9], v[86:89], v[150:153]
	v_mfma_f32_16x16x32_bf16 v[160:163], v[6:9], v[102:105], v[160:163]
	v_mfma_f32_16x16x32_bf16 v[168:171], v[6:9], v[118:121], v[168:171]
	v_mfma_f32_16x16x32_bf16 v[2:5], v[6:9], v[126:129], v[2:5]
	v_mfma_f32_16x16x32_bf16 v[6:9], v[10:13], v[122:125], 0
	v_mfma_f32_16x16x32_bf16 v[156:159], v[10:13], v[62:65], 0
	v_mfma_f32_16x16x32_bf16 v[164:167], v[10:13], v[98:101], 0
	v_mfma_f32_16x16x32_bf16 v[172:175], v[10:13], v[114:117], 0
	v_mfma_f32_16x16x32_bf16 v[10:13], v[14:17], v[126:129], v[6:9]
	v_mfma_f32_16x16x32_bf16 v[156:159], v[14:17], v[86:89], v[156:159]
	v_mfma_f32_16x16x32_bf16 v[164:167], v[14:17], v[102:105], v[164:167]
	v_mfma_f32_16x16x32_bf16 v[172:175], v[14:17], v[118:121], v[172:175]
	s_setprio 0
	s_setprio 1
	v_mfma_f32_16x16x32_bf16 v[6:9], v[18:21], v[62:65], 0
	v_mfma_f32_16x16x32_bf16 v[14:17], v[22:25], v[86:89], v[6:9]
	v_mfma_f32_16x16x32_bf16 v[6:9], v[26:29], v[62:65], 0
	v_mfma_f32_16x16x32_bf16 v[176:179], v[30:33], v[86:89], v[6:9]
	v_mfma_f32_16x16x32_bf16 v[6:9], v[18:21], v[98:101], 0
	v_mfma_f32_16x16x32_bf16 v[180:183], v[22:25], v[102:105], v[6:9]
	v_mfma_f32_16x16x32_bf16 v[6:9], v[26:29], v[98:101], 0
	v_mfma_f32_16x16x32_bf16 v[188:191], v[30:33], v[102:105], v[6:9]
	v_mfma_f32_16x16x32_bf16 v[6:9], v[18:21], v[114:117], 0
	v_mfma_f32_16x16x32_bf16 v[192:195], v[22:25], v[118:121], v[6:9]
	v_mfma_f32_16x16x32_bf16 v[6:9], v[26:29], v[114:117], 0
	v_mfma_f32_16x16x32_bf16 v[196:199], v[30:33], v[118:121], v[6:9]
	v_mfma_f32_16x16x32_bf16 v[6:9], v[18:21], v[122:125], 0
	v_mfma_f32_16x16x32_bf16 v[200:203], v[22:25], v[126:129], v[6:9]
	v_mfma_f32_16x16x32_bf16 v[6:9], v[26:29], v[122:125], 0
	v_mfma_f32_16x16x32_bf16 v[204:207], v[30:33], v[126:129], v[6:9]
	s_setprio 0
	s_barrier
	s_add_i32 s3, 0, 0x18000
	s_add_i32 s35, 0, 0x1c000
	v_add_u32_e32 v149, s3, v144
	v_add_u32_e32 v150, s35, v144
	s_nop 0
	ds_read_b128 v[6:9], v149
	ds_read_b128 v[26:29], v149 offset:1024
	ds_read_b128 v[30:33], v149 offset:2048
	ds_read_b128 v[208:211], v149 offset:3072
	ds_read_b128 v[212:215], v150
	ds_read_b128 v[216:219], v150 offset:1024
	ds_read_b128 v[220:223], v150 offset:2048
	ds_read_b128 v[224:227], v150 offset:3072
	s_mov_b32 m0, s55
	v_lshl_add_u64 v[62:63], v[140:141], 0, s[72:73]
	ds_read_b128 v[18:21], v147 offset:32768
	ds_read_b128 v[22:25], v147 offset:33792
	ds_read_b128 v[228:231], v147 offset:34816
	ds_read_b128 v[232:235], v147 offset:35840
	ds_read_b128 v[236:239], v147 offset:36864
	ds_read_b128 v[240:243], v147 offset:37888
	ds_read_b128 v[244:247], v147 offset:38912
	ds_read_b128 v[248:251], v147 offset:39936
	global_load_lds_dwordx4 v[62:63], off
	v_lshl_add_u64 v[62:63], v[140:141], 0, s[74:75]
	s_mov_b32 m0, s56
	s_nop 0
	global_load_lds_dwordx4 v[62:63], off
	s_waitcnt vmcnt(8)
	s_waitcnt lgkmcnt(0)
	s_waitcnt lgkmcnt(0)
	v_mfma_f32_16x16x32_bf16 v[62:65], v[6:9], v[18:21], v[66:69]
	v_mfma_f32_16x16x32_bf16 v[118:121], v[26:29], v[22:25], v[62:65]
	v_mfma_f32_16x16x32_bf16 v[62:65], v[30:33], v[18:21], v[70:73]
	s_barrier
	s_setprio 1
	v_mfma_f32_16x16x32_bf16 v[114:117], v[208:211], v[22:25], v[62:65]
	v_mfma_f32_16x16x32_bf16 v[62:65], v[6:9], v[228:231], v[74:77]
	v_mfma_f32_16x16x32_bf16 v[102:105], v[26:29], v[232:235], v[62:65]
	v_mfma_f32_16x16x32_bf16 v[62:65], v[30:33], v[228:231], v[78:81]
	v_mfma_f32_16x16x32_bf16 v[98:101], v[208:211], v[232:235], v[62:65]
	v_mfma_f32_16x16x32_bf16 v[62:65], v[6:9], v[236:239], v[82:85]
	v_mfma_f32_16x16x32_bf16 v[86:89], v[26:29], v[240:243], v[62:65]
	v_mfma_f32_16x16x32_bf16 v[62:65], v[30:33], v[236:239], v[90:93]
	v_mfma_f32_16x16x32_bf16 v[82:85], v[208:211], v[240:243], v[62:65]
	v_mfma_f32_16x16x32_bf16 v[62:65], v[6:9], v[244:247], v[94:97]
	v_mfma_f32_16x16x32_bf16 v[70:73], v[26:29], v[248:251], v[62:65]
	v_mfma_f32_16x16x32_bf16 v[62:65], v[30:33], v[244:247], v[106:109]
	v_mfma_f32_16x16x32_bf16 v[62:65], v[208:211], v[248:251], v[62:65]
	s_setprio 0
	s_setprio 1
	v_mfma_f32_16x16x32_bf16 v[66:69], v[212:215], v[18:21], v[110:113]
	v_mfma_f32_16x16x32_bf16 v[18:21], v[220:223], v[18:21], v[34:37]
	v_mfma_f32_16x16x32_bf16 v[122:125], v[224:227], v[22:25], v[18:21]
	v_mfma_f32_16x16x32_bf16 v[18:21], v[212:215], v[228:231], v[38:41]
	v_mfma_f32_16x16x32_bf16 v[110:113], v[216:219], v[232:235], v[18:21]
	v_mfma_f32_16x16x32_bf16 v[18:21], v[220:223], v[228:231], v[42:45]
	v_mfma_f32_16x16x32_bf16 v[106:109], v[224:227], v[232:235], v[18:21]
	v_mfma_f32_16x16x32_bf16 v[18:21], v[212:215], v[236:239], v[46:49]
	v_mfma_f32_16x16x32_bf16 v[94:97], v[216:219], v[240:243], v[18:21]
	v_mfma_f32_16x16x32_bf16 v[18:21], v[220:223], v[236:239], v[50:53]
	v_mfma_f32_16x16x32_bf16 v[90:93], v[224:227], v[240:243], v[18:21]
	v_mfma_f32_16x16x32_bf16 v[18:21], v[212:215], v[244:247], v[54:57]
	v_mfma_f32_16x16x32_bf16 v[78:81], v[216:219], v[248:251], v[18:21]
	v_mfma_f32_16x16x32_bf16 v[18:21], v[220:223], v[244:247], v[58:61]
	v_mfma_f32_16x16x32_bf16 v[126:129], v[216:219], v[22:25], v[66:69]
	v_mfma_f32_16x16x32_bf16 v[74:77], v[224:227], v[248:251], v[18:21]
	s_setprio 0
	s_barrier
	s_add_i32 s3, s3, s51
	s_nop 2
	v_lshl_add_u64 v[18:19], v[184:185], 0, s[78:79]
	s_mov_b32 m0, s3
	s_add_i32 s34, s3, 0x2000
	ds_read_b128 v[42:45], v147 offset:49152
	ds_read_b128 v[46:49], v147 offset:50176
	ds_read_b128 v[228:231], v147 offset:51200
	ds_read_b128 v[232:235], v147 offset:52224
	ds_read_b128 v[236:239], v147 offset:53248
	ds_read_b128 v[240:243], v147 offset:54272
	ds_read_b128 v[244:247], v147 offset:55296
	ds_read_b128 v[248:251], v147 offset:56320
	global_load_lds_dwordx4 v[18:19], off
	v_lshl_add_u64 v[18:19], v[184:185], 0, s[82:83]
	s_mov_b32 m0, s34
	s_add_i32 s35, s35, s51
	global_load_lds_dwordx4 v[18:19], off
	v_lshl_add_u64 v[18:19], v[184:185], 0, s[84:85]
	s_mov_b32 m0, s35
	s_add_i32 s36, s35, 0x2000
	global_load_lds_dwordx4 v[18:19], off
	v_lshl_add_u64 v[18:19], v[184:185], 0, s[86:87]
	s_mov_b32 m0, s36
	s_nop 0
	global_load_lds_dwordx4 v[18:19], off
	v_lshl_add_u64 v[18:19], v[140:141], 0, s[78:79]
	s_mov_b32 m0, s57
	s_nop 0
	global_load_lds_dwordx4 v[18:19], off
	v_lshl_add_u64 v[18:19], v[140:141], 0, s[82:83]
	s_mov_b32 m0, s58
	s_nop 0
	global_load_lds_dwordx4 v[18:19], off
	s_waitcnt vmcnt(8)
	s_waitcnt lgkmcnt(0)
	s_waitcnt lgkmcnt(0)
	v_mfma_f32_16x16x32_bf16 v[18:21], v[6:9], v[42:45], v[152:155]
	v_mfma_f32_16x16x32_bf16 v[54:57], v[26:29], v[46:49], v[18:21]
	v_mfma_f32_16x16x32_bf16 v[18:21], v[30:33], v[42:45], v[156:159]
	s_barrier
	s_setprio 1
	v_mfma_f32_16x16x32_bf16 v[50:53], v[208:211], v[46:49], v[18:21]
	v_mfma_f32_16x16x32_bf16 v[18:21], v[6:9], v[228:231], v[160:163]
	v_mfma_f32_16x16x32_bf16 v[38:41], v[26:29], v[232:235], v[18:21]
	v_mfma_f32_16x16x32_bf16 v[18:21], v[30:33], v[228:231], v[164:167]
	v_mfma_f32_16x16x32_bf16 v[34:37], v[208:211], v[232:235], v[18:21]
	v_mfma_f32_16x16x32_bf16 v[18:21], v[6:9], v[236:239], v[168:171]
	v_mfma_f32_16x16x32_bf16 v[2:5], v[6:9], v[244:247], v[2:5]
	v_mfma_f32_16x16x32_bf16 v[22:25], v[26:29], v[240:243], v[18:21]
	v_mfma_f32_16x16x32_bf16 v[18:21], v[30:33], v[236:239], v[172:175]
	v_mfma_f32_16x16x32_bf16 v[6:9], v[26:29], v[248:251], v[2:5]
	v_mfma_f32_16x16x32_bf16 v[2:5], v[30:33], v[244:247], v[10:13]
	v_mfma_f32_16x16x32_bf16 v[18:21], v[208:211], v[240:243], v[18:21]
	v_mfma_f32_16x16x32_bf16 v[2:5], v[208:211], v[248:251], v[2:5]
	s_setprio 0
	s_setprio 1
	v_mfma_f32_16x16x32_bf16 v[10:13], v[212:215], v[42:45], v[14:17]
	v_mfma_f32_16x16x32_bf16 v[66:69], v[216:219], v[46:49], v[10:13]
	v_mfma_f32_16x16x32_bf16 v[10:13], v[220:223], v[42:45], v[176:179]
	v_mfma_f32_16x16x32_bf16 v[58:61], v[224:227], v[46:49], v[10:13]
	v_mfma_f32_16x16x32_bf16 v[10:13], v[212:215], v[228:231], v[180:183]
	v_mfma_f32_16x16x32_bf16 v[46:49], v[216:219], v[232:235], v[10:13]
	v_mfma_f32_16x16x32_bf16 v[10:13], v[220:223], v[228:231], v[188:191]
	v_mfma_f32_16x16x32_bf16 v[42:45], v[224:227], v[232:235], v[10:13]
	v_mfma_f32_16x16x32_bf16 v[10:13], v[212:215], v[236:239], v[192:195]
	v_mfma_f32_16x16x32_bf16 v[30:33], v[216:219], v[240:243], v[10:13]
	v_mfma_f32_16x16x32_bf16 v[10:13], v[220:223], v[236:239], v[196:199]
	v_mfma_f32_16x16x32_bf16 v[26:29], v[224:227], v[240:243], v[10:13]
	v_mfma_f32_16x16x32_bf16 v[10:13], v[212:215], v[244:247], v[200:203]
	v_mfma_f32_16x16x32_bf16 v[14:17], v[216:219], v[248:251], v[10:13]
	v_mfma_f32_16x16x32_bf16 v[10:13], v[220:223], v[244:247], v[204:207]
	v_mfma_f32_16x16x32_bf16 v[10:13], v[224:227], v[248:251], v[10:13]
	s_setprio 0
	s_barrier
	v_lshl_add_u64 v[140:141], s[24:25], 0, v[134:135]
	s_mov_b32 s37, 0
	s_mov_b64 s[6:7], 0
.LBB0_201:
	ds_read_b128 v[152:155], v145
	ds_read_b128 v[156:159], v145 offset:1024
	ds_read_b128 v[160:163], v145 offset:2048
	ds_read_b128 v[164:167], v145 offset:3072
	ds_read_b128 v[168:171], v146
	ds_read_b128 v[172:175], v146 offset:1024
	ds_read_b128 v[176:179], v146 offset:2048
	ds_read_b128 v[180:183], v146 offset:3072
	s_add_u32 s12, s24, s6
	s_addc_u32 s13, s25, s7
	s_add_u32 s12, s12, 0x200
	s_addc_u32 s13, s13, 0
	s_add_u32 s14, s46, s6
	s_addc_u32 s15, s47, s7
	s_cmpk_eq_i32 s6, 0x600
	s_cselect_b32 s81, s48, s13
	s_cselect_b32 s80, s49, s12
	s_cselect_b32 s13, s89, s15
	s_cselect_b32 s12, s91, s14
	v_lshl_add_u64 v[184:185], v[140:141], 0, s[6:7]
	s_mov_b32 m0, vcc_lo
	v_lshl_add_u64 v[220:221], v[184:185], 0, s[84:85]
	ds_read_b128 v[188:191], v147
	ds_read_b128 v[192:195], v147 offset:1024
	ds_read_b128 v[196:199], v147 offset:2048
	ds_read_b128 v[200:203], v147 offset:3072
	ds_read_b128 v[204:207], v147 offset:4096
	ds_read_b128 v[208:211], v147 offset:5120
	ds_read_b128 v[212:215], v147 offset:6144
	ds_read_b128 v[216:219], v147 offset:7168
	global_load_lds_dwordx4 v[220:221], off
	v_lshl_add_u64 v[184:185], v[184:185], 0, s[86:87]
	s_mov_b32 m0, vcc_hi
	s_nop 0
	global_load_lds_dwordx4 v[184:185], off
	s_waitcnt vmcnt(8)
	s_waitcnt lgkmcnt(0)
	s_waitcnt lgkmcnt(0)
	v_mfma_f32_16x16x32_bf16 v[118:121], v[152:155], v[188:191], v[118:121]
	v_mfma_f32_16x16x32_bf16 v[114:117], v[160:163], v[188:191], v[114:117]
	v_mfma_f32_16x16x32_bf16 v[102:105], v[152:155], v[196:199], v[102:105]
	s_barrier
	s_setprio 1
	v_mfma_f32_16x16x32_bf16 v[98:101], v[160:163], v[196:199], v[98:101]
	v_mfma_f32_16x16x32_bf16 v[86:89], v[152:155], v[204:207], v[86:89]
	v_mfma_f32_16x16x32_bf16 v[82:85], v[160:163], v[204:207], v[82:85]
	v_mfma_f32_16x16x32_bf16 v[70:73], v[152:155], v[212:215], v[70:73]
	v_mfma_f32_16x16x32_bf16 v[62:65], v[160:163], v[212:215], v[62:65]
	v_mfma_f32_16x16x32_bf16 v[118:121], v[156:159], v[192:195], v[118:121]
	v_mfma_f32_16x16x32_bf16 v[114:117], v[164:167], v[192:195], v[114:117]
	v_mfma_f32_16x16x32_bf16 v[102:105], v[156:159], v[200:203], v[102:105]
	v_mfma_f32_16x16x32_bf16 v[98:101], v[164:167], v[200:203], v[98:101]
	v_mfma_f32_16x16x32_bf16 v[86:89], v[156:159], v[208:211], v[86:89]
	v_mfma_f32_16x16x32_bf16 v[82:85], v[164:167], v[208:211], v[82:85]
	v_mfma_f32_16x16x32_bf16 v[70:73], v[156:159], v[216:219], v[70:73]
	v_mfma_f32_16x16x32_bf16 v[62:65], v[164:167], v[216:219], v[62:65]
	s_setprio 0
	s_setprio 1
	v_mfma_f32_16x16x32_bf16 v[126:129], v[168:171], v[188:191], v[126:129]
	v_mfma_f32_16x16x32_bf16 v[122:125], v[176:179], v[188:191], v[122:125]
	v_mfma_f32_16x16x32_bf16 v[110:113], v[168:171], v[196:199], v[110:113]
	v_mfma_f32_16x16x32_bf16 v[106:109], v[176:179], v[196:199], v[106:109]
	v_mfma_f32_16x16x32_bf16 v[94:97], v[168:171], v[204:207], v[94:97]
	v_mfma_f32_16x16x32_bf16 v[90:93], v[176:179], v[204:207], v[90:93]
	v_mfma_f32_16x16x32_bf16 v[78:81], v[168:171], v[212:215], v[78:81]
	v_mfma_f32_16x16x32_bf16 v[74:77], v[176:179], v[212:215], v[74:77]
	v_mfma_f32_16x16x32_bf16 v[126:129], v[172:175], v[192:195], v[126:129]
	v_mfma_f32_16x16x32_bf16 v[122:125], v[180:183], v[192:195], v[122:125]
	v_mfma_f32_16x16x32_bf16 v[110:113], v[172:175], v[200:203], v[110:113]
	v_mfma_f32_16x16x32_bf16 v[106:109], v[180:183], v[200:203], v[106:109]
	v_mfma_f32_16x16x32_bf16 v[94:97], v[172:175], v[208:211], v[94:97]
	v_mfma_f32_16x16x32_bf16 v[90:93], v[180:183], v[208:211], v[90:93]
	v_mfma_f32_16x16x32_bf16 v[78:81], v[172:175], v[216:219], v[78:81]
	v_mfma_f32_16x16x32_bf16 v[74:77], v[180:183], v[216:219], v[74:77]
	s_setprio 0
	s_barrier
	s_mov_b32 m0, s8
	v_lshl_add_u64 v[184:185], s[12:13], 0, v[132:133]
	ds_read_b128 v[188:191], v147 offset:16384
	ds_read_b128 v[192:195], v147 offset:17408
	ds_read_b128 v[196:199], v147 offset:18432
	ds_read_b128 v[200:203], v147 offset:19456
	ds_read_b128 v[204:207], v147 offset:20480
	ds_read_b128 v[208:211], v147 offset:21504
	ds_read_b128 v[212:215], v147 offset:22528
	ds_read_b128 v[216:219], v147 offset:23552
	global_load_lds_dwordx4 v[184:185], off
	v_lshl_add_u64 v[220:221], v[184:185], 0, s[26:27]
	s_mov_b32 m0, s9
	s_nop 0
	global_load_lds_dwordx4 v[220:221], off
	v_lshl_add_u64 v[220:221], v[184:185], 0, s[28:29]
	s_mov_b32 m0, s33
	s_nop 0
	global_load_lds_dwordx4 v[220:221], off
	v_lshl_add_u64 v[220:221], v[184:185], 0, s[30:31]
	s_mov_b32 m0, s2
	s_nop 0
	global_load_lds_dwordx4 v[220:221], off
	v_lshl_add_u64 v[220:221], s[80:81], 0, v[130:131]
	s_mov_b32 m0, s11
	v_lshl_add_u64 v[222:223], v[220:221], 0, s[26:27]
	global_load_lds_dwordx4 v[220:221], off
	s_mov_b32 m0, s54
	s_nop 0
	global_load_lds_dwordx4 v[222:223], off
	s_waitcnt vmcnt(8)
	s_waitcnt lgkmcnt(0)
	s_waitcnt lgkmcnt(0)
	v_mfma_f32_16x16x32_bf16 v[54:57], v[152:155], v[188:191], v[54:57]
	v_mfma_f32_16x16x32_bf16 v[50:53], v[160:163], v[188:191], v[50:53]
	v_mfma_f32_16x16x32_bf16 v[38:41], v[152:155], v[196:199], v[38:41]
	s_barrier
	s_setprio 1
	v_mfma_f32_16x16x32_bf16 v[34:37], v[160:163], v[196:199], v[34:37]
	v_mfma_f32_16x16x32_bf16 v[22:25], v[152:155], v[204:207], v[22:25]
	v_mfma_f32_16x16x32_bf16 v[18:21], v[160:163], v[204:207], v[18:21]
	v_mfma_f32_16x16x32_bf16 v[6:9], v[152:155], v[212:215], v[6:9]
	v_mfma_f32_16x16x32_bf16 v[2:5], v[160:163], v[212:215], v[2:5]
	v_mfma_f32_16x16x32_bf16 v[54:57], v[156:159], v[192:195], v[54:57]
	v_mfma_f32_16x16x32_bf16 v[50:53], v[164:167], v[192:195], v[50:53]
	v_mfma_f32_16x16x32_bf16 v[38:41], v[156:159], v[200:203], v[38:41]
	v_mfma_f32_16x16x32_bf16 v[34:37], v[164:167], v[200:203], v[34:37]
	v_mfma_f32_16x16x32_bf16 v[22:25], v[156:159], v[208:211], v[22:25]
	v_mfma_f32_16x16x32_bf16 v[18:21], v[164:167], v[208:211], v[18:21]
	v_mfma_f32_16x16x32_bf16 v[6:9], v[156:159], v[216:219], v[6:9]
	v_mfma_f32_16x16x32_bf16 v[2:5], v[164:167], v[216:219], v[2:5]
	s_setprio 0
	s_setprio 1
	v_mfma_f32_16x16x32_bf16 v[66:69], v[168:171], v[188:191], v[66:69]
	v_mfma_f32_16x16x32_bf16 v[58:61], v[176:179], v[188:191], v[58:61]
	v_mfma_f32_16x16x32_bf16 v[46:49], v[168:171], v[196:199], v[46:49]
	v_mfma_f32_16x16x32_bf16 v[42:45], v[176:179], v[196:199], v[42:45]
	v_mfma_f32_16x16x32_bf16 v[30:33], v[168:171], v[204:207], v[30:33]
	v_mfma_f32_16x16x32_bf16 v[26:29], v[176:179], v[204:207], v[26:29]
	v_mfma_f32_16x16x32_bf16 v[14:17], v[168:171], v[212:215], v[14:17]
	v_mfma_f32_16x16x32_bf16 v[10:13], v[176:179], v[212:215], v[10:13]
	v_mfma_f32_16x16x32_bf16 v[66:69], v[172:175], v[192:195], v[66:69]
	v_mfma_f32_16x16x32_bf16 v[58:61], v[180:183], v[192:195], v[58:61]
	v_mfma_f32_16x16x32_bf16 v[46:49], v[172:175], v[200:203], v[46:49]
	v_mfma_f32_16x16x32_bf16 v[42:45], v[180:183], v[200:203], v[42:45]
	v_mfma_f32_16x16x32_bf16 v[30:33], v[172:175], v[208:211], v[30:33]
	v_mfma_f32_16x16x32_bf16 v[26:29], v[180:183], v[208:211], v[26:29]
	v_mfma_f32_16x16x32_bf16 v[14:17], v[172:175], v[216:219], v[14:17]
	v_mfma_f32_16x16x32_bf16 v[10:13], v[180:183], v[216:219], v[10:13]
	s_setprio 0
	s_barrier
	ds_read_b128 v[152:155], v149
	ds_read_b128 v[156:159], v149 offset:1024
	ds_read_b128 v[160:163], v149 offset:2048
	ds_read_b128 v[164:167], v149 offset:3072
	ds_read_b128 v[168:171], v150
	ds_read_b128 v[172:175], v150 offset:1024
	ds_read_b128 v[176:179], v150 offset:2048
	ds_read_b128 v[180:183], v150 offset:3072
	s_mov_b32 m0, s55
	v_lshl_add_u64 v[222:223], v[220:221], 0, s[28:29]
	ds_read_b128 v[188:191], v147 offset:32768
	ds_read_b128 v[192:195], v147 offset:33792
	ds_read_b128 v[196:199], v147 offset:34816
	ds_read_b128 v[200:203], v147 offset:35840
	ds_read_b128 v[204:207], v147 offset:36864
	ds_read_b128 v[208:211], v147 offset:37888
	ds_read_b128 v[212:215], v147 offset:38912
	ds_read_b128 v[216:219], v147 offset:39936
	global_load_lds_dwordx4 v[222:223], off
	v_lshl_add_u64 v[222:223], v[220:221], 0, s[30:31]
	s_mov_b32 m0, s56
	s_nop 0
	global_load_lds_dwordx4 v[222:223], off
	s_waitcnt vmcnt(8)
	s_waitcnt lgkmcnt(0)
	s_waitcnt lgkmcnt(0)
	v_mfma_f32_16x16x32_bf16 v[118:121], v[152:155], v[188:191], v[118:121]
	v_mfma_f32_16x16x32_bf16 v[114:117], v[160:163], v[188:191], v[114:117]
	v_mfma_f32_16x16x32_bf16 v[102:105], v[152:155], v[196:199], v[102:105]
	s_barrier
	s_setprio 1
	v_mfma_f32_16x16x32_bf16 v[98:101], v[160:163], v[196:199], v[98:101]
	v_mfma_f32_16x16x32_bf16 v[86:89], v[152:155], v[204:207], v[86:89]
	v_mfma_f32_16x16x32_bf16 v[82:85], v[160:163], v[204:207], v[82:85]
	v_mfma_f32_16x16x32_bf16 v[70:73], v[152:155], v[212:215], v[70:73]
	v_mfma_f32_16x16x32_bf16 v[62:65], v[160:163], v[212:215], v[62:65]
	v_mfma_f32_16x16x32_bf16 v[118:121], v[156:159], v[192:195], v[118:121]
	v_mfma_f32_16x16x32_bf16 v[114:117], v[164:167], v[192:195], v[114:117]
	v_mfma_f32_16x16x32_bf16 v[102:105], v[156:159], v[200:203], v[102:105]
	v_mfma_f32_16x16x32_bf16 v[98:101], v[164:167], v[200:203], v[98:101]
	v_mfma_f32_16x16x32_bf16 v[86:89], v[156:159], v[208:211], v[86:89]
	v_mfma_f32_16x16x32_bf16 v[82:85], v[164:167], v[208:211], v[82:85]
	v_mfma_f32_16x16x32_bf16 v[70:73], v[156:159], v[216:219], v[70:73]
	v_mfma_f32_16x16x32_bf16 v[62:65], v[164:167], v[216:219], v[62:65]
	s_setprio 0
	s_setprio 1
	v_mfma_f32_16x16x32_bf16 v[126:129], v[168:171], v[188:191], v[126:129]
	v_mfma_f32_16x16x32_bf16 v[122:125], v[176:179], v[188:191], v[122:125]
	v_mfma_f32_16x16x32_bf16 v[110:113], v[168:171], v[196:199], v[110:113]
	v_mfma_f32_16x16x32_bf16 v[106:109], v[176:179], v[196:199], v[106:109]
	v_mfma_f32_16x16x32_bf16 v[94:97], v[168:171], v[204:207], v[94:97]
	v_mfma_f32_16x16x32_bf16 v[90:93], v[176:179], v[204:207], v[90:93]
	v_mfma_f32_16x16x32_bf16 v[78:81], v[168:171], v[212:215], v[78:81]
	v_mfma_f32_16x16x32_bf16 v[74:77], v[176:179], v[212:215], v[74:77]
	v_mfma_f32_16x16x32_bf16 v[126:129], v[172:175], v[192:195], v[126:129]
	v_mfma_f32_16x16x32_bf16 v[122:125], v[180:183], v[192:195], v[122:125]
	v_mfma_f32_16x16x32_bf16 v[110:113], v[172:175], v[200:203], v[110:113]
	v_mfma_f32_16x16x32_bf16 v[106:109], v[180:183], v[200:203], v[106:109]
	v_mfma_f32_16x16x32_bf16 v[94:97], v[172:175], v[208:211], v[94:97]
	v_mfma_f32_16x16x32_bf16 v[90:93], v[180:183], v[208:211], v[90:93]
	v_mfma_f32_16x16x32_bf16 v[78:81], v[172:175], v[216:219], v[78:81]
	v_mfma_f32_16x16x32_bf16 v[74:77], v[180:183], v[216:219], v[74:77]
	s_setprio 0
	s_barrier
	s_mov_b32 m0, s3
	v_lshl_add_u64 v[222:223], v[184:185], 0, s[38:39]
	ds_read_b128 v[188:191], v147 offset:49152
	ds_read_b128 v[192:195], v147 offset:50176
	ds_read_b128 v[196:199], v147 offset:51200
	ds_read_b128 v[200:203], v147 offset:52224
	ds_read_b128 v[204:207], v147 offset:53248
	ds_read_b128 v[208:211], v147 offset:54272
	ds_read_b128 v[212:215], v147 offset:55296
	ds_read_b128 v[216:219], v147 offset:56320
	global_load_lds_dwordx4 v[222:223], off
	v_lshl_add_u64 v[222:223], v[184:185], 0, s[40:41]
	s_mov_b32 m0, s34
	s_nop 0
	global_load_lds_dwordx4 v[222:223], off
	v_lshl_add_u64 v[222:223], v[184:185], 0, s[42:43]
	s_mov_b32 m0, s35
	v_lshl_add_u64 v[184:185], v[184:185], 0, s[44:45]
	global_load_lds_dwordx4 v[222:223], off
	s_mov_b32 m0, s36
	s_nop 0
	global_load_lds_dwordx4 v[184:185], off
	v_lshl_add_u64 v[184:185], v[220:221], 0, s[38:39]
	s_mov_b32 m0, s57
	s_nop 0
	global_load_lds_dwordx4 v[184:185], off
	v_lshl_add_u64 v[184:185], v[220:221], 0, s[40:41]
	s_mov_b32 m0, s58
	s_nop 0
	global_load_lds_dwordx4 v[184:185], off
	s_waitcnt vmcnt(8)
	s_waitcnt lgkmcnt(0)
	s_waitcnt lgkmcnt(0)
	v_mfma_f32_16x16x32_bf16 v[54:57], v[152:155], v[188:191], v[54:57]
	v_mfma_f32_16x16x32_bf16 v[50:53], v[160:163], v[188:191], v[50:53]
	v_mfma_f32_16x16x32_bf16 v[38:41], v[152:155], v[196:199], v[38:41]
	s_barrier
	s_setprio 1
	v_mfma_f32_16x16x32_bf16 v[34:37], v[160:163], v[196:199], v[34:37]
	v_mfma_f32_16x16x32_bf16 v[22:25], v[152:155], v[204:207], v[22:25]
	v_mfma_f32_16x16x32_bf16 v[18:21], v[160:163], v[204:207], v[18:21]
	v_mfma_f32_16x16x32_bf16 v[6:9], v[152:155], v[212:215], v[6:9]
	v_mfma_f32_16x16x32_bf16 v[2:5], v[160:163], v[212:215], v[2:5]
	v_mfma_f32_16x16x32_bf16 v[54:57], v[156:159], v[192:195], v[54:57]
	v_mfma_f32_16x16x32_bf16 v[50:53], v[164:167], v[192:195], v[50:53]
	v_mfma_f32_16x16x32_bf16 v[38:41], v[156:159], v[200:203], v[38:41]
	v_mfma_f32_16x16x32_bf16 v[34:37], v[164:167], v[200:203], v[34:37]
	v_mfma_f32_16x16x32_bf16 v[22:25], v[156:159], v[208:211], v[22:25]
	v_mfma_f32_16x16x32_bf16 v[18:21], v[164:167], v[208:211], v[18:21]
	v_mfma_f32_16x16x32_bf16 v[6:9], v[156:159], v[216:219], v[6:9]
	v_mfma_f32_16x16x32_bf16 v[2:5], v[164:167], v[216:219], v[2:5]
	s_setprio 0
	s_setprio 1
	v_mfma_f32_16x16x32_bf16 v[66:69], v[168:171], v[188:191], v[66:69]
	v_mfma_f32_16x16x32_bf16 v[58:61], v[176:179], v[188:191], v[58:61]
	v_mfma_f32_16x16x32_bf16 v[46:49], v[168:171], v[196:199], v[46:49]
	v_mfma_f32_16x16x32_bf16 v[42:45], v[176:179], v[196:199], v[42:45]
	v_mfma_f32_16x16x32_bf16 v[30:33], v[168:171], v[204:207], v[30:33]
	v_mfma_f32_16x16x32_bf16 v[26:29], v[176:179], v[204:207], v[26:29]
	v_mfma_f32_16x16x32_bf16 v[14:17], v[168:171], v[212:215], v[14:17]
	v_mfma_f32_16x16x32_bf16 v[10:13], v[176:179], v[212:215], v[10:13]
	v_mfma_f32_16x16x32_bf16 v[66:69], v[172:175], v[192:195], v[66:69]
	v_mfma_f32_16x16x32_bf16 v[58:61], v[180:183], v[192:195], v[58:61]
	v_mfma_f32_16x16x32_bf16 v[46:49], v[172:175], v[200:203], v[46:49]
	v_mfma_f32_16x16x32_bf16 v[42:45], v[180:183], v[200:203], v[42:45]
	v_mfma_f32_16x16x32_bf16 v[30:33], v[172:175], v[208:211], v[30:33]
	v_mfma_f32_16x16x32_bf16 v[26:29], v[180:183], v[208:211], v[26:29]
	v_mfma_f32_16x16x32_bf16 v[14:17], v[172:175], v[216:219], v[14:17]
	v_mfma_f32_16x16x32_bf16 v[10:13], v[180:183], v[216:219], v[10:13]
	s_setprio 0
	s_barrier
	s_add_i32 s37, s37, 2
	s_add_u32 s6, s6, 0x100
	s_addc_u32 s7, s7, 0
	s_cmp_gt_u32 s37, 13
	s_cbranch_scc0 .LBB0_201
	s_and_b64 vcc, exec, s[62:63]
	s_cbranch_vccz .LBB0_204
	s_barrier

.LBB0_389:
	s_waitcnt lgkmcnt(0)
	ds_read_b128 v[2:5], v218
	ds_read_b128 v[6:9], v218 offset:1024
	ds_read_b128 v[10:13], v218 offset:2048
	ds_read_b128 v[14:17], v218 offset:3072
	ds_read_b128 v[18:21], v219
	ds_read_b128 v[22:25], v219 offset:1024
	ds_read_b128 v[26:29], v219 offset:2048
	ds_read_b128 v[30:33], v219 offset:3072
	s_add_u32 s2, s34, 0x100
	s_addc_u32 s8, s35, 0
	s_add_u32 s11, s26, 0x100
	s_addc_u32 s12, s27, 0
	s_cmp_eq_u32 s55, 2
	s_cselect_b32 s9, s95, s8
	s_cselect_b32 s8, s94, s2
	s_cselect_b32 s13, s97, s12
	s_cselect_b32 s12, s96, s11
	v_lshl_add_u64 v[66:67], s[34:35], 0, v[188:189]
	s_add_i32 s11, s57, 0xc000
	v_lshl_add_u64 v[68:69], v[66:67], 0, s[80:81]
	s_mov_b32 m0, s11
	s_add_i32 s40, s57, 0xe000
	ds_read_b128 v[34:37], v220
	ds_read_b128 v[38:41], v220 offset:1024
	ds_read_b128 v[42:45], v220 offset:2048
	ds_read_b128 v[46:49], v220 offset:3072
	ds_read_b128 v[50:53], v220 offset:4096
	ds_read_b128 v[54:57], v220 offset:5120
	ds_read_b128 v[58:61], v220 offset:6144
	ds_read_b128 v[62:65], v220 offset:7168
	global_load_lds_dwordx4 v[68:69], off
	v_lshl_add_u64 v[66:67], v[66:67], 0, s[84:85]
	s_mov_b32 m0, s40
	s_nop 0
	global_load_lds_dwordx4 v[66:67], off
	s_waitcnt vmcnt(8)
	s_waitcnt lgkmcnt(0)
	s_waitcnt lgkmcnt(0)
	v_mfma_f32_16x16x32_bf16 v[90:93], v[2:5], v[58:61], 0
	v_mfma_f32_16x16x32_bf16 v[66:69], v[2:5], v[34:37], 0
	v_mfma_f32_16x16x32_bf16 v[70:73], v[10:13], v[34:37], 0
	s_barrier
	s_setprio 1
	v_mfma_f32_16x16x32_bf16 v[74:77], v[2:5], v[42:45], 0
	v_mfma_f32_16x16x32_bf16 v[78:81], v[10:13], v[42:45], 0
	v_mfma_f32_16x16x32_bf16 v[82:85], v[2:5], v[50:53], 0
	v_mfma_f32_16x16x32_bf16 v[86:89], v[10:13], v[50:53], 0
	v_mfma_f32_16x16x32_bf16 v[98:101], v[6:9], v[62:65], v[90:93]
	v_mfma_f32_16x16x32_bf16 v[90:93], v[10:13], v[58:61], 0
	v_mfma_f32_16x16x32_bf16 v[66:69], v[6:9], v[38:41], v[66:69]
	v_mfma_f32_16x16x32_bf16 v[70:73], v[14:17], v[38:41], v[70:73]
	v_mfma_f32_16x16x32_bf16 v[74:77], v[6:9], v[46:49], v[74:77]
	v_mfma_f32_16x16x32_bf16 v[78:81], v[14:17], v[46:49], v[78:81]
	v_mfma_f32_16x16x32_bf16 v[82:85], v[6:9], v[54:57], v[82:85]
	v_mfma_f32_16x16x32_bf16 v[86:89], v[14:17], v[54:57], v[86:89]
	v_mfma_f32_16x16x32_bf16 v[102:105], v[14:17], v[62:65], v[90:93]
	s_setprio 0
	s_setprio 1
	v_mfma_f32_16x16x32_bf16 v[90:93], v[18:21], v[34:37], 0
	v_mfma_f32_16x16x32_bf16 v[34:37], v[26:29], v[34:37], 0
	v_mfma_f32_16x16x32_bf16 v[114:117], v[22:25], v[38:41], v[90:93]
	v_mfma_f32_16x16x32_bf16 v[34:37], v[30:33], v[38:41], v[34:37]
	v_mfma_f32_16x16x32_bf16 v[38:41], v[18:21], v[42:45], 0
	v_mfma_f32_16x16x32_bf16 v[42:45], v[26:29], v[42:45], 0
	v_mfma_f32_16x16x32_bf16 v[38:41], v[22:25], v[46:49], v[38:41]
	v_mfma_f32_16x16x32_bf16 v[42:45], v[30:33], v[46:49], v[42:45]
	v_mfma_f32_16x16x32_bf16 v[46:49], v[18:21], v[50:53], 0
	v_mfma_f32_16x16x32_bf16 v[50:53], v[26:29], v[50:53], 0
	v_mfma_f32_16x16x32_bf16 v[46:49], v[22:25], v[54:57], v[46:49]
	v_mfma_f32_16x16x32_bf16 v[50:53], v[30:33], v[54:57], v[50:53]
	v_mfma_f32_16x16x32_bf16 v[54:57], v[18:21], v[58:61], 0
	v_mfma_f32_16x16x32_bf16 v[58:61], v[26:29], v[58:61], 0
	v_mfma_f32_16x16x32_bf16 v[54:57], v[22:25], v[62:65], v[54:57]
	v_mfma_f32_16x16x32_bf16 v[58:61], v[30:33], v[62:65], v[58:61]
	s_setprio 0
	s_barrier
	s_add_i32 s46, s89, s56
	v_lshl_add_u64 v[184:185], s[12:13], 0, v[190:191]
	s_mov_b32 m0, s46
	s_add_i32 s47, s46, 0x2000
	ds_read_b128 v[62:65], v220 offset:16384
	ds_read_b128 v[90:93], v220 offset:17408
	ds_read_b128 v[94:97], v220 offset:18432
	ds_read_b128 v[106:109], v220 offset:19456
	ds_read_b128 v[110:113], v220 offset:20480
	ds_read_b128 v[118:121], v220 offset:21504
	ds_read_b128 v[122:125], v220 offset:22528
	ds_read_b128 v[126:129], v220 offset:23552
	global_load_lds_dwordx4 v[184:185], off
	v_lshl_add_u64 v[130:131], v[184:185], 0, s[24:25]
	s_mov_b32 m0, s47
	s_add_i32 s48, s90, s56
	global_load_lds_dwordx4 v[130:131], off
	v_lshl_add_u64 v[130:131], v[184:185], 0, s[28:29]
	s_mov_b32 m0, s48
	s_add_i32 s49, s48, 0x2000
	global_load_lds_dwordx4 v[130:131], off
	v_lshl_add_u64 v[130:131], v[184:185], 0, s[30:31]
	s_mov_b32 m0, s49
	v_lshl_add_u64 v[250:251], s[8:9], 0, v[188:189]
	global_load_lds_dwordx4 v[130:131], off
	s_mov_b32 m0, s57
	v_lshl_add_u64 v[130:131], v[250:251], 0, s[24:25]
	global_load_lds_dwordx4 v[250:251], off
	s_mov_b32 m0, s58
	s_nop 0
	global_load_lds_dwordx4 v[130:131], off
	s_waitcnt vmcnt(8)
	s_waitcnt lgkmcnt(0)
	s_waitcnt lgkmcnt(0)
	v_mfma_f32_16x16x32_bf16 v[130:133], v[2:5], v[62:65], 0
	v_mfma_f32_16x16x32_bf16 v[140:143], v[2:5], v[94:97], 0
	v_mfma_f32_16x16x32_bf16 v[148:151], v[2:5], v[110:113], 0
	s_barrier
	s_setprio 1
	v_mfma_f32_16x16x32_bf16 v[2:5], v[2:5], v[122:125], 0
	v_mfma_f32_16x16x32_bf16 v[132:135], v[6:9], v[90:93], v[130:133]
	v_mfma_f32_16x16x32_bf16 v[140:143], v[6:9], v[106:109], v[140:143]
	v_mfma_f32_16x16x32_bf16 v[148:151], v[6:9], v[118:121], v[148:151]
	v_mfma_f32_16x16x32_bf16 v[2:5], v[6:9], v[126:129], v[2:5]
	v_mfma_f32_16x16x32_bf16 v[6:9], v[10:13], v[122:125], 0
	v_mfma_f32_16x16x32_bf16 v[136:139], v[10:13], v[62:65], 0
	v_mfma_f32_16x16x32_bf16 v[144:147], v[10:13], v[94:97], 0
	v_mfma_f32_16x16x32_bf16 v[152:155], v[10:13], v[110:113], 0
	v_mfma_f32_16x16x32_bf16 v[6:9], v[14:17], v[126:129], v[6:9]
	v_mfma_f32_16x16x32_bf16 v[136:139], v[14:17], v[90:93], v[136:139]
	v_mfma_f32_16x16x32_bf16 v[144:147], v[14:17], v[106:109], v[144:147]
	v_mfma_f32_16x16x32_bf16 v[152:155], v[14:17], v[118:121], v[152:155]
	s_setprio 0
	s_setprio 1
	v_mfma_f32_16x16x32_bf16 v[10:13], v[18:21], v[62:65], 0
	v_mfma_f32_16x16x32_bf16 v[156:159], v[22:25], v[90:93], v[10:13]
	v_mfma_f32_16x16x32_bf16 v[10:13], v[26:29], v[62:65], 0
	v_mfma_f32_16x16x32_bf16 v[160:163], v[30:33], v[90:93], v[10:13]
	v_mfma_f32_16x16x32_bf16 v[10:13], v[18:21], v[94:97], 0
	v_mfma_f32_16x16x32_bf16 v[164:167], v[22:25], v[106:109], v[10:13]
	v_mfma_f32_16x16x32_bf16 v[10:13], v[26:29], v[94:97], 0
	v_mfma_f32_16x16x32_bf16 v[168:171], v[30:33], v[106:109], v[10:13]
	v_mfma_f32_16x16x32_bf16 v[10:13], v[18:21], v[110:113], 0
	v_mfma_f32_16x16x32_bf16 v[172:175], v[22:25], v[118:121], v[10:13]
	v_mfma_f32_16x16x32_bf16 v[10:13], v[26:29], v[110:113], 0
	v_mfma_f32_16x16x32_bf16 v[176:179], v[30:33], v[118:121], v[10:13]
	v_mfma_f32_16x16x32_bf16 v[10:13], v[18:21], v[122:125], 0
	v_mfma_f32_16x16x32_bf16 v[180:183], v[22:25], v[126:129], v[10:13]
	v_mfma_f32_16x16x32_bf16 v[10:13], v[26:29], v[122:125], 0
	v_mfma_f32_16x16x32_bf16 v[196:199], v[30:33], v[126:129], v[10:13]
	s_setprio 0
	s_barrier
	s_add_i32 s2, 0, 0x18000
	s_add_i32 s50, 0, 0x1c000
	v_add_u32_e32 v130, s2, v216
	v_add_u32_e32 v131, s50, v216
	s_nop 0
	ds_read_b128 v[10:13], v130
	ds_read_b128 v[14:17], v130 offset:1024
	ds_read_b128 v[18:21], v130 offset:2048
	ds_read_b128 v[22:25], v130 offset:3072
	ds_read_b128 v[200:203], v131
	ds_read_b128 v[204:207], v131 offset:1024
	ds_read_b128 v[208:211], v131 offset:2048
	ds_read_b128 v[222:225], v131 offset:3072
	s_mov_b32 m0, s59
	v_lshl_add_u64 v[90:91], v[250:251], 0, s[28:29]
	ds_read_b128 v[26:29], v220 offset:32768
	ds_read_b128 v[30:33], v220 offset:33792
	ds_read_b128 v[62:65], v220 offset:34816
	ds_read_b128 v[226:229], v220 offset:35840
	ds_read_b128 v[230:233], v220 offset:36864
	ds_read_b128 v[234:237], v220 offset:37888
	ds_read_b128 v[238:241], v220 offset:38912
	ds_read_b128 v[242:245], v220 offset:39936
	global_load_lds_dwordx4 v[90:91], off
	v_lshl_add_u64 v[90:91], v[250:251], 0, s[30:31]
	s_mov_b32 m0, s60
	s_nop 0
	global_load_lds_dwordx4 v[90:91], off
	s_waitcnt vmcnt(8)
	s_waitcnt lgkmcnt(0)
	s_waitcnt lgkmcnt(0)
	v_mfma_f32_16x16x32_bf16 v[66:69], v[10:13], v[26:29], v[66:69]
	v_mfma_f32_16x16x32_bf16 v[126:129], v[14:17], v[30:33], v[66:69]
	v_mfma_f32_16x16x32_bf16 v[66:69], v[18:21], v[26:29], v[70:73]
	s_barrier
	s_setprio 1
	v_mfma_f32_16x16x32_bf16 v[122:125], v[22:25], v[30:33], v[66:69]
	v_mfma_f32_16x16x32_bf16 v[66:69], v[10:13], v[62:65], v[74:77]
	v_mfma_f32_16x16x32_bf16 v[110:113], v[14:17], v[226:229], v[66:69]
	v_mfma_f32_16x16x32_bf16 v[66:69], v[18:21], v[62:65], v[78:81]
	v_mfma_f32_16x16x32_bf16 v[106:109], v[22:25], v[226:229], v[66:69]
	v_mfma_f32_16x16x32_bf16 v[66:69], v[10:13], v[230:233], v[82:85]
	v_mfma_f32_16x16x32_bf16 v[94:97], v[14:17], v[234:237], v[66:69]
	v_mfma_f32_16x16x32_bf16 v[66:69], v[18:21], v[230:233], v[86:89]
	v_mfma_f32_16x16x32_bf16 v[90:93], v[22:25], v[234:237], v[66:69]
	v_mfma_f32_16x16x32_bf16 v[66:69], v[10:13], v[238:241], v[98:101]
	v_mfma_f32_16x16x32_bf16 v[78:81], v[14:17], v[242:245], v[66:69]
	v_mfma_f32_16x16x32_bf16 v[66:69], v[18:21], v[238:241], v[102:105]
	v_mfma_f32_16x16x32_bf16 v[74:77], v[22:25], v[242:245], v[66:69]
	s_setprio 0
	s_setprio 1
	v_mfma_f32_16x16x32_bf16 v[66:69], v[200:203], v[26:29], v[114:117]
	v_mfma_f32_16x16x32_bf16 v[26:29], v[208:211], v[26:29], v[34:37]
	v_mfma_f32_16x16x32_bf16 v[114:117], v[222:225], v[30:33], v[26:29]
	v_mfma_f32_16x16x32_bf16 v[26:29], v[200:203], v[62:65], v[38:41]
	v_mfma_f32_16x16x32_bf16 v[102:105], v[204:207], v[226:229], v[26:29]
	v_mfma_f32_16x16x32_bf16 v[26:29], v[208:211], v[62:65], v[42:45]
	v_mfma_f32_16x16x32_bf16 v[98:101], v[222:225], v[226:229], v[26:29]
	v_mfma_f32_16x16x32_bf16 v[26:29], v[200:203], v[230:233], v[46:49]
	v_mfma_f32_16x16x32_bf16 v[86:89], v[204:207], v[234:237], v[26:29]
	v_mfma_f32_16x16x32_bf16 v[26:29], v[208:211], v[230:233], v[50:53]
	v_mfma_f32_16x16x32_bf16 v[82:85], v[222:225], v[234:237], v[26:29]
	v_mfma_f32_16x16x32_bf16 v[26:29], v[200:203], v[238:241], v[54:57]
	v_mfma_f32_16x16x32_bf16 v[70:73], v[204:207], v[242:245], v[26:29]
	v_mfma_f32_16x16x32_bf16 v[26:29], v[208:211], v[238:241], v[58:61]
	v_mfma_f32_16x16x32_bf16 v[118:121], v[204:207], v[30:33], v[66:69]
	v_mfma_f32_16x16x32_bf16 v[66:69], v[222:225], v[242:245], v[26:29]
	s_setprio 0
	s_barrier
	s_add_i32 s2, s2, s56
	s_nop 2
	v_lshl_add_u64 v[26:27], v[184:185], 0, s[64:65]
	s_mov_b32 m0, s2
	s_add_i32 s33, s2, 0x2000
	ds_read_b128 v[34:37], v220 offset:49152
	ds_read_b128 v[38:41], v220 offset:50176
	ds_read_b128 v[226:229], v220 offset:51200
	ds_read_b128 v[230:233], v220 offset:52224
	ds_read_b128 v[234:237], v220 offset:53248
	ds_read_b128 v[238:241], v220 offset:54272
	ds_read_b128 v[242:245], v220 offset:55296
	ds_read_b128 v[246:249], v220 offset:56320
	global_load_lds_dwordx4 v[26:27], off
	v_lshl_add_u64 v[26:27], v[184:185], 0, s[74:75]
	s_mov_b32 m0, s33
	s_add_i32 s50, s50, s56
	global_load_lds_dwordx4 v[26:27], off
	v_lshl_add_u64 v[26:27], v[184:185], 0, s[80:81]
	s_mov_b32 m0, s50
	s_add_i32 s51, s50, 0x2000
	global_load_lds_dwordx4 v[26:27], off
	v_lshl_add_u64 v[26:27], v[184:185], 0, s[84:85]
	s_mov_b32 m0, s51
	s_nop 0
	global_load_lds_dwordx4 v[26:27], off
	v_lshl_add_u64 v[26:27], v[250:251], 0, s[64:65]
	s_mov_b32 m0, s3
	s_nop 0
	global_load_lds_dwordx4 v[26:27], off
	v_lshl_add_u64 v[26:27], v[250:251], 0, s[74:75]
	s_mov_b32 m0, s61
	s_nop 0
	global_load_lds_dwordx4 v[26:27], off
	s_waitcnt vmcnt(8)
	s_waitcnt lgkmcnt(0)
	s_waitcnt lgkmcnt(0)
	v_mfma_f32_16x16x32_bf16 v[26:29], v[10:13], v[34:37], v[132:135]
	v_mfma_f32_16x16x32_bf16 v[62:65], v[14:17], v[38:41], v[26:29]
	v_mfma_f32_16x16x32_bf16 v[26:29], v[18:21], v[34:37], v[136:139]
	s_barrier
	s_setprio 1
	v_mfma_f32_16x16x32_bf16 v[58:61], v[22:25], v[38:41], v[26:29]
	v_mfma_f32_16x16x32_bf16 v[26:29], v[10:13], v[226:229], v[140:143]
	v_mfma_f32_16x16x32_bf16 v[46:49], v[14:17], v[230:233], v[26:29]
	v_mfma_f32_16x16x32_bf16 v[26:29], v[18:21], v[226:229], v[144:147]
	v_mfma_f32_16x16x32_bf16 v[42:45], v[22:25], v[230:233], v[26:29]
	v_mfma_f32_16x16x32_bf16 v[26:29], v[10:13], v[234:237], v[148:151]
	v_mfma_f32_16x16x32_bf16 v[2:5], v[10:13], v[242:245], v[2:5]
	v_mfma_f32_16x16x32_bf16 v[30:33], v[14:17], v[238:241], v[26:29]
	v_mfma_f32_16x16x32_bf16 v[26:29], v[18:21], v[234:237], v[152:155]
	v_mfma_f32_16x16x32_bf16 v[14:17], v[14:17], v[246:249], v[2:5]
	v_mfma_f32_16x16x32_bf16 v[2:5], v[18:21], v[242:245], v[6:9]
	v_mfma_f32_16x16x32_bf16 v[26:29], v[22:25], v[238:241], v[26:29]
	v_mfma_f32_16x16x32_bf16 v[10:13], v[22:25], v[246:249], v[2:5]
	s_setprio 0
	s_setprio 1
	v_mfma_f32_16x16x32_bf16 v[2:5], v[200:203], v[34:37], v[156:159]
	v_mfma_f32_16x16x32_bf16 v[54:57], v[204:207], v[38:41], v[2:5]
	v_mfma_f32_16x16x32_bf16 v[2:5], v[208:211], v[34:37], v[160:163]
	v_mfma_f32_16x16x32_bf16 v[50:53], v[222:225], v[38:41], v[2:5]
	v_mfma_f32_16x16x32_bf16 v[2:5], v[200:203], v[226:229], v[164:167]
	v_mfma_f32_16x16x32_bf16 v[38:41], v[204:207], v[230:233], v[2:5]
	v_mfma_f32_16x16x32_bf16 v[2:5], v[208:211], v[226:229], v[168:171]
	v_mfma_f32_16x16x32_bf16 v[34:37], v[222:225], v[230:233], v[2:5]
	v_mfma_f32_16x16x32_bf16 v[2:5], v[200:203], v[234:237], v[172:175]
	v_mfma_f32_16x16x32_bf16 v[22:25], v[204:207], v[238:241], v[2:5]
	v_mfma_f32_16x16x32_bf16 v[2:5], v[208:211], v[234:237], v[176:179]
	v_mfma_f32_16x16x32_bf16 v[18:21], v[222:225], v[238:241], v[2:5]
	v_mfma_f32_16x16x32_bf16 v[2:5], v[200:203], v[242:245], v[180:183]
	v_mfma_f32_16x16x32_bf16 v[6:9], v[204:207], v[246:249], v[2:5]
	v_mfma_f32_16x16x32_bf16 v[2:5], v[208:211], v[242:245], v[196:199]
	v_mfma_f32_16x16x32_bf16 v[2:5], v[222:225], v[246:249], v[2:5]
	s_setprio 0
	s_barrier
	s_cmp_lt_i32 s55, 3
	s_cbranch_scc1 .LBB0_392
	s_add_u32 s8, s34, 0xb0180
	s_addc_u32 s9, s35, 0
	s_add_u32 s36, s26, 0x200
	s_addc_u32 s37, s27, 0
	s_mov_b32 s66, 4
.LBB0_391:
	ds_read_b128 v[132:135], v218
	ds_read_b128 v[136:139], v218 offset:1024
	ds_read_b128 v[140:143], v218 offset:2048
	ds_read_b128 v[144:147], v218 offset:3072
	ds_read_b128 v[148:151], v219
	ds_read_b128 v[152:155], v219 offset:1024
	ds_read_b128 v[156:159], v219 offset:2048
	ds_read_b128 v[160:163], v219 offset:3072
	s_add_u32 s12, s8, 0xfff50080
	s_addc_u32 s13, s9, -1
	s_cmp_eq_u32 s55, s66
	s_cselect_b32 s13, s95, s13
	s_cselect_b32 s12, s94, s12
	s_cselect_b32 s15, s97, s37
	s_cselect_b32 s14, s96, s36
	s_mov_b32 m0, s11
	v_lshl_add_u64 v[184:185], s[8:9], 0, v[192:193]
	ds_read_b128 v[164:167], v220
	ds_read_b128 v[168:171], v220 offset:1024
	ds_read_b128 v[172:175], v220 offset:2048
	ds_read_b128 v[176:179], v220 offset:3072
	ds_read_b128 v[180:183], v220 offset:4096
	ds_read_b128 v[196:199], v220 offset:5120
	ds_read_b128 v[200:203], v220 offset:6144
	ds_read_b128 v[204:207], v220 offset:7168
	global_load_lds_dwordx4 v[184:185], off
	v_lshl_add_u64 v[184:185], v[184:185], 0, s[24:25]
	s_mov_b32 m0, s40
	s_nop 0
	global_load_lds_dwordx4 v[184:185], off
	s_waitcnt vmcnt(8)
	s_waitcnt lgkmcnt(0)
	s_waitcnt lgkmcnt(0)
	v_mfma_f32_16x16x32_bf16 v[126:129], v[132:135], v[164:167], v[126:129]
	v_mfma_f32_16x16x32_bf16 v[122:125], v[140:143], v[164:167], v[122:125]
	v_mfma_f32_16x16x32_bf16 v[110:113], v[132:135], v[172:175], v[110:113]
	s_barrier
	s_setprio 1
	v_mfma_f32_16x16x32_bf16 v[106:109], v[140:143], v[172:175], v[106:109]
	v_mfma_f32_16x16x32_bf16 v[94:97], v[132:135], v[180:183], v[94:97]
	v_mfma_f32_16x16x32_bf16 v[90:93], v[140:143], v[180:183], v[90:93]
	v_mfma_f32_16x16x32_bf16 v[78:81], v[132:135], v[200:203], v[78:81]
	v_mfma_f32_16x16x32_bf16 v[74:77], v[140:143], v[200:203], v[74:77]
	v_mfma_f32_16x16x32_bf16 v[126:129], v[136:139], v[168:171], v[126:129]
	v_mfma_f32_16x16x32_bf16 v[122:125], v[144:147], v[168:171], v[122:125]
	v_mfma_f32_16x16x32_bf16 v[110:113], v[136:139], v[176:179], v[110:113]
	v_mfma_f32_16x16x32_bf16 v[106:109], v[144:147], v[176:179], v[106:109]
	v_mfma_f32_16x16x32_bf16 v[94:97], v[136:139], v[196:199], v[94:97]
	v_mfma_f32_16x16x32_bf16 v[90:93], v[144:147], v[196:199], v[90:93]
	v_mfma_f32_16x16x32_bf16 v[78:81], v[136:139], v[204:207], v[78:81]
	v_mfma_f32_16x16x32_bf16 v[74:77], v[144:147], v[204:207], v[74:77]
	s_setprio 0
	s_setprio 1
	v_mfma_f32_16x16x32_bf16 v[118:121], v[148:151], v[164:167], v[118:121]
	v_mfma_f32_16x16x32_bf16 v[114:117], v[156:159], v[164:167], v[114:117]
	v_mfma_f32_16x16x32_bf16 v[102:105], v[148:151], v[172:175], v[102:105]
	v_mfma_f32_16x16x32_bf16 v[98:101], v[156:159], v[172:175], v[98:101]
	v_mfma_f32_16x16x32_bf16 v[86:89], v[148:151], v[180:183], v[86:89]
	v_mfma_f32_16x16x32_bf16 v[82:85], v[156:159], v[180:183], v[82:85]
	v_mfma_f32_16x16x32_bf16 v[70:73], v[148:151], v[200:203], v[70:73]
	v_mfma_f32_16x16x32_bf16 v[66:69], v[156:159], v[200:203], v[66:69]
	v_mfma_f32_16x16x32_bf16 v[118:121], v[152:155], v[168:171], v[118:121]
	v_mfma_f32_16x16x32_bf16 v[114:117], v[160:163], v[168:171], v[114:117]
	v_mfma_f32_16x16x32_bf16 v[102:105], v[152:155], v[176:179], v[102:105]
	v_mfma_f32_16x16x32_bf16 v[98:101], v[160:163], v[176:179], v[98:101]
	v_mfma_f32_16x16x32_bf16 v[86:89], v[152:155], v[196:199], v[86:89]
	v_mfma_f32_16x16x32_bf16 v[82:85], v[160:163], v[196:199], v[82:85]
	v_mfma_f32_16x16x32_bf16 v[70:73], v[152:155], v[204:207], v[70:73]
	v_mfma_f32_16x16x32_bf16 v[66:69], v[160:163], v[204:207], v[66:69]
	s_setprio 0
	s_barrier
	s_mov_b32 m0, s46
	v_lshl_add_u64 v[184:185], s[14:15], 0, v[190:191]
	ds_read_b128 v[164:167], v220 offset:16384
	ds_read_b128 v[168:171], v220 offset:17408
	ds_read_b128 v[172:175], v220 offset:18432
	ds_read_b128 v[176:179], v220 offset:19456
	ds_read_b128 v[180:183], v220 offset:20480
	ds_read_b128 v[196:199], v220 offset:21504
	ds_read_b128 v[200:203], v220 offset:22528
	ds_read_b128 v[204:207], v220 offset:23552
	global_load_lds_dwordx4 v[184:185], off
	v_lshl_add_u64 v[208:209], v[184:185], 0, s[24:25]
	s_mov_b32 m0, s47
	s_nop 0
	global_load_lds_dwordx4 v[208:209], off
	v_lshl_add_u64 v[208:209], v[184:185], 0, s[28:29]
	s_mov_b32 m0, s48
	s_nop 0
	global_load_lds_dwordx4 v[208:209], off
	v_lshl_add_u64 v[208:209], v[184:185], 0, s[30:31]
	s_mov_b32 m0, s49
	s_nop 0
	global_load_lds_dwordx4 v[208:209], off
	v_lshl_add_u64 v[208:209], s[12:13], 0, v[188:189]
	s_mov_b32 m0, s57
	v_lshl_add_u64 v[210:211], v[208:209], 0, s[24:25]
	global_load_lds_dwordx4 v[208:209], off
	s_mov_b32 m0, s58
	s_nop 0
	global_load_lds_dwordx4 v[210:211], off
	s_waitcnt vmcnt(8)
	s_waitcnt lgkmcnt(0)
	s_waitcnt lgkmcnt(0)
	v_mfma_f32_16x16x32_bf16 v[62:65], v[132:135], v[164:167], v[62:65]
	v_mfma_f32_16x16x32_bf16 v[58:61], v[140:143], v[164:167], v[58:61]
	v_mfma_f32_16x16x32_bf16 v[46:49], v[132:135], v[172:175], v[46:49]
	s_barrier
	s_setprio 1
	v_mfma_f32_16x16x32_bf16 v[42:45], v[140:143], v[172:175], v[42:45]
	v_mfma_f32_16x16x32_bf16 v[30:33], v[132:135], v[180:183], v[30:33]
	v_mfma_f32_16x16x32_bf16 v[26:29], v[140:143], v[180:183], v[26:29]
	v_mfma_f32_16x16x32_bf16 v[14:17], v[132:135], v[200:203], v[14:17]
	v_mfma_f32_16x16x32_bf16 v[10:13], v[140:143], v[200:203], v[10:13]
	v_mfma_f32_16x16x32_bf16 v[62:65], v[136:139], v[168:171], v[62:65]
	v_mfma_f32_16x16x32_bf16 v[58:61], v[144:147], v[168:171], v[58:61]
	v_mfma_f32_16x16x32_bf16 v[46:49], v[136:139], v[176:179], v[46:49]
	v_mfma_f32_16x16x32_bf16 v[42:45], v[144:147], v[176:179], v[42:45]
	v_mfma_f32_16x16x32_bf16 v[30:33], v[136:139], v[196:199], v[30:33]
	v_mfma_f32_16x16x32_bf16 v[26:29], v[144:147], v[196:199], v[26:29]
	v_mfma_f32_16x16x32_bf16 v[14:17], v[136:139], v[204:207], v[14:17]
	v_mfma_f32_16x16x32_bf16 v[10:13], v[144:147], v[204:207], v[10:13]
	s_setprio 0
	s_setprio 1
	v_mfma_f32_16x16x32_bf16 v[54:57], v[148:151], v[164:167], v[54:57]
	v_mfma_f32_16x16x32_bf16 v[50:53], v[156:159], v[164:167], v[50:53]
	v_mfma_f32_16x16x32_bf16 v[38:41], v[148:151], v[172:175], v[38:41]
	v_mfma_f32_16x16x32_bf16 v[34:37], v[156:159], v[172:175], v[34:37]
	v_mfma_f32_16x16x32_bf16 v[22:25], v[148:151], v[180:183], v[22:25]
	v_mfma_f32_16x16x32_bf16 v[18:21], v[156:159], v[180:183], v[18:21]
	v_mfma_f32_16x16x32_bf16 v[6:9], v[148:151], v[200:203], v[6:9]
	v_mfma_f32_16x16x32_bf16 v[2:5], v[156:159], v[200:203], v[2:5]
	v_mfma_f32_16x16x32_bf16 v[54:57], v[152:155], v[168:171], v[54:57]
	v_mfma_f32_16x16x32_bf16 v[50:53], v[160:163], v[168:171], v[50:53]
	v_mfma_f32_16x16x32_bf16 v[38:41], v[152:155], v[176:179], v[38:41]
	v_mfma_f32_16x16x32_bf16 v[34:37], v[160:163], v[176:179], v[34:37]
	v_mfma_f32_16x16x32_bf16 v[22:25], v[152:155], v[196:199], v[22:25]
	v_mfma_f32_16x16x32_bf16 v[18:21], v[160:163], v[196:199], v[18:21]
	v_mfma_f32_16x16x32_bf16 v[6:9], v[152:155], v[204:207], v[6:9]
	v_mfma_f32_16x16x32_bf16 v[2:5], v[160:163], v[204:207], v[2:5]
	s_setprio 0
	s_barrier
	ds_read_b128 v[132:135], v130
	ds_read_b128 v[136:139], v130 offset:1024
	ds_read_b128 v[140:143], v130 offset:2048
	ds_read_b128 v[144:147], v130 offset:3072
	ds_read_b128 v[148:151], v131
	ds_read_b128 v[152:155], v131 offset:1024
	ds_read_b128 v[156:159], v131 offset:2048
	ds_read_b128 v[160:163], v131 offset:3072
	s_mov_b32 m0, s59
	v_lshl_add_u64 v[210:211], v[208:209], 0, s[28:29]
	ds_read_b128 v[164:167], v220 offset:32768
	ds_read_b128 v[168:171], v220 offset:33792
	ds_read_b128 v[172:175], v220 offset:34816
	ds_read_b128 v[176:179], v220 offset:35840
	ds_read_b128 v[180:183], v220 offset:36864
	ds_read_b128 v[196:199], v220 offset:37888
	ds_read_b128 v[200:203], v220 offset:38912
	ds_read_b128 v[204:207], v220 offset:39936
	global_load_lds_dwordx4 v[210:211], off
	v_lshl_add_u64 v[210:211], v[208:209], 0, s[30:31]
	s_mov_b32 m0, s60
	s_nop 0
	global_load_lds_dwordx4 v[210:211], off
	s_waitcnt vmcnt(8)
	s_waitcnt lgkmcnt(0)
	s_waitcnt lgkmcnt(0)
	v_mfma_f32_16x16x32_bf16 v[126:129], v[132:135], v[164:167], v[126:129]
	v_mfma_f32_16x16x32_bf16 v[122:125], v[140:143], v[164:167], v[122:125]
	v_mfma_f32_16x16x32_bf16 v[110:113], v[132:135], v[172:175], v[110:113]
	s_barrier
	s_setprio 1
	v_mfma_f32_16x16x32_bf16 v[106:109], v[140:143], v[172:175], v[106:109]
	v_mfma_f32_16x16x32_bf16 v[94:97], v[132:135], v[180:183], v[94:97]
	v_mfma_f32_16x16x32_bf16 v[90:93], v[140:143], v[180:183], v[90:93]
	v_mfma_f32_16x16x32_bf16 v[78:81], v[132:135], v[200:203], v[78:81]
	v_mfma_f32_16x16x32_bf16 v[74:77], v[140:143], v[200:203], v[74:77]
	v_mfma_f32_16x16x32_bf16 v[126:129], v[136:139], v[168:171], v[126:129]
	v_mfma_f32_16x16x32_bf16 v[122:125], v[144:147], v[168:171], v[122:125]
	v_mfma_f32_16x16x32_bf16 v[110:113], v[136:139], v[176:179], v[110:113]
	v_mfma_f32_16x16x32_bf16 v[106:109], v[144:147], v[176:179], v[106:109]
	v_mfma_f32_16x16x32_bf16 v[94:97], v[136:139], v[196:199], v[94:97]
	v_mfma_f32_16x16x32_bf16 v[90:93], v[144:147], v[196:199], v[90:93]
	v_mfma_f32_16x16x32_bf16 v[78:81], v[136:139], v[204:207], v[78:81]
	v_mfma_f32_16x16x32_bf16 v[74:77], v[144:147], v[204:207], v[74:77]
	s_setprio 0
	s_setprio 1
	v_mfma_f32_16x16x32_bf16 v[118:121], v[148:151], v[164:167], v[118:121]
	v_mfma_f32_16x16x32_bf16 v[114:117], v[156:159], v[164:167], v[114:117]
	v_mfma_f32_16x16x32_bf16 v[102:105], v[148:151], v[172:175], v[102:105]
	v_mfma_f32_16x16x32_bf16 v[98:101], v[156:159], v[172:175], v[98:101]
	v_mfma_f32_16x16x32_bf16 v[86:89], v[148:151], v[180:183], v[86:89]
	v_mfma_f32_16x16x32_bf16 v[82:85], v[156:159], v[180:183], v[82:85]
	v_mfma_f32_16x16x32_bf16 v[70:73], v[148:151], v[200:203], v[70:73]
	v_mfma_f32_16x16x32_bf16 v[66:69], v[156:159], v[200:203], v[66:69]
	v_mfma_f32_16x16x32_bf16 v[118:121], v[152:155], v[168:171], v[118:121]
	v_mfma_f32_16x16x32_bf16 v[114:117], v[160:163], v[168:171], v[114:117]
	v_mfma_f32_16x16x32_bf16 v[102:105], v[152:155], v[176:179], v[102:105]
	v_mfma_f32_16x16x32_bf16 v[98:101], v[160:163], v[176:179], v[98:101]
	v_mfma_f32_16x16x32_bf16 v[86:89], v[152:155], v[196:199], v[86:89]
	v_mfma_f32_16x16x32_bf16 v[82:85], v[160:163], v[196:199], v[82:85]
	v_mfma_f32_16x16x32_bf16 v[70:73], v[152:155], v[204:207], v[70:73]
	v_mfma_f32_16x16x32_bf16 v[66:69], v[160:163], v[204:207], v[66:69]
	s_setprio 0
	s_barrier
	s_mov_b32 m0, s2
	v_lshl_add_u64 v[210:211], v[184:185], 0, s[64:65]
	ds_read_b128 v[164:167], v220 offset:49152
	ds_read_b128 v[168:171], v220 offset:50176
	ds_read_b128 v[172:175], v220 offset:51200
	ds_read_b128 v[176:179], v220 offset:52224
	ds_read_b128 v[180:183], v220 offset:53248
	ds_read_b128 v[196:199], v220 offset:54272
	ds_read_b128 v[200:203], v220 offset:55296
	ds_read_b128 v[204:207], v220 offset:56320
	global_load_lds_dwordx4 v[210:211], off
	v_lshl_add_u64 v[210:211], v[184:185], 0, s[74:75]
	s_mov_b32 m0, s33
	s_nop 0
	global_load_lds_dwordx4 v[210:211], off
	v_lshl_add_u64 v[210:211], v[184:185], 0, s[80:81]
	s_mov_b32 m0, s50
	v_lshl_add_u64 v[184:185], v[184:185], 0, s[84:85]
	global_load_lds_dwordx4 v[210:211], off
	s_mov_b32 m0, s51
	s_nop 0
	global_load_lds_dwordx4 v[184:185], off
	v_lshl_add_u64 v[184:185], v[208:209], 0, s[64:65]
	s_mov_b32 m0, s3
	s_nop 0
	global_load_lds_dwordx4 v[184:185], off
	v_lshl_add_u64 v[184:185], v[208:209], 0, s[74:75]
	s_mov_b32 m0, s61
	s_nop 0
	global_load_lds_dwordx4 v[184:185], off
	s_waitcnt vmcnt(8)
	s_waitcnt lgkmcnt(0)
	s_waitcnt lgkmcnt(0)
	v_mfma_f32_16x16x32_bf16 v[62:65], v[132:135], v[164:167], v[62:65]
	v_mfma_f32_16x16x32_bf16 v[58:61], v[140:143], v[164:167], v[58:61]
	v_mfma_f32_16x16x32_bf16 v[46:49], v[132:135], v[172:175], v[46:49]
	s_barrier
	s_setprio 1
	v_mfma_f32_16x16x32_bf16 v[42:45], v[140:143], v[172:175], v[42:45]
	v_mfma_f32_16x16x32_bf16 v[30:33], v[132:135], v[180:183], v[30:33]
	v_mfma_f32_16x16x32_bf16 v[26:29], v[140:143], v[180:183], v[26:29]
	v_mfma_f32_16x16x32_bf16 v[14:17], v[132:135], v[200:203], v[14:17]
	v_mfma_f32_16x16x32_bf16 v[10:13], v[140:143], v[200:203], v[10:13]
	v_mfma_f32_16x16x32_bf16 v[62:65], v[136:139], v[168:171], v[62:65]
	v_mfma_f32_16x16x32_bf16 v[58:61], v[144:147], v[168:171], v[58:61]
	v_mfma_f32_16x16x32_bf16 v[46:49], v[136:139], v[176:179], v[46:49]
	v_mfma_f32_16x16x32_bf16 v[42:45], v[144:147], v[176:179], v[42:45]
	v_mfma_f32_16x16x32_bf16 v[30:33], v[136:139], v[196:199], v[30:33]
	v_mfma_f32_16x16x32_bf16 v[26:29], v[144:147], v[196:199], v[26:29]
	v_mfma_f32_16x16x32_bf16 v[14:17], v[136:139], v[204:207], v[14:17]
	v_mfma_f32_16x16x32_bf16 v[10:13], v[144:147], v[204:207], v[10:13]
	s_setprio 0
	s_setprio 1
	v_mfma_f32_16x16x32_bf16 v[54:57], v[148:151], v[164:167], v[54:57]
	v_mfma_f32_16x16x32_bf16 v[50:53], v[156:159], v[164:167], v[50:53]
	v_mfma_f32_16x16x32_bf16 v[38:41], v[148:151], v[172:175], v[38:41]
	v_mfma_f32_16x16x32_bf16 v[34:37], v[156:159], v[172:175], v[34:37]
	v_mfma_f32_16x16x32_bf16 v[22:25], v[148:151], v[180:183], v[22:25]
	v_mfma_f32_16x16x32_bf16 v[18:21], v[156:159], v[180:183], v[18:21]
	v_mfma_f32_16x16x32_bf16 v[6:9], v[148:151], v[200:203], v[6:9]
	v_mfma_f32_16x16x32_bf16 v[2:5], v[156:159], v[200:203], v[2:5]
	v_mfma_f32_16x16x32_bf16 v[54:57], v[152:155], v[168:171], v[54:57]
	v_mfma_f32_16x16x32_bf16 v[50:53], v[160:163], v[168:171], v[50:53]
	v_mfma_f32_16x16x32_bf16 v[38:41], v[152:155], v[176:179], v[38:41]
	v_mfma_f32_16x16x32_bf16 v[34:37], v[160:163], v[176:179], v[34:37]
	v_mfma_f32_16x16x32_bf16 v[22:25], v[152:155], v[196:199], v[22:25]
	v_mfma_f32_16x16x32_bf16 v[18:21], v[160:163], v[196:199], v[18:21]
	v_mfma_f32_16x16x32_bf16 v[6:9], v[152:155], v[204:207], v[6:9]
	v_mfma_f32_16x16x32_bf16 v[2:5], v[160:163], v[204:207], v[2:5]
	s_setprio 0
	s_barrier
	s_add_i32 s12, s66, 2
	s_add_u32 s8, s8, 0x100
	s_addc_u32 s9, s9, 0
	s_add_u32 s36, s36, 0x100
	s_addc_u32 s37, s37, 0
	s_cmp_ge_i32 s66, s55
	s_mov_b32 s66, s12
	s_cbranch_scc0 .LBB0_391

.LBB0_712:
	s_ashr_i32 s45, s44, 31
	s_xor_b64 s[46:47], s[10:11], -1
	s_lshl_b64 s[12:13], s[44:45], 19
	v_readlane_b32 s14, v254, 62
	v_readlane_b32 s15, v254, 63
	s_add_u32 s80, s14, s12
	s_addc_u32 s81, s15, s13
	s_and_b64 s[12:13], s[10:11], exec
	s_cselect_b32 s41, s81, s49
	s_cselect_b32 s45, s80, s48
	s_ashr_i32 s63, s62, 31
	s_lshl_b64 s[12:13], s[62:63], 19
	v_readlane_b32 s14, v255, 17
	v_readlane_b32 s15, v255, 18
	s_add_u32 s66, s14, s12
	s_addc_u32 s67, s15, s13
	s_and_b64 s[12:13], s[10:11], exec
	s_cselect_b32 s58, s67, s65
	s_cselect_b32 s59, s66, s64
	v_lshl_add_u64 v[160:161], s[48:49], 0, v[162:163]
	s_add_i32 s60, s92, 0xc000
	v_lshl_add_u64 v[66:67], v[160:161], 0, s[72:73]
	s_mov_b32 m0, s60
	s_add_i32 s61, s92, 0xe000
	global_load_lds_dwordx4 v[66:67], off
	v_lshl_add_u64 v[66:67], v[160:161], 0, s[78:79]
	s_mov_b32 m0, s61
	s_nop 0
	global_load_lds_dwordx4 v[66:67], off
	s_waitcnt vmcnt(8)
	s_waitcnt lgkmcnt(0)
	s_waitcnt lgkmcnt(0)
	v_mfma_f32_16x16x32_bf16 v[86:89], v[10:13], v[50:53], 0
	v_mfma_f32_16x16x32_bf16 v[90:93], v[14:17], v[54:57], v[86:89]
	v_mfma_f32_16x16x32_bf16 v[86:89], v[2:5], v[58:61], 0
	s_barrier
	s_setprio 1
	v_mfma_f32_16x16x32_bf16 v[66:69], v[2:5], v[34:37], 0
	v_mfma_f32_16x16x32_bf16 v[70:73], v[10:13], v[34:37], 0
	v_mfma_f32_16x16x32_bf16 v[74:77], v[2:5], v[42:45], 0
	v_mfma_f32_16x16x32_bf16 v[78:81], v[10:13], v[42:45], 0
	v_mfma_f32_16x16x32_bf16 v[82:85], v[2:5], v[50:53], 0
	v_mfma_f32_16x16x32_bf16 v[94:97], v[6:9], v[62:65], v[86:89]
	v_mfma_f32_16x16x32_bf16 v[86:89], v[10:13], v[58:61], 0
	v_mfma_f32_16x16x32_bf16 v[66:69], v[6:9], v[38:41], v[66:69]
	v_mfma_f32_16x16x32_bf16 v[70:73], v[14:17], v[38:41], v[70:73]
	v_mfma_f32_16x16x32_bf16 v[74:77], v[6:9], v[46:49], v[74:77]
	v_mfma_f32_16x16x32_bf16 v[78:81], v[14:17], v[46:49], v[78:81]
	v_mfma_f32_16x16x32_bf16 v[82:85], v[6:9], v[54:57], v[82:85]
	v_mfma_f32_16x16x32_bf16 v[106:109], v[14:17], v[62:65], v[86:89]
	s_setprio 0
	s_setprio 1
	v_mfma_f32_16x16x32_bf16 v[86:89], v[18:21], v[34:37], 0
	v_mfma_f32_16x16x32_bf16 v[34:37], v[26:29], v[34:37], 0
	v_mfma_f32_16x16x32_bf16 v[110:113], v[22:25], v[38:41], v[86:89]
	v_mfma_f32_16x16x32_bf16 v[34:37], v[30:33], v[38:41], v[34:37]
	v_mfma_f32_16x16x32_bf16 v[38:41], v[18:21], v[42:45], 0
	v_mfma_f32_16x16x32_bf16 v[42:45], v[26:29], v[42:45], 0
	v_mfma_f32_16x16x32_bf16 v[38:41], v[22:25], v[46:49], v[38:41]
	v_mfma_f32_16x16x32_bf16 v[42:45], v[30:33], v[46:49], v[42:45]
	v_mfma_f32_16x16x32_bf16 v[46:49], v[18:21], v[50:53], 0
	v_mfma_f32_16x16x32_bf16 v[132:135], v[22:25], v[54:57], v[46:49]
	v_mfma_f32_16x16x32_bf16 v[46:49], v[26:29], v[50:53], 0
	v_mfma_f32_16x16x32_bf16 v[50:53], v[30:33], v[54:57], v[46:49]
	v_mfma_f32_16x16x32_bf16 v[46:49], v[18:21], v[58:61], 0
	v_mfma_f32_16x16x32_bf16 v[136:139], v[22:25], v[62:65], v[46:49]
	v_mfma_f32_16x16x32_bf16 v[46:49], v[26:29], v[58:61], 0
	v_mfma_f32_16x16x32_bf16 v[58:61], v[30:33], v[62:65], v[46:49]
	s_setprio 0
	s_barrier
	v_lshl_add_u64 v[252:253], s[64:65], 0, v[164:165]
	s_add_i32 s63, s52, s51
	v_lshl_add_u64 v[122:123], v[252:253], 0, s[26:27]
	s_mov_b32 m0, s63
	s_add_i32 vcc_lo, s63, 0x2000
	ds_read_b128 v[46:49], v179 offset:16384
	ds_read_b128 v[54:57], v179 offset:17408
	ds_read_b128 v[62:65], v179 offset:18432
	ds_read_b128 v[86:89], v179 offset:19456
	ds_read_b128 v[98:101], v179 offset:20480
	ds_read_b128 v[102:105], v179 offset:21504
	ds_read_b128 v[114:117], v179 offset:22528
	ds_read_b128 v[118:121], v179 offset:23552
	global_load_lds_dwordx4 v[122:123], off
	v_lshl_add_u64 v[122:123], v[252:253], 0, s[28:29]
	s_mov_b32 m0, vcc_lo
	s_add_i32 vcc_hi, s53, s51
	global_load_lds_dwordx4 v[122:123], off
	v_lshl_add_u64 v[122:123], v[252:253], 0, s[30:31]
	s_mov_b32 m0, vcc_hi
	s_add_i32 s54, vcc_hi, 0x2000
	global_load_lds_dwordx4 v[122:123], off
	v_lshl_add_u64 v[122:123], v[252:253], 0, s[74:75]
	s_mov_b32 m0, s54
	s_nop 0
	global_load_lds_dwordx4 v[122:123], off
	v_lshl_add_u64 v[122:123], v[160:161], 0, s[26:27]
	s_mov_b32 m0, s92
	s_nop 0
	global_load_lds_dwordx4 v[122:123], off
	v_lshl_add_u64 v[122:123], v[160:161], 0, s[28:29]
	s_mov_b32 m0, s93
	s_nop 0
	global_load_lds_dwordx4 v[122:123], off
	s_waitcnt vmcnt(8)
	s_waitcnt lgkmcnt(0)
	s_waitcnt lgkmcnt(0)
	v_mfma_f32_16x16x32_bf16 v[122:125], v[2:5], v[46:49], 0
	v_mfma_f32_16x16x32_bf16 v[140:143], v[6:9], v[54:57], v[122:125]
	v_mfma_f32_16x16x32_bf16 v[122:125], v[10:13], v[46:49], 0
	s_barrier
	s_setprio 1
	v_mfma_f32_16x16x32_bf16 v[144:147], v[14:17], v[54:57], v[122:125]
	v_mfma_f32_16x16x32_bf16 v[122:125], v[2:5], v[62:65], 0
	v_mfma_f32_16x16x32_bf16 v[148:151], v[6:9], v[86:89], v[122:125]
	v_mfma_f32_16x16x32_bf16 v[122:125], v[10:13], v[62:65], 0
	v_mfma_f32_16x16x32_bf16 v[152:155], v[14:17], v[86:89], v[122:125]
	v_mfma_f32_16x16x32_bf16 v[122:125], v[2:5], v[98:101], 0
	v_mfma_f32_16x16x32_bf16 v[2:5], v[2:5], v[114:117], 0
	v_mfma_f32_16x16x32_bf16 v[156:159], v[6:9], v[102:105], v[122:125]
	v_mfma_f32_16x16x32_bf16 v[2:5], v[6:9], v[118:121], v[2:5]
	v_mfma_f32_16x16x32_bf16 v[6:9], v[10:13], v[114:117], 0
	v_mfma_f32_16x16x32_bf16 v[122:125], v[10:13], v[98:101], 0
	v_mfma_f32_16x16x32_bf16 v[10:13], v[14:17], v[118:121], v[6:9]
	v_mfma_f32_16x16x32_bf16 v[170:173], v[14:17], v[102:105], v[122:125]
	s_setprio 0
	s_setprio 1
	v_mfma_f32_16x16x32_bf16 v[6:9], v[18:21], v[46:49], 0
	v_mfma_f32_16x16x32_bf16 v[14:17], v[22:25], v[54:57], v[6:9]
	v_mfma_f32_16x16x32_bf16 v[6:9], v[26:29], v[46:49], 0
	v_mfma_f32_16x16x32_bf16 v[182:185], v[30:33], v[54:57], v[6:9]
	v_mfma_f32_16x16x32_bf16 v[6:9], v[18:21], v[62:65], 0
	v_mfma_f32_16x16x32_bf16 v[188:191], v[22:25], v[86:89], v[6:9]
	v_mfma_f32_16x16x32_bf16 v[6:9], v[26:29], v[62:65], 0
	v_mfma_f32_16x16x32_bf16 v[192:195], v[30:33], v[86:89], v[6:9]
	v_mfma_f32_16x16x32_bf16 v[6:9], v[18:21], v[98:101], 0
	v_mfma_f32_16x16x32_bf16 v[196:199], v[22:25], v[102:105], v[6:9]
	v_mfma_f32_16x16x32_bf16 v[6:9], v[26:29], v[98:101], 0
	v_mfma_f32_16x16x32_bf16 v[200:203], v[30:33], v[102:105], v[6:9]
	v_mfma_f32_16x16x32_bf16 v[6:9], v[18:21], v[114:117], 0
	v_mfma_f32_16x16x32_bf16 v[204:207], v[22:25], v[118:121], v[6:9]
	v_mfma_f32_16x16x32_bf16 v[6:9], v[26:29], v[114:117], 0
	v_mfma_f32_16x16x32_bf16 v[208:211], v[30:33], v[118:121], v[6:9]
	s_setprio 0
	s_barrier
	s_add_i32 s2, 0, 0x18000
	s_add_i32 s82, 0, 0x1c000
	v_add_u32_e32 v130, s2, v176
	v_add_u32_e32 v131, s82, v176
	s_nop 0
	ds_read_b128 v[6:9], v130
	ds_read_b128 v[26:29], v130 offset:1024
	ds_read_b128 v[30:33], v130 offset:2048
	ds_read_b128 v[212:215], v130 offset:3072
	ds_read_b128 v[216:219], v131
	ds_read_b128 v[220:223], v131 offset:1024
	ds_read_b128 v[224:227], v131 offset:2048
	ds_read_b128 v[228:231], v131 offset:3072
	s_mov_b32 m0, s0
	v_lshl_add_u64 v[46:47], v[160:161], 0, s[30:31]
	ds_read_b128 v[18:21], v179 offset:32768
	ds_read_b128 v[22:25], v179 offset:33792
	ds_read_b128 v[62:65], v179 offset:34816
	ds_read_b128 v[232:235], v179 offset:35840
	ds_read_b128 v[236:239], v179 offset:36864
	ds_read_b128 v[240:243], v179 offset:37888
	ds_read_b128 v[244:247], v179 offset:38912
	ds_read_b128 v[248:251], v179 offset:39936
	global_load_lds_dwordx4 v[46:47], off
	v_lshl_add_u64 v[46:47], v[160:161], 0, s[74:75]
	s_mov_b32 m0, s1
	s_nop 0
	global_load_lds_dwordx4 v[46:47], off
	s_waitcnt vmcnt(8)
	s_waitcnt lgkmcnt(0)
	s_waitcnt lgkmcnt(0)
	v_mfma_f32_16x16x32_bf16 v[46:49], v[6:9], v[18:21], v[66:69]
	v_mfma_f32_16x16x32_bf16 v[118:121], v[26:29], v[22:25], v[46:49]
	v_mfma_f32_16x16x32_bf16 v[46:49], v[30:33], v[18:21], v[70:73]
	s_barrier
	s_setprio 1
	v_mfma_f32_16x16x32_bf16 v[114:117], v[212:215], v[22:25], v[46:49]
	v_mfma_f32_16x16x32_bf16 v[46:49], v[6:9], v[62:65], v[74:77]
	v_mfma_f32_16x16x32_bf16 v[102:105], v[26:29], v[232:235], v[46:49]
	v_mfma_f32_16x16x32_bf16 v[46:49], v[30:33], v[62:65], v[78:81]
	v_mfma_f32_16x16x32_bf16 v[98:101], v[212:215], v[232:235], v[46:49]
	v_mfma_f32_16x16x32_bf16 v[46:49], v[6:9], v[236:239], v[82:85]
	v_mfma_f32_16x16x32_bf16 v[86:89], v[26:29], v[240:243], v[46:49]
	v_mfma_f32_16x16x32_bf16 v[46:49], v[30:33], v[236:239], v[90:93]
	v_mfma_f32_16x16x32_bf16 v[78:81], v[212:215], v[240:243], v[46:49]
	v_mfma_f32_16x16x32_bf16 v[46:49], v[6:9], v[244:247], v[94:97]
	v_mfma_f32_16x16x32_bf16 v[54:57], v[26:29], v[248:251], v[46:49]
	v_mfma_f32_16x16x32_bf16 v[46:49], v[30:33], v[244:247], v[106:109]
	v_mfma_f32_16x16x32_bf16 v[46:49], v[212:215], v[248:251], v[46:49]
	s_setprio 0
	s_setprio 1
	v_mfma_f32_16x16x32_bf16 v[66:69], v[216:219], v[18:21], v[110:113]
	v_mfma_f32_16x16x32_bf16 v[18:21], v[224:227], v[18:21], v[34:37]
	v_mfma_f32_16x16x32_bf16 v[122:125], v[228:231], v[22:25], v[18:21]
	v_mfma_f32_16x16x32_bf16 v[18:21], v[216:219], v[62:65], v[38:41]
	v_mfma_f32_16x16x32_bf16 v[110:113], v[220:223], v[232:235], v[18:21]
	v_mfma_f32_16x16x32_bf16 v[18:21], v[224:227], v[62:65], v[42:45]
	v_mfma_f32_16x16x32_bf16 v[106:109], v[228:231], v[232:235], v[18:21]
	v_mfma_f32_16x16x32_bf16 v[18:21], v[216:219], v[236:239], v[132:135]
	v_mfma_f32_16x16x32_bf16 v[94:97], v[220:223], v[240:243], v[18:21]
	v_mfma_f32_16x16x32_bf16 v[18:21], v[224:227], v[236:239], v[50:53]
	v_mfma_f32_16x16x32_bf16 v[90:93], v[228:231], v[240:243], v[18:21]
	v_mfma_f32_16x16x32_bf16 v[18:21], v[216:219], v[244:247], v[136:139]
	v_mfma_f32_16x16x32_bf16 v[126:129], v[220:223], v[22:25], v[66:69]
	v_mfma_f32_16x16x32_bf16 v[66:69], v[220:223], v[248:251], v[18:21]
	v_mfma_f32_16x16x32_bf16 v[18:21], v[224:227], v[244:247], v[58:61]
	v_mfma_f32_16x16x32_bf16 v[58:61], v[228:231], v[248:251], v[18:21]
	s_setprio 0
	s_barrier
	s_add_i32 s2, s2, s51
	s_nop 3
	v_lshl_add_u64 v[18:19], v[252:253], 0, s[38:39]
	s_mov_b32 m0, s2
	s_add_i32 s33, s2, 0x2000
	ds_read_b128 v[42:45], v179 offset:49152
	ds_read_b128 v[50:53], v179 offset:50176
	ds_read_b128 v[132:135], v179 offset:51200
	ds_read_b128 v[136:139], v179 offset:52224
	ds_read_b128 v[232:235], v179 offset:53248
	ds_read_b128 v[236:239], v179 offset:54272
	ds_read_b128 v[240:243], v179 offset:55296
	ds_read_b128 v[244:247], v179 offset:56320
	global_load_lds_dwordx4 v[18:19], off
	v_lshl_add_u64 v[18:19], v[252:253], 0, s[6:7]
	s_mov_b32 m0, s33
	s_mov_b64 s[12:13], 0x40180
	s_add_i32 s82, s82, s51
	global_load_lds_dwordx4 v[18:19], off
	v_lshl_add_u64 v[18:19], v[252:253], 0, s[12:13]
	s_mov_b32 m0, s82
	s_mov_b64 s[12:13], 0x60180
	s_add_i32 s50, s82, 0x2000
	global_load_lds_dwordx4 v[18:19], off
	v_lshl_add_u64 v[18:19], v[252:253], 0, s[12:13]
	s_mov_b32 m0, s50
	s_nop 0
	global_load_lds_dwordx4 v[18:19], off
	v_lshl_add_u64 v[18:19], v[160:161], 0, s[38:39]
	s_mov_b32 m0, s3
	s_nop 0
	global_load_lds_dwordx4 v[18:19], off
	v_lshl_add_u64 v[18:19], v[160:161], 0, s[6:7]
	s_mov_b32 m0, s76
	s_nop 0
	global_load_lds_dwordx4 v[18:19], off
	s_waitcnt vmcnt(8)
	s_waitcnt lgkmcnt(0)
	s_waitcnt lgkmcnt(0)
	v_mfma_f32_16x16x32_bf16 v[18:21], v[6:9], v[42:45], v[140:143]
	v_mfma_f32_16x16x32_bf16 v[70:73], v[26:29], v[50:53], v[18:21]
	v_mfma_f32_16x16x32_bf16 v[18:21], v[30:33], v[42:45], v[144:147]
	s_barrier
	s_setprio 1
	v_mfma_f32_16x16x32_bf16 v[62:65], v[212:215], v[50:53], v[18:21]
	v_mfma_f32_16x16x32_bf16 v[18:21], v[6:9], v[132:135], v[148:151]
	v_mfma_f32_16x16x32_bf16 v[38:41], v[26:29], v[136:139], v[18:21]
	v_mfma_f32_16x16x32_bf16 v[18:21], v[30:33], v[132:135], v[152:155]
	v_mfma_f32_16x16x32_bf16 v[34:37], v[212:215], v[136:139], v[18:21]
	v_mfma_f32_16x16x32_bf16 v[18:21], v[6:9], v[232:235], v[156:159]
	v_mfma_f32_16x16x32_bf16 v[2:5], v[6:9], v[240:243], v[2:5]
	v_mfma_f32_16x16x32_bf16 v[22:25], v[26:29], v[236:239], v[18:21]
	v_mfma_f32_16x16x32_bf16 v[18:21], v[30:33], v[232:235], v[170:173]
	v_mfma_f32_16x16x32_bf16 v[6:9], v[26:29], v[244:247], v[2:5]
	v_mfma_f32_16x16x32_bf16 v[2:5], v[30:33], v[240:243], v[10:13]
	v_mfma_f32_16x16x32_bf16 v[18:21], v[212:215], v[236:239], v[18:21]
	v_mfma_f32_16x16x32_bf16 v[2:5], v[212:215], v[244:247], v[2:5]
	s_setprio 0
	s_setprio 1
	v_mfma_f32_16x16x32_bf16 v[10:13], v[216:219], v[42:45], v[14:17]
	v_mfma_f32_16x16x32_bf16 v[82:85], v[220:223], v[50:53], v[10:13]
	v_mfma_f32_16x16x32_bf16 v[10:13], v[224:227], v[42:45], v[182:185]
	v_mfma_f32_16x16x32_bf16 v[74:77], v[228:231], v[50:53], v[10:13]
	v_mfma_f32_16x16x32_bf16 v[10:13], v[216:219], v[132:135], v[188:191]
	v_mfma_f32_16x16x32_bf16 v[50:53], v[220:223], v[136:139], v[10:13]
	v_mfma_f32_16x16x32_bf16 v[10:13], v[224:227], v[132:135], v[192:195]
	v_mfma_f32_16x16x32_bf16 v[42:45], v[228:231], v[136:139], v[10:13]
	v_mfma_f32_16x16x32_bf16 v[10:13], v[216:219], v[232:235], v[196:199]
	v_mfma_f32_16x16x32_bf16 v[30:33], v[220:223], v[236:239], v[10:13]
	v_mfma_f32_16x16x32_bf16 v[10:13], v[224:227], v[232:235], v[200:203]
	v_mfma_f32_16x16x32_bf16 v[26:29], v[228:231], v[236:239], v[10:13]
	v_mfma_f32_16x16x32_bf16 v[10:13], v[216:219], v[240:243], v[204:207]
	v_mfma_f32_16x16x32_bf16 v[14:17], v[220:223], v[244:247], v[10:13]
	v_mfma_f32_16x16x32_bf16 v[10:13], v[224:227], v[240:243], v[208:211]
	v_mfma_f32_16x16x32_bf16 v[10:13], v[228:231], v[244:247], v[10:13]
	s_setprio 0
	s_barrier
	s_add_u32 s48, s48, 0x40180
	s_addc_u32 s49, s49, 0
	s_add_u32 s36, s64, 0x200
	s_addc_u32 s37, s65, 0
	s_mov_b32 s64, 0
.LBB0_713:
	ds_read_b128 v[132:135], v177
	ds_read_b128 v[136:139], v177 offset:1024
	ds_read_b128 v[140:143], v177 offset:2048
	ds_read_b128 v[144:147], v177 offset:3072
	ds_read_b128 v[148:151], v178
	ds_read_b128 v[152:155], v178 offset:1024
	ds_read_b128 v[156:159], v178 offset:2048
	ds_read_b128 v[170:173], v178 offset:3072
	s_add_u32 s12, s48, 0xfffc0080
	s_addc_u32 s13, s49, -1
	s_cmp_eq_u32 s64, 12
	s_cselect_b32 s13, s41, s13
	s_cselect_b32 s12, s45, s12
	s_cselect_b32 s15, s58, s37
	s_cselect_b32 s14, s59, s36
	s_mov_b32 m0, s60
	v_lshl_add_u64 v[160:161], s[48:49], 0, v[168:169]
	ds_read_b128 v[182:185], v179
	ds_read_b128 v[188:191], v179 offset:1024
	ds_read_b128 v[192:195], v179 offset:2048
	ds_read_b128 v[196:199], v179 offset:3072
	ds_read_b128 v[200:203], v179 offset:4096
	ds_read_b128 v[204:207], v179 offset:5120
	ds_read_b128 v[208:211], v179 offset:6144
	ds_read_b128 v[212:215], v179 offset:7168
	global_load_lds_dwordx4 v[160:161], off
	v_lshl_add_u64 v[160:161], v[160:161], 0, s[86:87]
	s_mov_b32 m0, s61
	s_nop 0
	global_load_lds_dwordx4 v[160:161], off
	s_waitcnt vmcnt(8)
	s_waitcnt lgkmcnt(0)
	s_waitcnt lgkmcnt(0)
	v_mfma_f32_16x16x32_bf16 v[118:121], v[132:135], v[182:185], v[118:121]
	v_mfma_f32_16x16x32_bf16 v[114:117], v[140:143], v[182:185], v[114:117]
	v_mfma_f32_16x16x32_bf16 v[102:105], v[132:135], v[192:195], v[102:105]
	s_barrier
	s_setprio 1
	v_mfma_f32_16x16x32_bf16 v[98:101], v[140:143], v[192:195], v[98:101]
	v_mfma_f32_16x16x32_bf16 v[86:89], v[132:135], v[200:203], v[86:89]
	v_mfma_f32_16x16x32_bf16 v[78:81], v[140:143], v[200:203], v[78:81]
	v_mfma_f32_16x16x32_bf16 v[54:57], v[132:135], v[208:211], v[54:57]
	v_mfma_f32_16x16x32_bf16 v[46:49], v[140:143], v[208:211], v[46:49]
	v_mfma_f32_16x16x32_bf16 v[118:121], v[136:139], v[188:191], v[118:121]
	v_mfma_f32_16x16x32_bf16 v[114:117], v[144:147], v[188:191], v[114:117]
	v_mfma_f32_16x16x32_bf16 v[102:105], v[136:139], v[196:199], v[102:105]
	v_mfma_f32_16x16x32_bf16 v[98:101], v[144:147], v[196:199], v[98:101]
	v_mfma_f32_16x16x32_bf16 v[86:89], v[136:139], v[204:207], v[86:89]
	v_mfma_f32_16x16x32_bf16 v[78:81], v[144:147], v[204:207], v[78:81]
	v_mfma_f32_16x16x32_bf16 v[54:57], v[136:139], v[212:215], v[54:57]
	v_mfma_f32_16x16x32_bf16 v[46:49], v[144:147], v[212:215], v[46:49]
	s_setprio 0
	s_setprio 1
	v_mfma_f32_16x16x32_bf16 v[126:129], v[148:151], v[182:185], v[126:129]
	v_mfma_f32_16x16x32_bf16 v[122:125], v[156:159], v[182:185], v[122:125]
	v_mfma_f32_16x16x32_bf16 v[110:113], v[148:151], v[192:195], v[110:113]
	v_mfma_f32_16x16x32_bf16 v[106:109], v[156:159], v[192:195], v[106:109]
	v_mfma_f32_16x16x32_bf16 v[94:97], v[148:151], v[200:203], v[94:97]
	v_mfma_f32_16x16x32_bf16 v[90:93], v[156:159], v[200:203], v[90:93]
	v_mfma_f32_16x16x32_bf16 v[66:69], v[148:151], v[208:211], v[66:69]
	v_mfma_f32_16x16x32_bf16 v[58:61], v[156:159], v[208:211], v[58:61]
	v_mfma_f32_16x16x32_bf16 v[126:129], v[152:155], v[188:191], v[126:129]
	v_mfma_f32_16x16x32_bf16 v[122:125], v[170:173], v[188:191], v[122:125]
	v_mfma_f32_16x16x32_bf16 v[110:113], v[152:155], v[196:199], v[110:113]
	v_mfma_f32_16x16x32_bf16 v[106:109], v[170:173], v[196:199], v[106:109]
	v_mfma_f32_16x16x32_bf16 v[94:97], v[152:155], v[204:207], v[94:97]
	v_mfma_f32_16x16x32_bf16 v[90:93], v[170:173], v[204:207], v[90:93]
	v_mfma_f32_16x16x32_bf16 v[66:69], v[152:155], v[212:215], v[66:69]
	v_mfma_f32_16x16x32_bf16 v[58:61], v[170:173], v[212:215], v[58:61]
	s_setprio 0
	s_barrier
	s_mov_b32 m0, s63
	v_lshl_add_u64 v[160:161], s[14:15], 0, v[164:165]
	ds_read_b128 v[182:185], v179 offset:16384
	ds_read_b128 v[188:191], v179 offset:17408
	ds_read_b128 v[192:195], v179 offset:18432
	ds_read_b128 v[196:199], v179 offset:19456
	ds_read_b128 v[200:203], v179 offset:20480
	ds_read_b128 v[204:207], v179 offset:21504
	ds_read_b128 v[208:211], v179 offset:22528
	ds_read_b128 v[212:215], v179 offset:23552
	global_load_lds_dwordx4 v[160:161], off
	v_lshl_add_u64 v[216:217], v[160:161], 0, s[86:87]
	s_mov_b32 m0, vcc_lo
	s_nop 0
	global_load_lds_dwordx4 v[216:217], off
	v_lshl_add_u64 v[216:217], v[160:161], 0, s[88:89]
	s_mov_b32 m0, vcc_hi
	s_nop 0
	global_load_lds_dwordx4 v[216:217], off
	v_lshl_add_u64 v[216:217], v[160:161], 0, s[90:91]
	s_mov_b32 m0, s54
	s_nop 0
	global_load_lds_dwordx4 v[216:217], off
	v_lshl_add_u64 v[216:217], s[12:13], 0, v[162:163]
	s_mov_b32 m0, s92
	v_lshl_add_u64 v[218:219], v[216:217], 0, s[86:87]
	global_load_lds_dwordx4 v[216:217], off
	s_mov_b32 m0, s93
	s_nop 0
	global_load_lds_dwordx4 v[218:219], off
	s_waitcnt vmcnt(8)
	s_waitcnt lgkmcnt(0)
	s_waitcnt lgkmcnt(0)
	v_mfma_f32_16x16x32_bf16 v[70:73], v[132:135], v[182:185], v[70:73]
	v_mfma_f32_16x16x32_bf16 v[62:65], v[140:143], v[182:185], v[62:65]
	v_mfma_f32_16x16x32_bf16 v[38:41], v[132:135], v[192:195], v[38:41]
	s_barrier
	s_setprio 1
	v_mfma_f32_16x16x32_bf16 v[34:37], v[140:143], v[192:195], v[34:37]
	v_mfma_f32_16x16x32_bf16 v[22:25], v[132:135], v[200:203], v[22:25]
	v_mfma_f32_16x16x32_bf16 v[18:21], v[140:143], v[200:203], v[18:21]
	v_mfma_f32_16x16x32_bf16 v[6:9], v[132:135], v[208:211], v[6:9]
	v_mfma_f32_16x16x32_bf16 v[2:5], v[140:143], v[208:211], v[2:5]
	v_mfma_f32_16x16x32_bf16 v[70:73], v[136:139], v[188:191], v[70:73]
	v_mfma_f32_16x16x32_bf16 v[62:65], v[144:147], v[188:191], v[62:65]
	v_mfma_f32_16x16x32_bf16 v[38:41], v[136:139], v[196:199], v[38:41]
	v_mfma_f32_16x16x32_bf16 v[34:37], v[144:147], v[196:199], v[34:37]
	v_mfma_f32_16x16x32_bf16 v[22:25], v[136:139], v[204:207], v[22:25]
	v_mfma_f32_16x16x32_bf16 v[18:21], v[144:147], v[204:207], v[18:21]
	v_mfma_f32_16x16x32_bf16 v[6:9], v[136:139], v[212:215], v[6:9]
	v_mfma_f32_16x16x32_bf16 v[2:5], v[144:147], v[212:215], v[2:5]
	s_setprio 0
	s_setprio 1
	v_mfma_f32_16x16x32_bf16 v[82:85], v[148:151], v[182:185], v[82:85]
	v_mfma_f32_16x16x32_bf16 v[74:77], v[156:159], v[182:185], v[74:77]
	v_mfma_f32_16x16x32_bf16 v[50:53], v[148:151], v[192:195], v[50:53]
	v_mfma_f32_16x16x32_bf16 v[42:45], v[156:159], v[192:195], v[42:45]
	v_mfma_f32_16x16x32_bf16 v[30:33], v[148:151], v[200:203], v[30:33]
	v_mfma_f32_16x16x32_bf16 v[26:29], v[156:159], v[200:203], v[26:29]
	v_mfma_f32_16x16x32_bf16 v[14:17], v[148:151], v[208:211], v[14:17]
	v_mfma_f32_16x16x32_bf16 v[10:13], v[156:159], v[208:211], v[10:13]
	v_mfma_f32_16x16x32_bf16 v[82:85], v[152:155], v[188:191], v[82:85]
	v_mfma_f32_16x16x32_bf16 v[74:77], v[170:173], v[188:191], v[74:77]
	v_mfma_f32_16x16x32_bf16 v[50:53], v[152:155], v[196:199], v[50:53]
	v_mfma_f32_16x16x32_bf16 v[42:45], v[170:173], v[196:199], v[42:45]
	v_mfma_f32_16x16x32_bf16 v[30:33], v[152:155], v[204:207], v[30:33]
	v_mfma_f32_16x16x32_bf16 v[26:29], v[170:173], v[204:207], v[26:29]
	v_mfma_f32_16x16x32_bf16 v[14:17], v[152:155], v[212:215], v[14:17]
	v_mfma_f32_16x16x32_bf16 v[10:13], v[170:173], v[212:215], v[10:13]
	s_setprio 0
	s_barrier
	ds_read_b128 v[132:135], v130
	ds_read_b128 v[136:139], v130 offset:1024
	ds_read_b128 v[140:143], v130 offset:2048
	ds_read_b128 v[144:147], v130 offset:3072
	ds_read_b128 v[148:151], v131
	ds_read_b128 v[152:155], v131 offset:1024
	ds_read_b128 v[156:159], v131 offset:2048
	ds_read_b128 v[170:173], v131 offset:3072
	s_mov_b32 m0, s0
	v_lshl_add_u64 v[218:219], v[216:217], 0, s[88:89]
	ds_read_b128 v[182:185], v179 offset:32768
	ds_read_b128 v[188:191], v179 offset:33792
	ds_read_b128 v[192:195], v179 offset:34816
	ds_read_b128 v[196:199], v179 offset:35840
	ds_read_b128 v[200:203], v179 offset:36864
	ds_read_b128 v[204:207], v179 offset:37888
	ds_read_b128 v[208:211], v179 offset:38912
	ds_read_b128 v[212:215], v179 offset:39936
	global_load_lds_dwordx4 v[218:219], off
	v_lshl_add_u64 v[218:219], v[216:217], 0, s[90:91]
	s_mov_b32 m0, s1
	s_nop 0
	global_load_lds_dwordx4 v[218:219], off
	s_waitcnt vmcnt(8)
	s_waitcnt lgkmcnt(0)
	s_waitcnt lgkmcnt(0)
	v_mfma_f32_16x16x32_bf16 v[118:121], v[132:135], v[182:185], v[118:121]
	v_mfma_f32_16x16x32_bf16 v[114:117], v[140:143], v[182:185], v[114:117]
	v_mfma_f32_16x16x32_bf16 v[102:105], v[132:135], v[192:195], v[102:105]
	s_barrier
	s_setprio 1
	v_mfma_f32_16x16x32_bf16 v[98:101], v[140:143], v[192:195], v[98:101]
	v_mfma_f32_16x16x32_bf16 v[86:89], v[132:135], v[200:203], v[86:89]
	v_mfma_f32_16x16x32_bf16 v[78:81], v[140:143], v[200:203], v[78:81]
	v_mfma_f32_16x16x32_bf16 v[54:57], v[132:135], v[208:211], v[54:57]
	v_mfma_f32_16x16x32_bf16 v[46:49], v[140:143], v[208:211], v[46:49]
	v_mfma_f32_16x16x32_bf16 v[118:121], v[136:139], v[188:191], v[118:121]
	v_mfma_f32_16x16x32_bf16 v[114:117], v[144:147], v[188:191], v[114:117]
	v_mfma_f32_16x16x32_bf16 v[102:105], v[136:139], v[196:199], v[102:105]
	v_mfma_f32_16x16x32_bf16 v[98:101], v[144:147], v[196:199], v[98:101]
	v_mfma_f32_16x16x32_bf16 v[86:89], v[136:139], v[204:207], v[86:89]
	v_mfma_f32_16x16x32_bf16 v[78:81], v[144:147], v[204:207], v[78:81]
	v_mfma_f32_16x16x32_bf16 v[54:57], v[136:139], v[212:215], v[54:57]
	v_mfma_f32_16x16x32_bf16 v[46:49], v[144:147], v[212:215], v[46:49]
	s_setprio 0
	s_setprio 1
	v_mfma_f32_16x16x32_bf16 v[126:129], v[148:151], v[182:185], v[126:129]
	v_mfma_f32_16x16x32_bf16 v[122:125], v[156:159], v[182:185], v[122:125]
	v_mfma_f32_16x16x32_bf16 v[110:113], v[148:151], v[192:195], v[110:113]
	v_mfma_f32_16x16x32_bf16 v[106:109], v[156:159], v[192:195], v[106:109]
	v_mfma_f32_16x16x32_bf16 v[94:97], v[148:151], v[200:203], v[94:97]
	v_mfma_f32_16x16x32_bf16 v[90:93], v[156:159], v[200:203], v[90:93]
	v_mfma_f32_16x16x32_bf16 v[66:69], v[148:151], v[208:211], v[66:69]
	v_mfma_f32_16x16x32_bf16 v[58:61], v[156:159], v[208:211], v[58:61]
	v_mfma_f32_16x16x32_bf16 v[126:129], v[152:155], v[188:191], v[126:129]
	v_mfma_f32_16x16x32_bf16 v[122:125], v[170:173], v[188:191], v[122:125]
	v_mfma_f32_16x16x32_bf16 v[110:113], v[152:155], v[196:199], v[110:113]
	v_mfma_f32_16x16x32_bf16 v[106:109], v[170:173], v[196:199], v[106:109]
	v_mfma_f32_16x16x32_bf16 v[94:97], v[152:155], v[204:207], v[94:97]
	v_mfma_f32_16x16x32_bf16 v[90:93], v[170:173], v[204:207], v[90:93]
	v_mfma_f32_16x16x32_bf16 v[66:69], v[152:155], v[212:215], v[66:69]
	v_mfma_f32_16x16x32_bf16 v[58:61], v[170:173], v[212:215], v[58:61]
	s_setprio 0
	s_barrier
	s_mov_b32 m0, s2
	v_lshl_add_u64 v[218:219], v[160:161], 0, s[94:95]
	ds_read_b128 v[182:185], v179 offset:49152
	ds_read_b128 v[188:191], v179 offset:50176
	ds_read_b128 v[192:195], v179 offset:51200
	ds_read_b128 v[196:199], v179 offset:52224
	ds_read_b128 v[200:203], v179 offset:53248
	ds_read_b128 v[204:207], v179 offset:54272
	ds_read_b128 v[208:211], v179 offset:55296
	ds_read_b128 v[212:215], v179 offset:56320
	global_load_lds_dwordx4 v[218:219], off
	v_lshl_add_u64 v[218:219], v[160:161], 0, s[96:97]
	s_mov_b32 m0, s33
	s_nop 0
	global_load_lds_dwordx4 v[218:219], off
	v_lshl_add_u64 v[218:219], v[160:161], 0, s[72:73]
	s_mov_b32 m0, s82
	v_lshl_add_u64 v[160:161], v[160:161], 0, s[78:79]
	global_load_lds_dwordx4 v[218:219], off
	s_mov_b32 m0, s50
	s_nop 0
	global_load_lds_dwordx4 v[160:161], off
	v_lshl_add_u64 v[160:161], v[216:217], 0, s[94:95]
	s_mov_b32 m0, s3
	s_nop 0
	global_load_lds_dwordx4 v[160:161], off
	v_lshl_add_u64 v[160:161], v[216:217], 0, s[96:97]
	s_mov_b32 m0, s76
	s_nop 0
	global_load_lds_dwordx4 v[160:161], off
	s_waitcnt vmcnt(8)
	s_waitcnt lgkmcnt(0)
	s_waitcnt lgkmcnt(0)
	v_mfma_f32_16x16x32_bf16 v[70:73], v[132:135], v[182:185], v[70:73]
	v_mfma_f32_16x16x32_bf16 v[62:65], v[140:143], v[182:185], v[62:65]
	v_mfma_f32_16x16x32_bf16 v[38:41], v[132:135], v[192:195], v[38:41]
	s_barrier
	s_setprio 1
	v_mfma_f32_16x16x32_bf16 v[34:37], v[140:143], v[192:195], v[34:37]
	v_mfma_f32_16x16x32_bf16 v[22:25], v[132:135], v[200:203], v[22:25]
	v_mfma_f32_16x16x32_bf16 v[18:21], v[140:143], v[200:203], v[18:21]
	v_mfma_f32_16x16x32_bf16 v[6:9], v[132:135], v[208:211], v[6:9]
	v_mfma_f32_16x16x32_bf16 v[2:5], v[140:143], v[208:211], v[2:5]
	v_mfma_f32_16x16x32_bf16 v[70:73], v[136:139], v[188:191], v[70:73]
	v_mfma_f32_16x16x32_bf16 v[62:65], v[144:147], v[188:191], v[62:65]
	v_mfma_f32_16x16x32_bf16 v[38:41], v[136:139], v[196:199], v[38:41]
	v_mfma_f32_16x16x32_bf16 v[34:37], v[144:147], v[196:199], v[34:37]
	v_mfma_f32_16x16x32_bf16 v[22:25], v[136:139], v[204:207], v[22:25]
	v_mfma_f32_16x16x32_bf16 v[18:21], v[144:147], v[204:207], v[18:21]
	v_mfma_f32_16x16x32_bf16 v[6:9], v[136:139], v[212:215], v[6:9]
	v_mfma_f32_16x16x32_bf16 v[2:5], v[144:147], v[212:215], v[2:5]
	s_setprio 0
	s_setprio 1
	v_mfma_f32_16x16x32_bf16 v[82:85], v[148:151], v[182:185], v[82:85]
	v_mfma_f32_16x16x32_bf16 v[74:77], v[156:159], v[182:185], v[74:77]
	v_mfma_f32_16x16x32_bf16 v[50:53], v[148:151], v[192:195], v[50:53]
	v_mfma_f32_16x16x32_bf16 v[42:45], v[156:159], v[192:195], v[42:45]
	v_mfma_f32_16x16x32_bf16 v[30:33], v[148:151], v[200:203], v[30:33]
	v_mfma_f32_16x16x32_bf16 v[26:29], v[156:159], v[200:203], v[26:29]
	v_mfma_f32_16x16x32_bf16 v[14:17], v[148:151], v[208:211], v[14:17]
	v_mfma_f32_16x16x32_bf16 v[10:13], v[156:159], v[208:211], v[10:13]
	v_mfma_f32_16x16x32_bf16 v[82:85], v[152:155], v[188:191], v[82:85]
	v_mfma_f32_16x16x32_bf16 v[74:77], v[170:173], v[188:191], v[74:77]
	v_mfma_f32_16x16x32_bf16 v[50:53], v[152:155], v[196:199], v[50:53]
	v_mfma_f32_16x16x32_bf16 v[42:45], v[170:173], v[196:199], v[42:45]
	v_mfma_f32_16x16x32_bf16 v[30:33], v[152:155], v[204:207], v[30:33]
	v_mfma_f32_16x16x32_bf16 v[26:29], v[170:173], v[204:207], v[26:29]
	v_mfma_f32_16x16x32_bf16 v[14:17], v[152:155], v[212:215], v[14:17]
	v_mfma_f32_16x16x32_bf16 v[10:13], v[170:173], v[212:215], v[10:13]
	s_setprio 0
	s_barrier
	s_add_i32 s64, s64, 2
	s_add_u32 s48, s48, 0x100
	s_addc_u32 s49, s49, 0
	s_add_u32 s36, s36, 0x100
	s_addc_u32 s37, s37, 0
	s_cmp_gt_u32 s64, 13
	s_cbranch_scc0 .LBB0_713
	s_and_b64 vcc, exec, s[34:35]
	s_cbranch_vccz .LBB0_716
	s_barrier

.LBB0_975:
	s_ashr_i32 s91, s90, 31
	s_lshl_b64 s[12:13], s[90:91], 19
	s_add_u32 s2, s8, s12
	s_addc_u32 s12, s9, s13
	s_add_u32 s94, s2, s6
	s_addc_u32 s95, s12, s7
	s_and_b64 s[12:13], s[92:93], exec
	s_cselect_b32 s12, s95, s41
	s_cselect_b32 s13, s94, s40
	s_ashr_i32 s89, s88, 31
	s_lshl_b64 s[14:15], s[88:89], 19
	v_readlane_b32 s16, v255, 19
	ds_read_b128 v[2:5], v172
	ds_read_b128 v[6:9], v172 offset:1024
	ds_read_b128 v[10:13], v172 offset:2048
	ds_read_b128 v[14:17], v172 offset:3072
	ds_read_b128 v[18:21], v173
	ds_read_b128 v[22:25], v173 offset:1024
	ds_read_b128 v[26:29], v173 offset:2048
	ds_read_b128 v[30:33], v173 offset:3072
	v_readlane_b32 s17, v255, 20
	s_add_u32 s2, s16, s14
	s_addc_u32 s14, s17, s15
	s_add_u32 s96, s2, s6
	s_addc_u32 s97, s14, s7
	s_add_u32 s2, s40, 0x100
	s_addc_u32 s14, s41, 0
	s_add_u32 s16, s30, 0x100
	s_addc_u32 s15, s31, 0
	s_and_b64 s[6:7], s[92:93], exec
	s_cselect_b32 s45, s96, s30
	s_cselect_b32 s46, s97, s31
	s_cmp_eq_u32 s54, 2
	s_cselect_b32 s7, s12, s14
	s_cselect_b32 s6, s13, s2
	s_cselect_b32 s15, s46, s15
	s_cselect_b32 s14, s45, s16
	v_lshl_add_u64 v[66:67], s[40:41], 0, v[134:135]
	s_add_i32 s47, s25, 0xc000
	v_lshl_add_u64 v[68:69], v[66:67], 0, s[72:73]
	s_mov_b32 m0, s47
	s_add_i32 s48, s25, 0xe000
	ds_read_b128 v[34:37], v174
	ds_read_b128 v[38:41], v174 offset:1024
	ds_read_b128 v[42:45], v174 offset:2048
	ds_read_b128 v[46:49], v174 offset:3072
	ds_read_b128 v[50:53], v174 offset:4096
	ds_read_b128 v[54:57], v174 offset:5120
	ds_read_b128 v[58:61], v174 offset:6144
	ds_read_b128 v[62:65], v174 offset:7168
	global_load_lds_dwordx4 v[68:69], off
	v_lshl_add_u64 v[66:67], v[66:67], 0, s[74:75]
	s_mov_b32 m0, s48
	s_nop 0
	global_load_lds_dwordx4 v[66:67], off
	s_waitcnt vmcnt(8)
	s_waitcnt lgkmcnt(0)
	s_waitcnt lgkmcnt(0)
	v_mfma_f32_16x16x32_bf16 v[90:93], v[2:5], v[58:61], 0
	v_mfma_f32_16x16x32_bf16 v[66:69], v[2:5], v[34:37], 0
	v_mfma_f32_16x16x32_bf16 v[70:73], v[10:13], v[34:37], 0
	s_barrier
	s_setprio 1
	v_mfma_f32_16x16x32_bf16 v[74:77], v[2:5], v[42:45], 0
	v_mfma_f32_16x16x32_bf16 v[78:81], v[10:13], v[42:45], 0
	v_mfma_f32_16x16x32_bf16 v[82:85], v[2:5], v[50:53], 0
	v_mfma_f32_16x16x32_bf16 v[86:89], v[10:13], v[50:53], 0
	v_mfma_f32_16x16x32_bf16 v[98:101], v[6:9], v[62:65], v[90:93]
	v_mfma_f32_16x16x32_bf16 v[90:93], v[10:13], v[58:61], 0
	v_mfma_f32_16x16x32_bf16 v[66:69], v[6:9], v[38:41], v[66:69]
	v_mfma_f32_16x16x32_bf16 v[70:73], v[14:17], v[38:41], v[70:73]
	v_mfma_f32_16x16x32_bf16 v[74:77], v[6:9], v[46:49], v[74:77]
	v_mfma_f32_16x16x32_bf16 v[78:81], v[14:17], v[46:49], v[78:81]
	v_mfma_f32_16x16x32_bf16 v[82:85], v[6:9], v[54:57], v[82:85]
	v_mfma_f32_16x16x32_bf16 v[86:89], v[14:17], v[54:57], v[86:89]
	v_mfma_f32_16x16x32_bf16 v[102:105], v[14:17], v[62:65], v[90:93]
	s_setprio 0
	s_setprio 1
	v_mfma_f32_16x16x32_bf16 v[90:93], v[18:21], v[34:37], 0
	v_mfma_f32_16x16x32_bf16 v[34:37], v[26:29], v[34:37], 0
	v_mfma_f32_16x16x32_bf16 v[114:117], v[22:25], v[38:41], v[90:93]
	v_mfma_f32_16x16x32_bf16 v[34:37], v[30:33], v[38:41], v[34:37]
	v_mfma_f32_16x16x32_bf16 v[38:41], v[18:21], v[42:45], 0
	v_mfma_f32_16x16x32_bf16 v[42:45], v[26:29], v[42:45], 0
	v_mfma_f32_16x16x32_bf16 v[38:41], v[22:25], v[46:49], v[38:41]
	v_mfma_f32_16x16x32_bf16 v[42:45], v[30:33], v[46:49], v[42:45]
	v_mfma_f32_16x16x32_bf16 v[46:49], v[18:21], v[50:53], 0
	v_mfma_f32_16x16x32_bf16 v[50:53], v[26:29], v[50:53], 0
	v_mfma_f32_16x16x32_bf16 v[46:49], v[22:25], v[54:57], v[46:49]
	v_mfma_f32_16x16x32_bf16 v[50:53], v[30:33], v[54:57], v[50:53]
	v_mfma_f32_16x16x32_bf16 v[54:57], v[18:21], v[58:61], 0
	v_mfma_f32_16x16x32_bf16 v[58:61], v[26:29], v[58:61], 0
	v_mfma_f32_16x16x32_bf16 v[54:57], v[22:25], v[62:65], v[54:57]
	v_mfma_f32_16x16x32_bf16 v[58:61], v[30:33], v[62:65], v[58:61]
	s_setprio 0
	s_barrier
	s_add_i32 s49, s85, s55
	v_lshl_add_u64 v[166:167], s[14:15], 0, v[136:137]
	s_mov_b32 m0, s49
	s_add_i32 s50, s49, 0x2000
	ds_read_b128 v[62:65], v174 offset:16384
	ds_read_b128 v[90:93], v174 offset:17408
	ds_read_b128 v[94:97], v174 offset:18432
	ds_read_b128 v[106:109], v174 offset:19456
	ds_read_b128 v[110:113], v174 offset:20480
	ds_read_b128 v[118:121], v174 offset:21504
	ds_read_b128 v[122:125], v174 offset:22528
	ds_read_b128 v[126:129], v174 offset:23552
	global_load_lds_dwordx4 v[166:167], off
	v_lshl_add_u64 v[130:131], v[166:167], 0, s[28:29]
	s_mov_b32 m0, s50
	s_add_i32 s51, s86, s55
	global_load_lds_dwordx4 v[130:131], off
	v_lshl_add_u64 v[130:131], v[166:167], 0, s[34:35]
	s_mov_b32 m0, s51
	s_add_i32 s58, s51, 0x2000
	global_load_lds_dwordx4 v[130:131], off
	v_lshl_add_u64 v[130:131], v[166:167], 0, s[38:39]
	s_mov_b32 m0, s58
	v_lshl_add_u64 v[184:185], s[6:7], 0, v[134:135]
	global_load_lds_dwordx4 v[130:131], off
	s_mov_b32 m0, s25
	v_lshl_add_u64 v[130:131], v[184:185], 0, s[28:29]
	global_load_lds_dwordx4 v[184:185], off
	s_mov_b32 m0, s27
	s_nop 0
	global_load_lds_dwordx4 v[130:131], off
	s_waitcnt vmcnt(8)
	s_waitcnt lgkmcnt(0)
	s_waitcnt lgkmcnt(0)
	v_mfma_f32_16x16x32_bf16 v[130:133], v[2:5], v[62:65], 0
	v_mfma_f32_16x16x32_bf16 v[142:145], v[6:9], v[90:93], v[130:133]
	v_mfma_f32_16x16x32_bf16 v[130:133], v[10:13], v[62:65], 0
	s_barrier
	s_setprio 1
	v_mfma_f32_16x16x32_bf16 v[146:149], v[14:17], v[90:93], v[130:133]
	v_mfma_f32_16x16x32_bf16 v[130:133], v[2:5], v[94:97], 0
	v_mfma_f32_16x16x32_bf16 v[150:153], v[6:9], v[106:109], v[130:133]
	v_mfma_f32_16x16x32_bf16 v[130:133], v[10:13], v[94:97], 0
	v_mfma_f32_16x16x32_bf16 v[154:157], v[14:17], v[106:109], v[130:133]
	v_mfma_f32_16x16x32_bf16 v[130:133], v[2:5], v[110:113], 0
	v_mfma_f32_16x16x32_bf16 v[2:5], v[2:5], v[122:125], 0
	v_mfma_f32_16x16x32_bf16 v[158:161], v[6:9], v[118:121], v[130:133]
	v_mfma_f32_16x16x32_bf16 v[2:5], v[6:9], v[126:129], v[2:5]
	v_mfma_f32_16x16x32_bf16 v[6:9], v[10:13], v[122:125], 0
	v_mfma_f32_16x16x32_bf16 v[130:133], v[10:13], v[110:113], 0
	v_mfma_f32_16x16x32_bf16 v[6:9], v[14:17], v[126:129], v[6:9]
	v_mfma_f32_16x16x32_bf16 v[162:165], v[14:17], v[118:121], v[130:133]
	s_setprio 0
	s_setprio 1
	v_mfma_f32_16x16x32_bf16 v[10:13], v[18:21], v[62:65], 0
	v_mfma_f32_16x16x32_bf16 v[176:179], v[22:25], v[90:93], v[10:13]
	v_mfma_f32_16x16x32_bf16 v[10:13], v[26:29], v[62:65], 0
	v_mfma_f32_16x16x32_bf16 v[180:183], v[30:33], v[90:93], v[10:13]
	v_mfma_f32_16x16x32_bf16 v[10:13], v[18:21], v[94:97], 0
	v_mfma_f32_16x16x32_bf16 v[188:191], v[22:25], v[106:109], v[10:13]
	v_mfma_f32_16x16x32_bf16 v[10:13], v[26:29], v[94:97], 0
	v_mfma_f32_16x16x32_bf16 v[192:195], v[30:33], v[106:109], v[10:13]
	v_mfma_f32_16x16x32_bf16 v[10:13], v[18:21], v[110:113], 0
	v_mfma_f32_16x16x32_bf16 v[198:201], v[22:25], v[118:121], v[10:13]
	v_mfma_f32_16x16x32_bf16 v[10:13], v[26:29], v[110:113], 0
	v_mfma_f32_16x16x32_bf16 v[202:205], v[30:33], v[118:121], v[10:13]
	v_mfma_f32_16x16x32_bf16 v[10:13], v[18:21], v[122:125], 0
	v_mfma_f32_16x16x32_bf16 v[206:209], v[22:25], v[126:129], v[10:13]
	v_mfma_f32_16x16x32_bf16 v[10:13], v[26:29], v[122:125], 0
	v_mfma_f32_16x16x32_bf16 v[210:213], v[30:33], v[126:129], v[10:13]
	s_setprio 0
	s_barrier
	s_add_i32 s2, 0, 0x18000
	s_add_i32 s66, 0, 0x1c000
	v_add_u32_e32 v130, s2, v170
	v_add_u32_e32 v131, s66, v170
	s_nop 0
	ds_read_b128 v[10:13], v130
	ds_read_b128 v[14:17], v130 offset:1024
	ds_read_b128 v[18:21], v130 offset:2048
	ds_read_b128 v[22:25], v130 offset:3072
	ds_read_b128 v[214:217], v131
	ds_read_b128 v[218:221], v131 offset:1024
	ds_read_b128 v[222:225], v131 offset:2048
	ds_read_b128 v[226:229], v131 offset:3072
	s_mov_b32 m0, s56
	v_lshl_add_u64 v[90:91], v[184:185], 0, s[34:35]
	ds_read_b128 v[26:29], v174 offset:32768
	ds_read_b128 v[30:33], v174 offset:33792
	ds_read_b128 v[62:65], v174 offset:34816
	ds_read_b128 v[230:233], v174 offset:35840
	ds_read_b128 v[234:237], v174 offset:36864
	ds_read_b128 v[238:241], v174 offset:37888
	ds_read_b128 v[242:245], v174 offset:38912
	ds_read_b128 v[246:249], v174 offset:39936
	global_load_lds_dwordx4 v[90:91], off
	v_lshl_add_u64 v[90:91], v[184:185], 0, s[38:39]
	s_mov_b32 m0, s57
	s_nop 0
	global_load_lds_dwordx4 v[90:91], off
	s_waitcnt vmcnt(8)
	s_waitcnt lgkmcnt(0)
	s_waitcnt lgkmcnt(0)
	v_mfma_f32_16x16x32_bf16 v[66:69], v[10:13], v[26:29], v[66:69]
	v_mfma_f32_16x16x32_bf16 v[126:129], v[14:17], v[30:33], v[66:69]
	v_mfma_f32_16x16x32_bf16 v[66:69], v[18:21], v[26:29], v[70:73]
	s_barrier
	s_setprio 1
	v_mfma_f32_16x16x32_bf16 v[122:125], v[22:25], v[30:33], v[66:69]
	v_mfma_f32_16x16x32_bf16 v[66:69], v[10:13], v[62:65], v[74:77]
	v_mfma_f32_16x16x32_bf16 v[110:113], v[14:17], v[230:233], v[66:69]
	v_mfma_f32_16x16x32_bf16 v[66:69], v[18:21], v[62:65], v[78:81]
	v_mfma_f32_16x16x32_bf16 v[106:109], v[22:25], v[230:233], v[66:69]
	v_mfma_f32_16x16x32_bf16 v[66:69], v[10:13], v[234:237], v[82:85]
	v_mfma_f32_16x16x32_bf16 v[94:97], v[14:17], v[238:241], v[66:69]
	v_mfma_f32_16x16x32_bf16 v[66:69], v[18:21], v[234:237], v[86:89]
	v_mfma_f32_16x16x32_bf16 v[90:93], v[22:25], v[238:241], v[66:69]
	v_mfma_f32_16x16x32_bf16 v[66:69], v[10:13], v[242:245], v[98:101]
	v_mfma_f32_16x16x32_bf16 v[78:81], v[14:17], v[246:249], v[66:69]
	v_mfma_f32_16x16x32_bf16 v[66:69], v[18:21], v[242:245], v[102:105]
	v_mfma_f32_16x16x32_bf16 v[70:73], v[22:25], v[246:249], v[66:69]
	s_setprio 0
	s_setprio 1
	v_mfma_f32_16x16x32_bf16 v[66:69], v[214:217], v[26:29], v[114:117]
	v_mfma_f32_16x16x32_bf16 v[26:29], v[222:225], v[26:29], v[34:37]
	v_mfma_f32_16x16x32_bf16 v[114:117], v[226:229], v[30:33], v[26:29]
	v_mfma_f32_16x16x32_bf16 v[26:29], v[214:217], v[62:65], v[38:41]
	v_mfma_f32_16x16x32_bf16 v[102:105], v[218:221], v[230:233], v[26:29]
	v_mfma_f32_16x16x32_bf16 v[26:29], v[222:225], v[62:65], v[42:45]
	v_mfma_f32_16x16x32_bf16 v[98:101], v[226:229], v[230:233], v[26:29]
	v_mfma_f32_16x16x32_bf16 v[26:29], v[214:217], v[234:237], v[46:49]
	v_mfma_f32_16x16x32_bf16 v[86:89], v[218:221], v[238:241], v[26:29]
	v_mfma_f32_16x16x32_bf16 v[26:29], v[222:225], v[234:237], v[50:53]
	v_mfma_f32_16x16x32_bf16 v[82:85], v[226:229], v[238:241], v[26:29]
	v_mfma_f32_16x16x32_bf16 v[26:29], v[214:217], v[242:245], v[54:57]
	v_mfma_f32_16x16x32_bf16 v[118:121], v[218:221], v[30:33], v[66:69]
	v_mfma_f32_16x16x32_bf16 v[66:69], v[218:221], v[246:249], v[26:29]
	v_mfma_f32_16x16x32_bf16 v[26:29], v[222:225], v[242:245], v[58:61]
	v_mfma_f32_16x16x32_bf16 v[54:57], v[226:229], v[246:249], v[26:29]
	s_setprio 0
	s_barrier
	s_add_i32 s2, s2, s55
	s_nop 3
	v_lshl_add_u64 v[26:27], v[166:167], 0, s[62:63]
	s_mov_b32 m0, s2
	s_add_i32 s33, s2, 0x2000
	ds_read_b128 v[34:37], v174 offset:49152
	ds_read_b128 v[38:41], v174 offset:50176
	ds_read_b128 v[230:233], v174 offset:51200
	ds_read_b128 v[234:237], v174 offset:52224
	ds_read_b128 v[238:241], v174 offset:53248
	ds_read_b128 v[242:245], v174 offset:54272
	ds_read_b128 v[246:249], v174 offset:55296
	ds_read_b128 v[250:253], v174 offset:56320
	global_load_lds_dwordx4 v[26:27], off
	v_lshl_add_u64 v[26:27], v[166:167], 0, s[64:65]
	s_mov_b32 m0, s33
	s_add_i32 s66, s66, s55
	global_load_lds_dwordx4 v[26:27], off
	v_lshl_add_u64 v[26:27], v[166:167], 0, s[72:73]
	s_mov_b32 m0, s66
	s_add_i32 s67, s66, 0x2000
	global_load_lds_dwordx4 v[26:27], off
	v_lshl_add_u64 v[26:27], v[166:167], 0, s[74:75]
	s_mov_b32 m0, s67
	s_nop 0
	global_load_lds_dwordx4 v[26:27], off
	v_lshl_add_u64 v[26:27], v[184:185], 0, s[62:63]
	s_mov_b32 m0, s82
	s_nop 0
	global_load_lds_dwordx4 v[26:27], off
	v_lshl_add_u64 v[26:27], v[184:185], 0, s[64:65]
	s_mov_b32 m0, s83
	s_nop 0
	global_load_lds_dwordx4 v[26:27], off
	s_waitcnt vmcnt(8)
	s_waitcnt lgkmcnt(0)
	s_waitcnt lgkmcnt(0)
	v_mfma_f32_16x16x32_bf16 v[26:29], v[10:13], v[34:37], v[142:145]
	v_mfma_f32_16x16x32_bf16 v[74:77], v[14:17], v[38:41], v[26:29]
	v_mfma_f32_16x16x32_bf16 v[26:29], v[18:21], v[34:37], v[146:149]
	s_barrier
	s_setprio 1
	v_mfma_f32_16x16x32_bf16 v[62:65], v[22:25], v[38:41], v[26:29]
	v_mfma_f32_16x16x32_bf16 v[26:29], v[10:13], v[230:233], v[150:153]
	v_mfma_f32_16x16x32_bf16 v[46:49], v[14:17], v[234:237], v[26:29]
	v_mfma_f32_16x16x32_bf16 v[26:29], v[18:21], v[230:233], v[154:157]
	v_mfma_f32_16x16x32_bf16 v[42:45], v[22:25], v[234:237], v[26:29]
	v_mfma_f32_16x16x32_bf16 v[26:29], v[10:13], v[238:241], v[158:161]
	v_mfma_f32_16x16x32_bf16 v[2:5], v[10:13], v[246:249], v[2:5]
	v_mfma_f32_16x16x32_bf16 v[30:33], v[14:17], v[242:245], v[26:29]
	v_mfma_f32_16x16x32_bf16 v[26:29], v[18:21], v[238:241], v[162:165]
	v_mfma_f32_16x16x32_bf16 v[14:17], v[14:17], v[250:253], v[2:5]
	v_mfma_f32_16x16x32_bf16 v[2:5], v[18:21], v[246:249], v[6:9]
	v_mfma_f32_16x16x32_bf16 v[26:29], v[22:25], v[242:245], v[26:29]
	v_mfma_f32_16x16x32_bf16 v[10:13], v[22:25], v[250:253], v[2:5]
	s_setprio 0
	s_setprio 1
	v_mfma_f32_16x16x32_bf16 v[2:5], v[214:217], v[34:37], v[176:179]
	v_mfma_f32_16x16x32_bf16 v[58:61], v[218:221], v[38:41], v[2:5]
	v_mfma_f32_16x16x32_bf16 v[2:5], v[222:225], v[34:37], v[180:183]
	v_mfma_f32_16x16x32_bf16 v[50:53], v[226:229], v[38:41], v[2:5]
	v_mfma_f32_16x16x32_bf16 v[2:5], v[214:217], v[230:233], v[188:191]
	v_mfma_f32_16x16x32_bf16 v[38:41], v[218:221], v[234:237], v[2:5]
	v_mfma_f32_16x16x32_bf16 v[2:5], v[222:225], v[230:233], v[192:195]
	v_mfma_f32_16x16x32_bf16 v[34:37], v[226:229], v[234:237], v[2:5]
	v_mfma_f32_16x16x32_bf16 v[2:5], v[214:217], v[238:241], v[198:201]
	v_mfma_f32_16x16x32_bf16 v[22:25], v[218:221], v[242:245], v[2:5]
	v_mfma_f32_16x16x32_bf16 v[2:5], v[222:225], v[238:241], v[202:205]
	v_mfma_f32_16x16x32_bf16 v[18:21], v[226:229], v[242:245], v[2:5]
	v_mfma_f32_16x16x32_bf16 v[2:5], v[214:217], v[246:249], v[206:209]
	v_mfma_f32_16x16x32_bf16 v[6:9], v[218:221], v[250:253], v[2:5]
	v_mfma_f32_16x16x32_bf16 v[2:5], v[222:225], v[246:249], v[210:213]
	v_mfma_f32_16x16x32_bf16 v[2:5], v[226:229], v[250:253], v[2:5]
	s_setprio 0
	s_barrier
	s_cmp_lt_i32 s54, 3
	s_cbranch_scc1 .LBB0_978
	s_add_u32 s6, s40, 0x40180
	s_addc_u32 s7, s41, 0
	s_add_u32 s36, s30, 0x200
	s_addc_u32 s37, s31, 0
	s_mov_b32 s89, 4
.LBB0_977:
	ds_read_b128 v[142:145], v172
	ds_read_b128 v[146:149], v172 offset:1024
	ds_read_b128 v[150:153], v172 offset:2048
	ds_read_b128 v[154:157], v172 offset:3072
	ds_read_b128 v[158:161], v173
	ds_read_b128 v[162:165], v173 offset:1024
	ds_read_b128 v[176:179], v173 offset:2048
	ds_read_b128 v[180:183], v173 offset:3072
	s_add_u32 s14, s6, 0xfffc0080
	s_addc_u32 s15, s7, -1
	s_cmp_eq_u32 s54, s89
	s_cselect_b32 s15, s12, s15
	s_cselect_b32 s14, s13, s14
	s_cselect_b32 s17, s46, s37
	s_cselect_b32 s16, s45, s36
	s_mov_b32 m0, s47
	v_lshl_add_u64 v[132:133], s[6:7], 0, v[138:139]
	ds_read_b128 v[188:191], v174
	ds_read_b128 v[192:195], v174 offset:1024
	ds_read_b128 v[198:201], v174 offset:2048
	ds_read_b128 v[202:205], v174 offset:3072
	ds_read_b128 v[206:209], v174 offset:4096
	ds_read_b128 v[210:213], v174 offset:5120
	ds_read_b128 v[214:217], v174 offset:6144
	ds_read_b128 v[218:221], v174 offset:7168
	global_load_lds_dwordx4 v[132:133], off
	v_lshl_add_u64 v[132:133], v[132:133], 0, s[28:29]
	s_mov_b32 m0, s48
	s_nop 0
	global_load_lds_dwordx4 v[132:133], off
	s_waitcnt vmcnt(8)
	s_waitcnt lgkmcnt(0)
	s_waitcnt lgkmcnt(0)
	v_mfma_f32_16x16x32_bf16 v[126:129], v[142:145], v[188:191], v[126:129]
	v_mfma_f32_16x16x32_bf16 v[122:125], v[150:153], v[188:191], v[122:125]
	v_mfma_f32_16x16x32_bf16 v[110:113], v[142:145], v[198:201], v[110:113]
	s_barrier
	s_setprio 1
	v_mfma_f32_16x16x32_bf16 v[106:109], v[150:153], v[198:201], v[106:109]
	v_mfma_f32_16x16x32_bf16 v[94:97], v[142:145], v[206:209], v[94:97]
	v_mfma_f32_16x16x32_bf16 v[90:93], v[150:153], v[206:209], v[90:93]
	v_mfma_f32_16x16x32_bf16 v[78:81], v[142:145], v[214:217], v[78:81]
	v_mfma_f32_16x16x32_bf16 v[70:73], v[150:153], v[214:217], v[70:73]
	v_mfma_f32_16x16x32_bf16 v[126:129], v[146:149], v[192:195], v[126:129]
	v_mfma_f32_16x16x32_bf16 v[122:125], v[154:157], v[192:195], v[122:125]
	v_mfma_f32_16x16x32_bf16 v[110:113], v[146:149], v[202:205], v[110:113]
	v_mfma_f32_16x16x32_bf16 v[106:109], v[154:157], v[202:205], v[106:109]
	v_mfma_f32_16x16x32_bf16 v[94:97], v[146:149], v[210:213], v[94:97]
	v_mfma_f32_16x16x32_bf16 v[90:93], v[154:157], v[210:213], v[90:93]
	v_mfma_f32_16x16x32_bf16 v[78:81], v[146:149], v[218:221], v[78:81]
	v_mfma_f32_16x16x32_bf16 v[70:73], v[154:157], v[218:221], v[70:73]
	s_setprio 0
	s_setprio 1
	v_mfma_f32_16x16x32_bf16 v[118:121], v[158:161], v[188:191], v[118:121]
	v_mfma_f32_16x16x32_bf16 v[114:117], v[176:179], v[188:191], v[114:117]
	v_mfma_f32_16x16x32_bf16 v[102:105], v[158:161], v[198:201], v[102:105]
	v_mfma_f32_16x16x32_bf16 v[98:101], v[176:179], v[198:201], v[98:101]
	v_mfma_f32_16x16x32_bf16 v[86:89], v[158:161], v[206:209], v[86:89]
	v_mfma_f32_16x16x32_bf16 v[82:85], v[176:179], v[206:209], v[82:85]
	v_mfma_f32_16x16x32_bf16 v[66:69], v[158:161], v[214:217], v[66:69]
	v_mfma_f32_16x16x32_bf16 v[54:57], v[176:179], v[214:217], v[54:57]
	v_mfma_f32_16x16x32_bf16 v[118:121], v[162:165], v[192:195], v[118:121]
	v_mfma_f32_16x16x32_bf16 v[114:117], v[180:183], v[192:195], v[114:117]
	v_mfma_f32_16x16x32_bf16 v[102:105], v[162:165], v[202:205], v[102:105]
	v_mfma_f32_16x16x32_bf16 v[98:101], v[180:183], v[202:205], v[98:101]
	v_mfma_f32_16x16x32_bf16 v[86:89], v[162:165], v[210:213], v[86:89]
	v_mfma_f32_16x16x32_bf16 v[82:85], v[180:183], v[210:213], v[82:85]
	v_mfma_f32_16x16x32_bf16 v[66:69], v[162:165], v[218:221], v[66:69]
	v_mfma_f32_16x16x32_bf16 v[54:57], v[180:183], v[218:221], v[54:57]
	s_setprio 0
	s_barrier
	s_mov_b32 m0, s49
	v_lshl_add_u64 v[132:133], s[16:17], 0, v[136:137]
	ds_read_b128 v[188:191], v174 offset:16384
	ds_read_b128 v[192:195], v174 offset:17408
	ds_read_b128 v[198:201], v174 offset:18432
	ds_read_b128 v[202:205], v174 offset:19456
	ds_read_b128 v[206:209], v174 offset:20480
	ds_read_b128 v[210:213], v174 offset:21504
	ds_read_b128 v[214:217], v174 offset:22528
	ds_read_b128 v[218:221], v174 offset:23552
	global_load_lds_dwordx4 v[132:133], off
	v_lshl_add_u64 v[166:167], v[132:133], 0, s[28:29]
	s_mov_b32 m0, s50
	s_nop 0
	global_load_lds_dwordx4 v[166:167], off
	v_lshl_add_u64 v[166:167], v[132:133], 0, s[34:35]
	s_mov_b32 m0, s51
	s_nop 0
	global_load_lds_dwordx4 v[166:167], off
	v_lshl_add_u64 v[166:167], v[132:133], 0, s[38:39]
	s_mov_b32 m0, s58
	s_nop 0
	global_load_lds_dwordx4 v[166:167], off
	v_lshl_add_u64 v[166:167], s[14:15], 0, v[134:135]
	s_mov_b32 m0, s25
	v_lshl_add_u64 v[184:185], v[166:167], 0, s[28:29]
	global_load_lds_dwordx4 v[166:167], off
	s_mov_b32 m0, s27
	s_nop 0
	global_load_lds_dwordx4 v[184:185], off
	s_waitcnt vmcnt(8)
	s_waitcnt lgkmcnt(0)
	s_waitcnt lgkmcnt(0)
	v_mfma_f32_16x16x32_bf16 v[74:77], v[142:145], v[188:191], v[74:77]
	v_mfma_f32_16x16x32_bf16 v[62:65], v[150:153], v[188:191], v[62:65]
	v_mfma_f32_16x16x32_bf16 v[46:49], v[142:145], v[198:201], v[46:49]
	s_barrier
	s_setprio 1
	v_mfma_f32_16x16x32_bf16 v[42:45], v[150:153], v[198:201], v[42:45]
	v_mfma_f32_16x16x32_bf16 v[30:33], v[142:145], v[206:209], v[30:33]
	v_mfma_f32_16x16x32_bf16 v[26:29], v[150:153], v[206:209], v[26:29]
	v_mfma_f32_16x16x32_bf16 v[14:17], v[142:145], v[214:217], v[14:17]
	v_mfma_f32_16x16x32_bf16 v[10:13], v[150:153], v[214:217], v[10:13]
	v_mfma_f32_16x16x32_bf16 v[74:77], v[146:149], v[192:195], v[74:77]
	v_mfma_f32_16x16x32_bf16 v[62:65], v[154:157], v[192:195], v[62:65]
	v_mfma_f32_16x16x32_bf16 v[46:49], v[146:149], v[202:205], v[46:49]
	v_mfma_f32_16x16x32_bf16 v[42:45], v[154:157], v[202:205], v[42:45]
	v_mfma_f32_16x16x32_bf16 v[30:33], v[146:149], v[210:213], v[30:33]
	v_mfma_f32_16x16x32_bf16 v[26:29], v[154:157], v[210:213], v[26:29]
	v_mfma_f32_16x16x32_bf16 v[14:17], v[146:149], v[218:221], v[14:17]
	v_mfma_f32_16x16x32_bf16 v[10:13], v[154:157], v[218:221], v[10:13]
	s_setprio 0
	s_setprio 1
	v_mfma_f32_16x16x32_bf16 v[58:61], v[158:161], v[188:191], v[58:61]
	v_mfma_f32_16x16x32_bf16 v[50:53], v[176:179], v[188:191], v[50:53]
	v_mfma_f32_16x16x32_bf16 v[38:41], v[158:161], v[198:201], v[38:41]
	v_mfma_f32_16x16x32_bf16 v[34:37], v[176:179], v[198:201], v[34:37]
	v_mfma_f32_16x16x32_bf16 v[22:25], v[158:161], v[206:209], v[22:25]
	v_mfma_f32_16x16x32_bf16 v[18:21], v[176:179], v[206:209], v[18:21]
	v_mfma_f32_16x16x32_bf16 v[6:9], v[158:161], v[214:217], v[6:9]
	v_mfma_f32_16x16x32_bf16 v[2:5], v[176:179], v[214:217], v[2:5]
	v_mfma_f32_16x16x32_bf16 v[58:61], v[162:165], v[192:195], v[58:61]
	v_mfma_f32_16x16x32_bf16 v[50:53], v[180:183], v[192:195], v[50:53]
	v_mfma_f32_16x16x32_bf16 v[38:41], v[162:165], v[202:205], v[38:41]
	v_mfma_f32_16x16x32_bf16 v[34:37], v[180:183], v[202:205], v[34:37]
	v_mfma_f32_16x16x32_bf16 v[22:25], v[162:165], v[210:213], v[22:25]
	v_mfma_f32_16x16x32_bf16 v[18:21], v[180:183], v[210:213], v[18:21]
	v_mfma_f32_16x16x32_bf16 v[6:9], v[162:165], v[218:221], v[6:9]
	v_mfma_f32_16x16x32_bf16 v[2:5], v[180:183], v[218:221], v[2:5]
	s_setprio 0
	s_barrier
	ds_read_b128 v[142:145], v130
	ds_read_b128 v[146:149], v130 offset:1024
	ds_read_b128 v[150:153], v130 offset:2048
	ds_read_b128 v[154:157], v130 offset:3072
	ds_read_b128 v[158:161], v131
	ds_read_b128 v[162:165], v131 offset:1024
	ds_read_b128 v[176:179], v131 offset:2048
	ds_read_b128 v[180:183], v131 offset:3072
	s_mov_b32 m0, s56
	v_lshl_add_u64 v[184:185], v[166:167], 0, s[34:35]
	ds_read_b128 v[188:191], v174 offset:32768
	ds_read_b128 v[192:195], v174 offset:33792
	ds_read_b128 v[198:201], v174 offset:34816
	ds_read_b128 v[202:205], v174 offset:35840
	ds_read_b128 v[206:209], v174 offset:36864
	ds_read_b128 v[210:213], v174 offset:37888
	ds_read_b128 v[214:217], v174 offset:38912
	ds_read_b128 v[218:221], v174 offset:39936
	global_load_lds_dwordx4 v[184:185], off
	v_lshl_add_u64 v[184:185], v[166:167], 0, s[38:39]
	s_mov_b32 m0, s57
	s_nop 0
	global_load_lds_dwordx4 v[184:185], off
	s_waitcnt vmcnt(8)
	s_waitcnt lgkmcnt(0)
	s_waitcnt lgkmcnt(0)
	v_mfma_f32_16x16x32_bf16 v[126:129], v[142:145], v[188:191], v[126:129]
	v_mfma_f32_16x16x32_bf16 v[122:125], v[150:153], v[188:191], v[122:125]
	v_mfma_f32_16x16x32_bf16 v[110:113], v[142:145], v[198:201], v[110:113]
	s_barrier
	s_setprio 1
	v_mfma_f32_16x16x32_bf16 v[106:109], v[150:153], v[198:201], v[106:109]
	v_mfma_f32_16x16x32_bf16 v[94:97], v[142:145], v[206:209], v[94:97]
	v_mfma_f32_16x16x32_bf16 v[90:93], v[150:153], v[206:209], v[90:93]
	v_mfma_f32_16x16x32_bf16 v[78:81], v[142:145], v[214:217], v[78:81]
	v_mfma_f32_16x16x32_bf16 v[70:73], v[150:153], v[214:217], v[70:73]
	v_mfma_f32_16x16x32_bf16 v[126:129], v[146:149], v[192:195], v[126:129]
	v_mfma_f32_16x16x32_bf16 v[122:125], v[154:157], v[192:195], v[122:125]
	v_mfma_f32_16x16x32_bf16 v[110:113], v[146:149], v[202:205], v[110:113]
	v_mfma_f32_16x16x32_bf16 v[106:109], v[154:157], v[202:205], v[106:109]
	v_mfma_f32_16x16x32_bf16 v[94:97], v[146:149], v[210:213], v[94:97]
	v_mfma_f32_16x16x32_bf16 v[90:93], v[154:157], v[210:213], v[90:93]
	v_mfma_f32_16x16x32_bf16 v[78:81], v[146:149], v[218:221], v[78:81]
	v_mfma_f32_16x16x32_bf16 v[70:73], v[154:157], v[218:221], v[70:73]
	s_setprio 0
	s_setprio 1
	v_mfma_f32_16x16x32_bf16 v[118:121], v[158:161], v[188:191], v[118:121]
	v_mfma_f32_16x16x32_bf16 v[114:117], v[176:179], v[188:191], v[114:117]
	v_mfma_f32_16x16x32_bf16 v[102:105], v[158:161], v[198:201], v[102:105]
	v_mfma_f32_16x16x32_bf16 v[98:101], v[176:179], v[198:201], v[98:101]
	v_mfma_f32_16x16x32_bf16 v[86:89], v[158:161], v[206:209], v[86:89]
	v_mfma_f32_16x16x32_bf16 v[82:85], v[176:179], v[206:209], v[82:85]
	v_mfma_f32_16x16x32_bf16 v[66:69], v[158:161], v[214:217], v[66:69]
	v_mfma_f32_16x16x32_bf16 v[54:57], v[176:179], v[214:217], v[54:57]
	v_mfma_f32_16x16x32_bf16 v[118:121], v[162:165], v[192:195], v[118:121]
	v_mfma_f32_16x16x32_bf16 v[114:117], v[180:183], v[192:195], v[114:117]
	v_mfma_f32_16x16x32_bf16 v[102:105], v[162:165], v[202:205], v[102:105]
	v_mfma_f32_16x16x32_bf16 v[98:101], v[180:183], v[202:205], v[98:101]
	v_mfma_f32_16x16x32_bf16 v[86:89], v[162:165], v[210:213], v[86:89]
	v_mfma_f32_16x16x32_bf16 v[82:85], v[180:183], v[210:213], v[82:85]
	v_mfma_f32_16x16x32_bf16 v[66:69], v[162:165], v[218:221], v[66:69]
	v_mfma_f32_16x16x32_bf16 v[54:57], v[180:183], v[218:221], v[54:57]
	s_setprio 0
	s_barrier
	s_mov_b32 m0, s2
	v_lshl_add_u64 v[184:185], v[132:133], 0, s[62:63]
	ds_read_b128 v[188:191], v174 offset:49152
	ds_read_b128 v[192:195], v174 offset:50176
	ds_read_b128 v[198:201], v174 offset:51200
	ds_read_b128 v[202:205], v174 offset:52224
	ds_read_b128 v[206:209], v174 offset:53248
	ds_read_b128 v[210:213], v174 offset:54272
	ds_read_b128 v[214:217], v174 offset:55296
	ds_read_b128 v[218:221], v174 offset:56320
	global_load_lds_dwordx4 v[184:185], off
	v_lshl_add_u64 v[184:185], v[132:133], 0, s[64:65]
	s_mov_b32 m0, s33
	s_nop 0
	global_load_lds_dwordx4 v[184:185], off
	v_lshl_add_u64 v[184:185], v[132:133], 0, s[72:73]
	s_mov_b32 m0, s66
	v_lshl_add_u64 v[132:133], v[132:133], 0, s[74:75]
	global_load_lds_dwordx4 v[184:185], off
	s_mov_b32 m0, s67
	s_nop 0
	global_load_lds_dwordx4 v[132:133], off
	v_lshl_add_u64 v[132:133], v[166:167], 0, s[62:63]
	s_mov_b32 m0, s82
	s_nop 0
	global_load_lds_dwordx4 v[132:133], off
	v_lshl_add_u64 v[132:133], v[166:167], 0, s[64:65]
	s_mov_b32 m0, s83
	s_nop 0
	global_load_lds_dwordx4 v[132:133], off
	s_waitcnt vmcnt(8)
	s_waitcnt lgkmcnt(0)
	s_waitcnt lgkmcnt(0)
	v_mfma_f32_16x16x32_bf16 v[74:77], v[142:145], v[188:191], v[74:77]
	v_mfma_f32_16x16x32_bf16 v[62:65], v[150:153], v[188:191], v[62:65]
	v_mfma_f32_16x16x32_bf16 v[46:49], v[142:145], v[198:201], v[46:49]
	s_barrier
	s_setprio 1
	v_mfma_f32_16x16x32_bf16 v[42:45], v[150:153], v[198:201], v[42:45]
	v_mfma_f32_16x16x32_bf16 v[30:33], v[142:145], v[206:209], v[30:33]
	v_mfma_f32_16x16x32_bf16 v[26:29], v[150:153], v[206:209], v[26:29]
	v_mfma_f32_16x16x32_bf16 v[14:17], v[142:145], v[214:217], v[14:17]
	v_mfma_f32_16x16x32_bf16 v[10:13], v[150:153], v[214:217], v[10:13]
	v_mfma_f32_16x16x32_bf16 v[74:77], v[146:149], v[192:195], v[74:77]
	v_mfma_f32_16x16x32_bf16 v[62:65], v[154:157], v[192:195], v[62:65]
	v_mfma_f32_16x16x32_bf16 v[46:49], v[146:149], v[202:205], v[46:49]
	v_mfma_f32_16x16x32_bf16 v[42:45], v[154:157], v[202:205], v[42:45]
	v_mfma_f32_16x16x32_bf16 v[30:33], v[146:149], v[210:213], v[30:33]
	v_mfma_f32_16x16x32_bf16 v[26:29], v[154:157], v[210:213], v[26:29]
	v_mfma_f32_16x16x32_bf16 v[14:17], v[146:149], v[218:221], v[14:17]
	v_mfma_f32_16x16x32_bf16 v[10:13], v[154:157], v[218:221], v[10:13]
	s_setprio 0
	s_setprio 1
	v_mfma_f32_16x16x32_bf16 v[58:61], v[158:161], v[188:191], v[58:61]
	v_mfma_f32_16x16x32_bf16 v[50:53], v[176:179], v[188:191], v[50:53]
	v_mfma_f32_16x16x32_bf16 v[38:41], v[158:161], v[198:201], v[38:41]
	v_mfma_f32_16x16x32_bf16 v[34:37], v[176:179], v[198:201], v[34:37]
	v_mfma_f32_16x16x32_bf16 v[22:25], v[158:161], v[206:209], v[22:25]
	v_mfma_f32_16x16x32_bf16 v[18:21], v[176:179], v[206:209], v[18:21]
	v_mfma_f32_16x16x32_bf16 v[6:9], v[158:161], v[214:217], v[6:9]
	v_mfma_f32_16x16x32_bf16 v[2:5], v[176:179], v[214:217], v[2:5]
	v_mfma_f32_16x16x32_bf16 v[58:61], v[162:165], v[192:195], v[58:61]
	v_mfma_f32_16x16x32_bf16 v[50:53], v[180:183], v[192:195], v[50:53]
	v_mfma_f32_16x16x32_bf16 v[38:41], v[162:165], v[202:205], v[38:41]
	v_mfma_f32_16x16x32_bf16 v[34:37], v[180:183], v[202:205], v[34:37]
	v_mfma_f32_16x16x32_bf16 v[22:25], v[162:165], v[210:213], v[22:25]
	v_mfma_f32_16x16x32_bf16 v[18:21], v[180:183], v[210:213], v[18:21]
	v_mfma_f32_16x16x32_bf16 v[6:9], v[162:165], v[218:221], v[6:9]
	v_mfma_f32_16x16x32_bf16 v[2:5], v[180:183], v[218:221], v[2:5]
	s_setprio 0
	s_barrier
	s_add_i32 s14, s89, 2
	s_add_u32 s6, s6, 0x100
	s_addc_u32 s7, s7, 0
	s_add_u32 s36, s36, 0x100
	s_addc_u32 s37, s37, 0
	s_cmp_ge_i32 s89, s54
	s_mov_b32 s89, s14
	s_cbranch_scc0 .LBB0_977

.LBB0_1332:
	s_ashr_i32 s75, s74, 31
	s_lshl_b64 s[0:1], s[74:75], 19
	v_readlane_b32 s18, v255, 21
	v_readlane_b32 s19, v255, 22
	s_add_u32 s3, s18, s0
	ds_read_b128 v[2:5], v190
	ds_read_b128 v[6:9], v190 offset:1024
	ds_read_b128 v[10:13], v190 offset:2048
	ds_read_b128 v[14:17], v190 offset:3072
	ds_read_b128 v[18:21], v191
	ds_read_b128 v[22:25], v191 offset:1024
	ds_read_b128 v[26:29], v191 offset:2048
	ds_read_b128 v[30:33], v191 offset:3072
	s_addc_u32 s18, s19, s1
	s_lshl_b64 s[0:1], s[50:51], 7
	s_add_u32 s86, s3, s0
	s_addc_u32 s87, s18, s1
	s_add_u32 s3, s38, 0x440000
	s_addc_u32 s18, s39, 0
	s_add_u32 s20, s24, 0x100
	s_addc_u32 s21, s25, 0
	s_and_b64 s[0:1], s[80:81], exec
	s_cselect_b32 s46, s86, s24
	s_cselect_b32 s75, s87, s25
	s_cmp_eq_u32 s76, 2
	s_cselect_b32 s1, s75, s21
	s_cselect_b32 s0, s46, s20
	s_cselect_b32 s19, s85, s18
	s_cselect_b32 s18, s84, s3
	v_lshl_add_u64 v[66:67], s[38:39], 0, v[150:151]
	s_mov_b64 s[20:21], 0x221000
	s_add_i32 s79, s13, 0xc000
	v_lshl_add_u64 v[68:69], v[66:67], 0, s[20:21]
	s_mov_b32 m0, s79
	s_mov_b64 s[20:21], 0x221800
	s_add_i32 s92, s13, 0xe000
	ds_read_b128 v[34:37], v192
	ds_read_b128 v[38:41], v192 offset:1024
	ds_read_b128 v[42:45], v192 offset:2048
	ds_read_b128 v[46:49], v192 offset:3072
	ds_read_b128 v[50:53], v192 offset:4096
	ds_read_b128 v[54:57], v192 offset:5120
	ds_read_b128 v[58:61], v192 offset:6144
	ds_read_b128 v[62:65], v192 offset:7168
	global_load_lds_dwordx4 v[68:69], off
	v_lshl_add_u64 v[66:67], v[66:67], 0, s[20:21]
	s_mov_b32 m0, s92
	s_nop 0
	global_load_lds_dwordx4 v[66:67], off
	s_waitcnt vmcnt(8)
	s_waitcnt lgkmcnt(0)
	s_waitcnt lgkmcnt(0)
	v_mfma_f32_16x16x32_bf16 v[86:89], v[10:13], v[50:53], 0
	v_mfma_f32_16x16x32_bf16 v[90:93], v[14:17], v[54:57], v[86:89]
	v_mfma_f32_16x16x32_bf16 v[86:89], v[2:5], v[58:61], 0
	s_barrier
	s_setprio 1
	v_mfma_f32_16x16x32_bf16 v[66:69], v[2:5], v[34:37], 0
	v_mfma_f32_16x16x32_bf16 v[70:73], v[10:13], v[34:37], 0
	v_mfma_f32_16x16x32_bf16 v[74:77], v[2:5], v[42:45], 0
	v_mfma_f32_16x16x32_bf16 v[78:81], v[10:13], v[42:45], 0
	v_mfma_f32_16x16x32_bf16 v[82:85], v[2:5], v[50:53], 0
	v_mfma_f32_16x16x32_bf16 v[94:97], v[6:9], v[62:65], v[86:89]
	v_mfma_f32_16x16x32_bf16 v[86:89], v[10:13], v[58:61], 0
	v_mfma_f32_16x16x32_bf16 v[66:69], v[6:9], v[38:41], v[66:69]
	v_mfma_f32_16x16x32_bf16 v[70:73], v[14:17], v[38:41], v[70:73]
	v_mfma_f32_16x16x32_bf16 v[74:77], v[6:9], v[46:49], v[74:77]
	v_mfma_f32_16x16x32_bf16 v[78:81], v[14:17], v[46:49], v[78:81]
	v_mfma_f32_16x16x32_bf16 v[82:85], v[6:9], v[54:57], v[82:85]
	v_mfma_f32_16x16x32_bf16 v[106:109], v[14:17], v[62:65], v[86:89]
	s_setprio 0
	s_setprio 1
	v_mfma_f32_16x16x32_bf16 v[86:89], v[18:21], v[34:37], 0
	v_mfma_f32_16x16x32_bf16 v[34:37], v[26:29], v[34:37], 0
	v_mfma_f32_16x16x32_bf16 v[110:113], v[22:25], v[38:41], v[86:89]
	v_mfma_f32_16x16x32_bf16 v[34:37], v[30:33], v[38:41], v[34:37]
	v_mfma_f32_16x16x32_bf16 v[38:41], v[18:21], v[42:45], 0
	v_mfma_f32_16x16x32_bf16 v[42:45], v[26:29], v[42:45], 0
	v_mfma_f32_16x16x32_bf16 v[38:41], v[22:25], v[46:49], v[38:41]
	v_mfma_f32_16x16x32_bf16 v[42:45], v[30:33], v[46:49], v[42:45]
	v_mfma_f32_16x16x32_bf16 v[46:49], v[18:21], v[50:53], 0
	v_mfma_f32_16x16x32_bf16 v[50:53], v[26:29], v[50:53], 0
	v_mfma_f32_16x16x32_bf16 v[46:49], v[22:25], v[54:57], v[46:49]
	v_mfma_f32_16x16x32_bf16 v[50:53], v[30:33], v[54:57], v[50:53]
	v_mfma_f32_16x16x32_bf16 v[54:57], v[18:21], v[58:61], 0
	v_mfma_f32_16x16x32_bf16 v[54:57], v[22:25], v[62:65], v[54:57]
	v_mfma_f32_16x16x32_bf16 v[58:61], v[26:29], v[58:61], 0
	v_mfma_f32_16x16x32_bf16 v[132:135], v[30:33], v[62:65], v[58:61]
	s_setprio 0
	s_barrier
	s_add_i32 s93, s72, s77
	v_lshl_add_u64 v[148:149], s[0:1], 0, v[152:153]
	s_mov_b32 m0, s93
	s_add_i32 s94, s93, 0x2000
	s_nop 0
	ds_read_b128 v[58:61], v192 offset:16384
	ds_read_b128 v[62:65], v192 offset:17408
	ds_read_b128 v[86:89], v192 offset:18432
	ds_read_b128 v[98:101], v192 offset:19456
	ds_read_b128 v[102:105], v192 offset:20480
	ds_read_b128 v[114:117], v192 offset:21504
	ds_read_b128 v[118:121], v192 offset:22528
	ds_read_b128 v[122:125], v192 offset:23552
	global_load_lds_dwordx4 v[148:149], off
	v_lshl_add_u64 v[126:127], v[148:149], 0, s[16:17]
	s_mov_b32 m0, s94
	s_add_i32 s95, s73, s77
	global_load_lds_dwordx4 v[126:127], off
	v_lshl_add_u64 v[126:127], v[148:149], 0, s[26:27]
	s_mov_b32 m0, s95
	s_add_i32 s0, s95, 0x2000
	global_load_lds_dwordx4 v[126:127], off
	v_lshl_add_u64 v[126:127], v[148:149], 0, s[28:29]
	s_mov_b32 m0, s0
	v_lshl_add_u64 v[182:183], s[18:19], 0, v[150:151]
	global_load_lds_dwordx4 v[126:127], off
	s_mov_b32 m0, s13
	v_lshl_add_u64 v[126:127], v[182:183], 0, s[30:31]
	global_load_lds_dwordx4 v[182:183], off
	s_mov_b32 m0, s15
	s_nop 0
	global_load_lds_dwordx4 v[126:127], off
	s_waitcnt vmcnt(8)
	s_waitcnt lgkmcnt(0)
	s_waitcnt lgkmcnt(0)
	v_mfma_f32_16x16x32_bf16 v[126:129], v[2:5], v[58:61], 0
	v_mfma_f32_16x16x32_bf16 v[136:139], v[6:9], v[62:65], v[126:129]
	v_mfma_f32_16x16x32_bf16 v[126:129], v[10:13], v[58:61], 0
	s_barrier
	s_setprio 1
	v_mfma_f32_16x16x32_bf16 v[140:143], v[14:17], v[62:65], v[126:129]
	v_mfma_f32_16x16x32_bf16 v[126:129], v[2:5], v[86:89], 0
	v_mfma_f32_16x16x32_bf16 v[144:147], v[6:9], v[98:101], v[126:129]
	v_mfma_f32_16x16x32_bf16 v[126:129], v[10:13], v[86:89], 0
	v_mfma_f32_16x16x32_bf16 v[158:161], v[14:17], v[98:101], v[126:129]
	v_mfma_f32_16x16x32_bf16 v[126:129], v[2:5], v[102:105], 0
	v_mfma_f32_16x16x32_bf16 v[2:5], v[2:5], v[118:121], 0
	v_mfma_f32_16x16x32_bf16 v[162:165], v[6:9], v[114:117], v[126:129]
	v_mfma_f32_16x16x32_bf16 v[2:5], v[6:9], v[122:125], v[2:5]
	v_mfma_f32_16x16x32_bf16 v[6:9], v[10:13], v[118:121], 0
	v_mfma_f32_16x16x32_bf16 v[126:129], v[10:13], v[102:105], 0
	v_mfma_f32_16x16x32_bf16 v[10:13], v[14:17], v[122:125], v[6:9]
	v_mfma_f32_16x16x32_bf16 v[166:169], v[14:17], v[114:117], v[126:129]
	s_setprio 0
	s_setprio 1
	v_mfma_f32_16x16x32_bf16 v[6:9], v[18:21], v[58:61], 0
	v_mfma_f32_16x16x32_bf16 v[14:17], v[22:25], v[62:65], v[6:9]
	v_mfma_f32_16x16x32_bf16 v[6:9], v[26:29], v[58:61], 0
	v_mfma_f32_16x16x32_bf16 v[170:173], v[30:33], v[62:65], v[6:9]
	v_mfma_f32_16x16x32_bf16 v[6:9], v[18:21], v[86:89], 0
	v_mfma_f32_16x16x32_bf16 v[174:177], v[22:25], v[98:101], v[6:9]
	v_mfma_f32_16x16x32_bf16 v[6:9], v[26:29], v[86:89], 0
	v_mfma_f32_16x16x32_bf16 v[178:181], v[30:33], v[98:101], v[6:9]
	v_mfma_f32_16x16x32_bf16 v[6:9], v[18:21], v[102:105], 0
	v_mfma_f32_16x16x32_bf16 v[194:197], v[22:25], v[114:117], v[6:9]
	v_mfma_f32_16x16x32_bf16 v[6:9], v[26:29], v[102:105], 0
	v_mfma_f32_16x16x32_bf16 v[198:201], v[30:33], v[114:117], v[6:9]
	v_mfma_f32_16x16x32_bf16 v[6:9], v[18:21], v[118:121], 0
	v_mfma_f32_16x16x32_bf16 v[202:205], v[22:25], v[122:125], v[6:9]
	v_mfma_f32_16x16x32_bf16 v[6:9], v[26:29], v[118:121], 0
	v_mfma_f32_16x16x32_bf16 v[206:209], v[30:33], v[122:125], v[6:9]
	s_setprio 0
	s_barrier
	s_add_i32 s1, 0, 0x18000
	s_add_i32 s3, 0, 0x1c000
	v_add_u32_e32 v130, s1, v188
	v_add_u32_e32 v131, s3, v188
	s_nop 0
	ds_read_b128 v[6:9], v130
	ds_read_b128 v[26:29], v130 offset:1024
	ds_read_b128 v[30:33], v130 offset:2048
	ds_read_b128 v[210:213], v130 offset:3072
	ds_read_b128 v[214:217], v131
	ds_read_b128 v[218:221], v131 offset:1024
	ds_read_b128 v[222:225], v131 offset:2048
	ds_read_b128 v[226:229], v131 offset:3072
	s_mov_b32 m0, s96
	v_lshl_add_u64 v[58:59], v[182:183], 0, s[34:35]
	ds_read_b128 v[18:21], v192 offset:32768
	ds_read_b128 v[22:25], v192 offset:33792
	ds_read_b128 v[230:233], v192 offset:34816
	ds_read_b128 v[234:237], v192 offset:35840
	ds_read_b128 v[238:241], v192 offset:36864
	ds_read_b128 v[242:245], v192 offset:37888
	ds_read_b128 v[246:249], v192 offset:38912
	ds_read_b128 v[250:253], v192 offset:39936
	global_load_lds_dwordx4 v[58:59], off
	v_lshl_add_u64 v[58:59], v[182:183], 0, s[40:41]
	s_mov_b32 m0, s97
	s_nop 0
	global_load_lds_dwordx4 v[58:59], off
	s_waitcnt vmcnt(8)
	s_waitcnt lgkmcnt(0)
	s_waitcnt lgkmcnt(0)
	v_mfma_f32_16x16x32_bf16 v[58:61], v[6:9], v[18:21], v[66:69]
	v_mfma_f32_16x16x32_bf16 v[118:121], v[26:29], v[22:25], v[58:61]
	v_mfma_f32_16x16x32_bf16 v[58:61], v[30:33], v[18:21], v[70:73]
	s_barrier
	s_setprio 1
	v_mfma_f32_16x16x32_bf16 v[114:117], v[210:213], v[22:25], v[58:61]
	v_mfma_f32_16x16x32_bf16 v[58:61], v[6:9], v[230:233], v[74:77]
	v_mfma_f32_16x16x32_bf16 v[102:105], v[26:29], v[234:237], v[58:61]
	v_mfma_f32_16x16x32_bf16 v[58:61], v[30:33], v[230:233], v[78:81]
	v_mfma_f32_16x16x32_bf16 v[98:101], v[210:213], v[234:237], v[58:61]
	v_mfma_f32_16x16x32_bf16 v[58:61], v[6:9], v[238:241], v[82:85]
	v_mfma_f32_16x16x32_bf16 v[86:89], v[26:29], v[242:245], v[58:61]
	v_mfma_f32_16x16x32_bf16 v[58:61], v[30:33], v[238:241], v[90:93]
	v_mfma_f32_16x16x32_bf16 v[82:85], v[210:213], v[242:245], v[58:61]
	v_mfma_f32_16x16x32_bf16 v[58:61], v[6:9], v[246:249], v[94:97]
	v_mfma_f32_16x16x32_bf16 v[62:65], v[26:29], v[250:253], v[58:61]
	v_mfma_f32_16x16x32_bf16 v[58:61], v[30:33], v[246:249], v[106:109]
	v_mfma_f32_16x16x32_bf16 v[58:61], v[210:213], v[250:253], v[58:61]
	s_setprio 0
	s_setprio 1
	v_mfma_f32_16x16x32_bf16 v[66:69], v[214:217], v[18:21], v[110:113]
	v_mfma_f32_16x16x32_bf16 v[18:21], v[222:225], v[18:21], v[34:37]
	v_mfma_f32_16x16x32_bf16 v[122:125], v[226:229], v[22:25], v[18:21]
	v_mfma_f32_16x16x32_bf16 v[18:21], v[214:217], v[230:233], v[38:41]
	v_mfma_f32_16x16x32_bf16 v[110:113], v[218:221], v[234:237], v[18:21]
	v_mfma_f32_16x16x32_bf16 v[18:21], v[222:225], v[230:233], v[42:45]
	v_mfma_f32_16x16x32_bf16 v[106:109], v[226:229], v[234:237], v[18:21]
	v_mfma_f32_16x16x32_bf16 v[18:21], v[214:217], v[238:241], v[46:49]
	v_mfma_f32_16x16x32_bf16 v[94:97], v[218:221], v[242:245], v[18:21]
	v_mfma_f32_16x16x32_bf16 v[18:21], v[222:225], v[238:241], v[50:53]
	v_mfma_f32_16x16x32_bf16 v[90:93], v[226:229], v[242:245], v[18:21]
	v_mfma_f32_16x16x32_bf16 v[18:21], v[214:217], v[246:249], v[54:57]
	v_mfma_f32_16x16x32_bf16 v[78:81], v[218:221], v[250:253], v[18:21]
	v_mfma_f32_16x16x32_bf16 v[18:21], v[222:225], v[246:249], v[132:135]
	v_mfma_f32_16x16x32_bf16 v[126:129], v[218:221], v[22:25], v[66:69]
	v_mfma_f32_16x16x32_bf16 v[74:77], v[226:229], v[250:253], v[18:21]
	s_setprio 0
	s_barrier
	s_add_i32 s1, s1, s77
	s_nop 2
	v_lshl_add_u64 v[18:19], v[148:149], 0, s[48:49]
	s_mov_b32 m0, s1
	s_add_i32 s33, s1, 0x2000
	ds_read_b128 v[42:45], v192 offset:49152
	ds_read_b128 v[46:49], v192 offset:50176
	ds_read_b128 v[132:135], v192 offset:51200
	ds_read_b128 v[230:233], v192 offset:52224
	ds_read_b128 v[234:237], v192 offset:53248
	ds_read_b128 v[238:241], v192 offset:54272
	ds_read_b128 v[242:245], v192 offset:55296
	ds_read_b128 v[246:249], v192 offset:56320
	global_load_lds_dwordx4 v[18:19], off
	v_lshl_add_u64 v[18:19], v[148:149], 0, s[54:55]
	s_mov_b32 m0, s33
	s_add_i32 s3, s3, s77
	global_load_lds_dwordx4 v[18:19], off
	v_lshl_add_u64 v[18:19], v[148:149], 0, s[60:61]
	s_mov_b32 m0, s3
	s_add_i32 s66, s3, 0x2000
	global_load_lds_dwordx4 v[18:19], off
	v_lshl_add_u64 v[18:19], v[148:149], 0, s[62:63]
	s_mov_b32 m0, s66
	s_nop 0
	global_load_lds_dwordx4 v[18:19], off
	v_lshl_add_u64 v[18:19], v[182:183], 0, s[56:57]
	s_mov_b32 m0, s6
	s_nop 0
	global_load_lds_dwordx4 v[18:19], off
	v_lshl_add_u64 v[18:19], v[182:183], 0, s[58:59]
	s_mov_b32 m0, s7
	s_nop 0
	global_load_lds_dwordx4 v[18:19], off
	s_waitcnt vmcnt(8)
	s_waitcnt lgkmcnt(0)
	s_waitcnt lgkmcnt(0)
	v_mfma_f32_16x16x32_bf16 v[18:21], v[6:9], v[42:45], v[136:139]
	v_mfma_f32_16x16x32_bf16 v[54:57], v[26:29], v[46:49], v[18:21]
	v_mfma_f32_16x16x32_bf16 v[18:21], v[30:33], v[42:45], v[140:143]
	s_barrier
	s_setprio 1
	v_mfma_f32_16x16x32_bf16 v[50:53], v[210:213], v[46:49], v[18:21]
	v_mfma_f32_16x16x32_bf16 v[18:21], v[6:9], v[132:135], v[144:147]
	v_mfma_f32_16x16x32_bf16 v[38:41], v[26:29], v[230:233], v[18:21]
	v_mfma_f32_16x16x32_bf16 v[18:21], v[30:33], v[132:135], v[158:161]
	v_mfma_f32_16x16x32_bf16 v[34:37], v[210:213], v[230:233], v[18:21]
	v_mfma_f32_16x16x32_bf16 v[18:21], v[6:9], v[234:237], v[162:165]
	v_mfma_f32_16x16x32_bf16 v[2:5], v[6:9], v[242:245], v[2:5]
	v_mfma_f32_16x16x32_bf16 v[22:25], v[26:29], v[238:241], v[18:21]
	v_mfma_f32_16x16x32_bf16 v[18:21], v[30:33], v[234:237], v[166:169]
	v_mfma_f32_16x16x32_bf16 v[6:9], v[26:29], v[246:249], v[2:5]
	v_mfma_f32_16x16x32_bf16 v[2:5], v[30:33], v[242:245], v[10:13]
	v_mfma_f32_16x16x32_bf16 v[18:21], v[210:213], v[238:241], v[18:21]
	v_mfma_f32_16x16x32_bf16 v[2:5], v[210:213], v[246:249], v[2:5]
	s_setprio 0
	s_setprio 1
	v_mfma_f32_16x16x32_bf16 v[10:13], v[214:217], v[42:45], v[14:17]
	v_mfma_f32_16x16x32_bf16 v[70:73], v[218:221], v[46:49], v[10:13]
	v_mfma_f32_16x16x32_bf16 v[10:13], v[222:225], v[42:45], v[170:173]
	v_mfma_f32_16x16x32_bf16 v[66:69], v[226:229], v[46:49], v[10:13]
	v_mfma_f32_16x16x32_bf16 v[10:13], v[214:217], v[132:135], v[174:177]
	v_mfma_f32_16x16x32_bf16 v[46:49], v[218:221], v[230:233], v[10:13]
	v_mfma_f32_16x16x32_bf16 v[10:13], v[222:225], v[132:135], v[178:181]
	v_mfma_f32_16x16x32_bf16 v[42:45], v[226:229], v[230:233], v[10:13]
	v_mfma_f32_16x16x32_bf16 v[10:13], v[214:217], v[234:237], v[194:197]
	v_mfma_f32_16x16x32_bf16 v[30:33], v[218:221], v[238:241], v[10:13]
	v_mfma_f32_16x16x32_bf16 v[10:13], v[222:225], v[234:237], v[198:201]
	v_mfma_f32_16x16x32_bf16 v[26:29], v[226:229], v[238:241], v[10:13]
	v_mfma_f32_16x16x32_bf16 v[10:13], v[214:217], v[242:245], v[202:205]
	v_mfma_f32_16x16x32_bf16 v[14:17], v[218:221], v[246:249], v[10:13]
	v_mfma_f32_16x16x32_bf16 v[10:13], v[222:225], v[242:245], v[206:209]
	v_mfma_f32_16x16x32_bf16 v[10:13], v[226:229], v[246:249], v[10:13]
	s_setprio 0
	s_barrier
	s_cmp_lt_i32 s76, 3
	s_cbranch_scc1 .LBB0_1338
	s_add_u32 s36, s24, 0x200
	s_addc_u32 s37, s25, 0
	s_add_u32 s50, s38, 0x880000
	s_addc_u32 s51, s39, 0
	s_mov_b32 s67, 4

.LBB0_1336:
	ds_read_b128 v[132:135], v190
	ds_read_b128 v[136:139], v190 offset:1024
	ds_read_b128 v[140:143], v190 offset:2048
	ds_read_b128 v[144:147], v190 offset:3072
	ds_read_b128 v[158:161], v191
	ds_read_b128 v[162:165], v191 offset:1024
	ds_read_b128 v[166:169], v191 offset:2048
	ds_read_b128 v[170:173], v191 offset:3072
	s_and_b64 s[18:19], exec, s[90:91]
	s_cselect_b32 s19, s75, s37
	s_cselect_b32 s18, s46, s36
	s_mov_b32 s20, 0xffde1000
	v_lshl_add_u64 v[148:149], s[50:51], 0, v[154:155]
	s_mov_b32 s21, -1
	v_lshl_add_u64 v[182:183], v[148:149], 0, s[20:21]
	s_mov_b32 s20, 0xffde1800
	s_mov_b32 m0, s79
	s_mov_b32 s21, -1
	ds_read_b128 v[174:177], v192
	ds_read_b128 v[178:181], v192 offset:1024
	ds_read_b128 v[194:197], v192 offset:2048
	ds_read_b128 v[198:201], v192 offset:3072
	ds_read_b128 v[202:205], v192 offset:4096
	ds_read_b128 v[206:209], v192 offset:5120
	ds_read_b128 v[210:213], v192 offset:6144
	ds_read_b128 v[214:217], v192 offset:7168
	global_load_lds_dwordx4 v[182:183], off
	v_lshl_add_u64 v[148:149], v[148:149], 0, s[20:21]
	s_mov_b32 m0, s92
	s_nop 0
	global_load_lds_dwordx4 v[148:149], off
	s_waitcnt vmcnt(8)
	s_waitcnt lgkmcnt(0)
	s_waitcnt lgkmcnt(0)
	v_mfma_f32_16x16x32_bf16 v[118:121], v[132:135], v[174:177], v[118:121]
	v_mfma_f32_16x16x32_bf16 v[114:117], v[140:143], v[174:177], v[114:117]
	v_mfma_f32_16x16x32_bf16 v[102:105], v[132:135], v[194:197], v[102:105]
	s_barrier
	s_setprio 1
	v_mfma_f32_16x16x32_bf16 v[98:101], v[140:143], v[194:197], v[98:101]
	v_mfma_f32_16x16x32_bf16 v[86:89], v[132:135], v[202:205], v[86:89]
	v_mfma_f32_16x16x32_bf16 v[82:85], v[140:143], v[202:205], v[82:85]
	v_mfma_f32_16x16x32_bf16 v[62:65], v[132:135], v[210:213], v[62:65]
	v_mfma_f32_16x16x32_bf16 v[58:61], v[140:143], v[210:213], v[58:61]
	v_mfma_f32_16x16x32_bf16 v[118:121], v[136:139], v[178:181], v[118:121]
	v_mfma_f32_16x16x32_bf16 v[114:117], v[144:147], v[178:181], v[114:117]
	v_mfma_f32_16x16x32_bf16 v[102:105], v[136:139], v[198:201], v[102:105]
	v_mfma_f32_16x16x32_bf16 v[98:101], v[144:147], v[198:201], v[98:101]
	v_mfma_f32_16x16x32_bf16 v[86:89], v[136:139], v[206:209], v[86:89]
	v_mfma_f32_16x16x32_bf16 v[82:85], v[144:147], v[206:209], v[82:85]
	v_mfma_f32_16x16x32_bf16 v[62:65], v[136:139], v[214:217], v[62:65]
	v_mfma_f32_16x16x32_bf16 v[58:61], v[144:147], v[214:217], v[58:61]
	s_setprio 0
	s_setprio 1
	v_mfma_f32_16x16x32_bf16 v[126:129], v[158:161], v[174:177], v[126:129]
	v_mfma_f32_16x16x32_bf16 v[122:125], v[166:169], v[174:177], v[122:125]
	v_mfma_f32_16x16x32_bf16 v[110:113], v[158:161], v[194:197], v[110:113]
	v_mfma_f32_16x16x32_bf16 v[106:109], v[166:169], v[194:197], v[106:109]
	v_mfma_f32_16x16x32_bf16 v[94:97], v[158:161], v[202:205], v[94:97]
	v_mfma_f32_16x16x32_bf16 v[90:93], v[166:169], v[202:205], v[90:93]
	v_mfma_f32_16x16x32_bf16 v[78:81], v[158:161], v[210:213], v[78:81]
	v_mfma_f32_16x16x32_bf16 v[74:77], v[166:169], v[210:213], v[74:77]
	v_mfma_f32_16x16x32_bf16 v[126:129], v[162:165], v[178:181], v[126:129]
	v_mfma_f32_16x16x32_bf16 v[122:125], v[170:173], v[178:181], v[122:125]
	v_mfma_f32_16x16x32_bf16 v[110:113], v[162:165], v[198:201], v[110:113]
	v_mfma_f32_16x16x32_bf16 v[106:109], v[170:173], v[198:201], v[106:109]
	v_mfma_f32_16x16x32_bf16 v[94:97], v[162:165], v[206:209], v[94:97]
	v_mfma_f32_16x16x32_bf16 v[90:93], v[170:173], v[206:209], v[90:93]
	v_mfma_f32_16x16x32_bf16 v[78:81], v[162:165], v[214:217], v[78:81]
	v_mfma_f32_16x16x32_bf16 v[74:77], v[170:173], v[214:217], v[74:77]
	s_setprio 0
	s_barrier
	s_mov_b32 m0, s93
	v_lshl_add_u64 v[148:149], s[18:19], 0, v[152:153]
	ds_read_b128 v[174:177], v192 offset:16384
	ds_read_b128 v[178:181], v192 offset:17408
	ds_read_b128 v[194:197], v192 offset:18432
	ds_read_b128 v[198:201], v192 offset:19456
	ds_read_b128 v[202:205], v192 offset:20480
	ds_read_b128 v[206:209], v192 offset:21504
	ds_read_b128 v[210:213], v192 offset:22528
	ds_read_b128 v[214:217], v192 offset:23552
	global_load_lds_dwordx4 v[148:149], off
	v_lshl_add_u64 v[182:183], v[148:149], 0, s[16:17]
	s_mov_b32 m0, s94
	s_nop 0
	global_load_lds_dwordx4 v[182:183], off
	v_lshl_add_u64 v[182:183], v[148:149], 0, s[26:27]
	s_mov_b32 m0, s95
	s_nop 0
	global_load_lds_dwordx4 v[182:183], off
	v_lshl_add_u64 v[182:183], v[148:149], 0, s[28:29]
	s_mov_b32 m0, s0
	s_nop 0
	global_load_lds_dwordx4 v[182:183], off
	v_lshl_add_u64 v[182:183], s[88:89], 0, v[150:151]
	s_mov_b32 m0, s13
	v_lshl_add_u64 v[218:219], v[182:183], 0, s[30:31]
	global_load_lds_dwordx4 v[182:183], off
	s_mov_b32 m0, s15
	s_nop 0
	global_load_lds_dwordx4 v[218:219], off
	s_waitcnt vmcnt(8)
	s_waitcnt lgkmcnt(0)
	s_waitcnt lgkmcnt(0)
	v_mfma_f32_16x16x32_bf16 v[54:57], v[132:135], v[174:177], v[54:57]
	v_mfma_f32_16x16x32_bf16 v[50:53], v[140:143], v[174:177], v[50:53]
	v_mfma_f32_16x16x32_bf16 v[38:41], v[132:135], v[194:197], v[38:41]
	s_barrier
	s_setprio 1
	v_mfma_f32_16x16x32_bf16 v[34:37], v[140:143], v[194:197], v[34:37]
	v_mfma_f32_16x16x32_bf16 v[22:25], v[132:135], v[202:205], v[22:25]
	v_mfma_f32_16x16x32_bf16 v[18:21], v[140:143], v[202:205], v[18:21]
	v_mfma_f32_16x16x32_bf16 v[6:9], v[132:135], v[210:213], v[6:9]
	v_mfma_f32_16x16x32_bf16 v[2:5], v[140:143], v[210:213], v[2:5]
	v_mfma_f32_16x16x32_bf16 v[54:57], v[136:139], v[178:181], v[54:57]
	v_mfma_f32_16x16x32_bf16 v[50:53], v[144:147], v[178:181], v[50:53]
	v_mfma_f32_16x16x32_bf16 v[38:41], v[136:139], v[198:201], v[38:41]
	v_mfma_f32_16x16x32_bf16 v[34:37], v[144:147], v[198:201], v[34:37]
	v_mfma_f32_16x16x32_bf16 v[22:25], v[136:139], v[206:209], v[22:25]
	v_mfma_f32_16x16x32_bf16 v[18:21], v[144:147], v[206:209], v[18:21]
	v_mfma_f32_16x16x32_bf16 v[6:9], v[136:139], v[214:217], v[6:9]
	v_mfma_f32_16x16x32_bf16 v[2:5], v[144:147], v[214:217], v[2:5]
	s_setprio 0
	s_setprio 1
	v_mfma_f32_16x16x32_bf16 v[70:73], v[158:161], v[174:177], v[70:73]
	v_mfma_f32_16x16x32_bf16 v[66:69], v[166:169], v[174:177], v[66:69]
	v_mfma_f32_16x16x32_bf16 v[46:49], v[158:161], v[194:197], v[46:49]
	v_mfma_f32_16x16x32_bf16 v[42:45], v[166:169], v[194:197], v[42:45]
	v_mfma_f32_16x16x32_bf16 v[30:33], v[158:161], v[202:205], v[30:33]
	v_mfma_f32_16x16x32_bf16 v[26:29], v[166:169], v[202:205], v[26:29]
	v_mfma_f32_16x16x32_bf16 v[14:17], v[158:161], v[210:213], v[14:17]
	v_mfma_f32_16x16x32_bf16 v[10:13], v[166:169], v[210:213], v[10:13]
	v_mfma_f32_16x16x32_bf16 v[70:73], v[162:165], v[178:181], v[70:73]
	v_mfma_f32_16x16x32_bf16 v[66:69], v[170:173], v[178:181], v[66:69]
	v_mfma_f32_16x16x32_bf16 v[46:49], v[162:165], v[198:201], v[46:49]
	v_mfma_f32_16x16x32_bf16 v[42:45], v[170:173], v[198:201], v[42:45]
	v_mfma_f32_16x16x32_bf16 v[30:33], v[162:165], v[206:209], v[30:33]
	v_mfma_f32_16x16x32_bf16 v[26:29], v[170:173], v[206:209], v[26:29]
	v_mfma_f32_16x16x32_bf16 v[14:17], v[162:165], v[214:217], v[14:17]
	v_mfma_f32_16x16x32_bf16 v[10:13], v[170:173], v[214:217], v[10:13]
	s_setprio 0
	s_barrier
	ds_read_b128 v[132:135], v130
	ds_read_b128 v[136:139], v130 offset:1024
	ds_read_b128 v[140:143], v130 offset:2048
	ds_read_b128 v[144:147], v130 offset:3072
	ds_read_b128 v[158:161], v131
	ds_read_b128 v[162:165], v131 offset:1024
	ds_read_b128 v[166:169], v131 offset:2048
	ds_read_b128 v[170:173], v131 offset:3072
	s_mov_b32 m0, s96
	v_lshl_add_u64 v[218:219], v[182:183], 0, s[34:35]
	ds_read_b128 v[174:177], v192 offset:32768
	ds_read_b128 v[178:181], v192 offset:33792
	ds_read_b128 v[194:197], v192 offset:34816
	ds_read_b128 v[198:201], v192 offset:35840
	ds_read_b128 v[202:205], v192 offset:36864
	ds_read_b128 v[206:209], v192 offset:37888
	ds_read_b128 v[210:213], v192 offset:38912
	ds_read_b128 v[214:217], v192 offset:39936
	global_load_lds_dwordx4 v[218:219], off
	v_lshl_add_u64 v[218:219], v[182:183], 0, s[40:41]
	s_mov_b32 m0, s97
	s_nop 0
	global_load_lds_dwordx4 v[218:219], off
	s_waitcnt vmcnt(8)
	s_waitcnt lgkmcnt(0)
	s_waitcnt lgkmcnt(0)
	v_mfma_f32_16x16x32_bf16 v[118:121], v[132:135], v[174:177], v[118:121]
	v_mfma_f32_16x16x32_bf16 v[114:117], v[140:143], v[174:177], v[114:117]
	v_mfma_f32_16x16x32_bf16 v[102:105], v[132:135], v[194:197], v[102:105]
	s_barrier
	s_setprio 1
	v_mfma_f32_16x16x32_bf16 v[98:101], v[140:143], v[194:197], v[98:101]
	v_mfma_f32_16x16x32_bf16 v[86:89], v[132:135], v[202:205], v[86:89]
	v_mfma_f32_16x16x32_bf16 v[82:85], v[140:143], v[202:205], v[82:85]
	v_mfma_f32_16x16x32_bf16 v[62:65], v[132:135], v[210:213], v[62:65]
	v_mfma_f32_16x16x32_bf16 v[58:61], v[140:143], v[210:213], v[58:61]
	v_mfma_f32_16x16x32_bf16 v[118:121], v[136:139], v[178:181], v[118:121]
	v_mfma_f32_16x16x32_bf16 v[114:117], v[144:147], v[178:181], v[114:117]
	v_mfma_f32_16x16x32_bf16 v[102:105], v[136:139], v[198:201], v[102:105]
	v_mfma_f32_16x16x32_bf16 v[98:101], v[144:147], v[198:201], v[98:101]
	v_mfma_f32_16x16x32_bf16 v[86:89], v[136:139], v[206:209], v[86:89]
	v_mfma_f32_16x16x32_bf16 v[82:85], v[144:147], v[206:209], v[82:85]
	v_mfma_f32_16x16x32_bf16 v[62:65], v[136:139], v[214:217], v[62:65]
	v_mfma_f32_16x16x32_bf16 v[58:61], v[144:147], v[214:217], v[58:61]
	s_setprio 0
	s_setprio 1
	v_mfma_f32_16x16x32_bf16 v[126:129], v[158:161], v[174:177], v[126:129]
	v_mfma_f32_16x16x32_bf16 v[122:125], v[166:169], v[174:177], v[122:125]
	v_mfma_f32_16x16x32_bf16 v[110:113], v[158:161], v[194:197], v[110:113]
	v_mfma_f32_16x16x32_bf16 v[106:109], v[166:169], v[194:197], v[106:109]
	v_mfma_f32_16x16x32_bf16 v[94:97], v[158:161], v[202:205], v[94:97]
	v_mfma_f32_16x16x32_bf16 v[90:93], v[166:169], v[202:205], v[90:93]
	v_mfma_f32_16x16x32_bf16 v[78:81], v[158:161], v[210:213], v[78:81]
	v_mfma_f32_16x16x32_bf16 v[74:77], v[166:169], v[210:213], v[74:77]
	v_mfma_f32_16x16x32_bf16 v[126:129], v[162:165], v[178:181], v[126:129]
	v_mfma_f32_16x16x32_bf16 v[122:125], v[170:173], v[178:181], v[122:125]
	v_mfma_f32_16x16x32_bf16 v[110:113], v[162:165], v[198:201], v[110:113]
	v_mfma_f32_16x16x32_bf16 v[106:109], v[170:173], v[198:201], v[106:109]
	v_mfma_f32_16x16x32_bf16 v[94:97], v[162:165], v[206:209], v[94:97]
	v_mfma_f32_16x16x32_bf16 v[90:93], v[170:173], v[206:209], v[90:93]
	v_mfma_f32_16x16x32_bf16 v[78:81], v[162:165], v[214:217], v[78:81]
	v_mfma_f32_16x16x32_bf16 v[74:77], v[170:173], v[214:217], v[74:77]
	s_setprio 0
	s_barrier
	s_mov_b32 m0, s1
	v_lshl_add_u64 v[218:219], v[148:149], 0, s[48:49]
	ds_read_b128 v[174:177], v192 offset:49152
	ds_read_b128 v[178:181], v192 offset:50176
	ds_read_b128 v[194:197], v192 offset:51200
	ds_read_b128 v[198:201], v192 offset:52224
	ds_read_b128 v[202:205], v192 offset:53248
	ds_read_b128 v[206:209], v192 offset:54272
	ds_read_b128 v[210:213], v192 offset:55296
	ds_read_b128 v[214:217], v192 offset:56320
	global_load_lds_dwordx4 v[218:219], off
	v_lshl_add_u64 v[218:219], v[148:149], 0, s[54:55]
	s_mov_b32 m0, s33
	s_nop 0
	global_load_lds_dwordx4 v[218:219], off
	v_lshl_add_u64 v[218:219], v[148:149], 0, s[60:61]
	s_mov_b32 m0, s3
	v_lshl_add_u64 v[148:149], v[148:149], 0, s[62:63]
	global_load_lds_dwordx4 v[218:219], off
	s_mov_b32 m0, s66
	s_nop 0
	global_load_lds_dwordx4 v[148:149], off
	v_lshl_add_u64 v[148:149], v[182:183], 0, s[56:57]
	s_mov_b32 m0, s6
	s_nop 0
	global_load_lds_dwordx4 v[148:149], off
	v_lshl_add_u64 v[148:149], v[182:183], 0, s[58:59]
	s_mov_b32 m0, s7
	s_nop 0
	global_load_lds_dwordx4 v[148:149], off
	s_waitcnt vmcnt(8)
	s_waitcnt lgkmcnt(0)
	s_waitcnt lgkmcnt(0)
	v_mfma_f32_16x16x32_bf16 v[54:57], v[132:135], v[174:177], v[54:57]
	v_mfma_f32_16x16x32_bf16 v[50:53], v[140:143], v[174:177], v[50:53]
	v_mfma_f32_16x16x32_bf16 v[38:41], v[132:135], v[194:197], v[38:41]
	s_barrier
	s_setprio 1
	v_mfma_f32_16x16x32_bf16 v[34:37], v[140:143], v[194:197], v[34:37]
	v_mfma_f32_16x16x32_bf16 v[22:25], v[132:135], v[202:205], v[22:25]
	v_mfma_f32_16x16x32_bf16 v[18:21], v[140:143], v[202:205], v[18:21]
	v_mfma_f32_16x16x32_bf16 v[6:9], v[132:135], v[210:213], v[6:9]
	v_mfma_f32_16x16x32_bf16 v[2:5], v[140:143], v[210:213], v[2:5]
	v_mfma_f32_16x16x32_bf16 v[54:57], v[136:139], v[178:181], v[54:57]
	v_mfma_f32_16x16x32_bf16 v[50:53], v[144:147], v[178:181], v[50:53]
	v_mfma_f32_16x16x32_bf16 v[38:41], v[136:139], v[198:201], v[38:41]
	v_mfma_f32_16x16x32_bf16 v[34:37], v[144:147], v[198:201], v[34:37]
	v_mfma_f32_16x16x32_bf16 v[22:25], v[136:139], v[206:209], v[22:25]
	v_mfma_f32_16x16x32_bf16 v[18:21], v[144:147], v[206:209], v[18:21]
	v_mfma_f32_16x16x32_bf16 v[6:9], v[136:139], v[214:217], v[6:9]
	v_mfma_f32_16x16x32_bf16 v[2:5], v[144:147], v[214:217], v[2:5]
	s_setprio 0
	s_setprio 1
	v_mfma_f32_16x16x32_bf16 v[70:73], v[158:161], v[174:177], v[70:73]
	v_mfma_f32_16x16x32_bf16 v[66:69], v[166:169], v[174:177], v[66:69]
	v_mfma_f32_16x16x32_bf16 v[46:49], v[158:161], v[194:197], v[46:49]
	v_mfma_f32_16x16x32_bf16 v[42:45], v[166:169], v[194:197], v[42:45]
	v_mfma_f32_16x16x32_bf16 v[30:33], v[158:161], v[202:205], v[30:33]
	v_mfma_f32_16x16x32_bf16 v[26:29], v[166:169], v[202:205], v[26:29]
	v_mfma_f32_16x16x32_bf16 v[14:17], v[158:161], v[210:213], v[14:17]
	v_mfma_f32_16x16x32_bf16 v[10:13], v[166:169], v[210:213], v[10:13]
	v_mfma_f32_16x16x32_bf16 v[70:73], v[162:165], v[178:181], v[70:73]
	v_mfma_f32_16x16x32_bf16 v[66:69], v[170:173], v[178:181], v[66:69]
	v_mfma_f32_16x16x32_bf16 v[46:49], v[162:165], v[198:201], v[46:49]
	v_mfma_f32_16x16x32_bf16 v[42:45], v[170:173], v[198:201], v[42:45]
	v_mfma_f32_16x16x32_bf16 v[30:33], v[162:165], v[206:209], v[30:33]
	v_mfma_f32_16x16x32_bf16 v[26:29], v[170:173], v[206:209], v[26:29]
	v_mfma_f32_16x16x32_bf16 v[14:17], v[162:165], v[214:217], v[14:17]
	v_mfma_f32_16x16x32_bf16 v[10:13], v[170:173], v[214:217], v[10:13]
	s_setprio 0
	s_barrier
	s_add_i32 s88, s67, 2
	s_add_u32 s36, s36, 0x100
	s_addc_u32 s37, s37, 0
	s_add_u32 s50, s50, 0x440000
	s_addc_u32 s51, s51, 0
	s_cmp_ge_i32 s67, s76
	s_cbranch_scc1 .LBB0_1338
	s_mov_b32 s67, s88
	s_branch .LBB0_1334

.LBB0_1464:
	s_ashr_i32 s75, s74, 31
	s_lshl_b64 s[18:19], s[74:75], 19
	v_readlane_b32 s20, v255, 0
	v_readlane_b32 s21, v255, 1
	s_add_u32 s11, s20, s18
	s_addc_u32 s18, s21, s19
	s_add_u32 s80, s11, s6
	s_addc_u32 s81, s18, s7
	s_and_b64 s[18:19], s[78:79], exec
	s_cselect_b32 s11, s81, s39
	s_cselect_b32 s44, s80, s38
	s_ashr_i32 s73, s72, 31
	s_lshl_b64 s[18:19], s[72:73], 19
	v_readlane_b32 s20, v255, 23
	s_waitcnt lgkmcnt(0)
	ds_read_b128 v[2:5], v218
	ds_read_b128 v[6:9], v218 offset:1024
	ds_read_b128 v[10:13], v218 offset:2048
	ds_read_b128 v[14:17], v218 offset:3072
	ds_read_b128 v[18:21], v219
	ds_read_b128 v[22:25], v219 offset:1024
	ds_read_b128 v[26:29], v219 offset:2048
	ds_read_b128 v[30:33], v219 offset:3072
	v_readlane_b32 s21, v255, 24
	s_add_u32 s18, s20, s18
	s_addc_u32 s19, s21, s19
	s_add_u32 s82, s18, s6
	s_addc_u32 s83, s19, s7
	s_and_b64 s[6:7], s[78:79], exec
	s_cselect_b32 s50, s83, s29
	s_cselect_b32 s51, s82, s28
	s_add_u32 s6, s38, 0x100
	s_addc_u32 s7, s39, 0
	s_add_u32 s18, s28, 0x100
	s_addc_u32 s19, s29, 0
	s_cmp_eq_u32 s76, 2
	s_cselect_b32 s7, s11, s7
	s_cselect_b32 s6, s44, s6
	s_cselect_b32 s19, s50, s19
	s_cselect_b32 s18, s51, s18
	v_lshl_add_u64 v[66:67], s[38:39], 0, v[188:189]
	s_add_i32 s73, s25, 0xc000
	v_lshl_add_u64 v[68:69], v[66:67], 0, s[54:55]
	s_mov_b32 m0, s73
	s_add_i32 s75, s25, 0xe000
	ds_read_b128 v[34:37], v220
	ds_read_b128 v[38:41], v220 offset:1024
	ds_read_b128 v[42:45], v220 offset:2048
	ds_read_b128 v[46:49], v220 offset:3072
	ds_read_b128 v[50:53], v220 offset:4096
	ds_read_b128 v[54:57], v220 offset:5120
	ds_read_b128 v[58:61], v220 offset:6144
	ds_read_b128 v[62:65], v220 offset:7168
	global_load_lds_dwordx4 v[68:69], off
	v_lshl_add_u64 v[66:67], v[66:67], 0, s[56:57]
	s_mov_b32 m0, s75
	s_nop 0
	global_load_lds_dwordx4 v[66:67], off
	s_waitcnt vmcnt(8)
	s_waitcnt lgkmcnt(0)
	s_waitcnt lgkmcnt(0)
	v_mfma_f32_16x16x32_bf16 v[90:93], v[2:5], v[58:61], 0
	v_mfma_f32_16x16x32_bf16 v[66:69], v[2:5], v[34:37], 0
	v_mfma_f32_16x16x32_bf16 v[70:73], v[10:13], v[34:37], 0
	s_barrier
	s_setprio 1
	v_mfma_f32_16x16x32_bf16 v[74:77], v[2:5], v[42:45], 0
	v_mfma_f32_16x16x32_bf16 v[78:81], v[10:13], v[42:45], 0
	v_mfma_f32_16x16x32_bf16 v[82:85], v[2:5], v[50:53], 0
	v_mfma_f32_16x16x32_bf16 v[86:89], v[10:13], v[50:53], 0
	v_mfma_f32_16x16x32_bf16 v[98:101], v[6:9], v[62:65], v[90:93]
	v_mfma_f32_16x16x32_bf16 v[90:93], v[10:13], v[58:61], 0
	v_mfma_f32_16x16x32_bf16 v[66:69], v[6:9], v[38:41], v[66:69]
	v_mfma_f32_16x16x32_bf16 v[70:73], v[14:17], v[38:41], v[70:73]
	v_mfma_f32_16x16x32_bf16 v[74:77], v[6:9], v[46:49], v[74:77]
	v_mfma_f32_16x16x32_bf16 v[78:81], v[14:17], v[46:49], v[78:81]
	v_mfma_f32_16x16x32_bf16 v[82:85], v[6:9], v[54:57], v[82:85]
	v_mfma_f32_16x16x32_bf16 v[86:89], v[14:17], v[54:57], v[86:89]
	v_mfma_f32_16x16x32_bf16 v[102:105], v[14:17], v[62:65], v[90:93]
	s_setprio 0
	s_setprio 1
	v_mfma_f32_16x16x32_bf16 v[90:93], v[18:21], v[34:37], 0
	v_mfma_f32_16x16x32_bf16 v[34:37], v[26:29], v[34:37], 0
	v_mfma_f32_16x16x32_bf16 v[114:117], v[22:25], v[38:41], v[90:93]
	v_mfma_f32_16x16x32_bf16 v[34:37], v[30:33], v[38:41], v[34:37]
	v_mfma_f32_16x16x32_bf16 v[38:41], v[18:21], v[42:45], 0
	v_mfma_f32_16x16x32_bf16 v[42:45], v[26:29], v[42:45], 0
	v_mfma_f32_16x16x32_bf16 v[38:41], v[22:25], v[46:49], v[38:41]
	v_mfma_f32_16x16x32_bf16 v[42:45], v[30:33], v[46:49], v[42:45]
	v_mfma_f32_16x16x32_bf16 v[46:49], v[18:21], v[50:53], 0
	v_mfma_f32_16x16x32_bf16 v[50:53], v[26:29], v[50:53], 0
	v_mfma_f32_16x16x32_bf16 v[46:49], v[22:25], v[54:57], v[46:49]
	v_mfma_f32_16x16x32_bf16 v[50:53], v[30:33], v[54:57], v[50:53]
	v_mfma_f32_16x16x32_bf16 v[54:57], v[18:21], v[58:61], 0
	v_mfma_f32_16x16x32_bf16 v[58:61], v[26:29], v[58:61], 0
	v_mfma_f32_16x16x32_bf16 v[54:57], v[22:25], v[62:65], v[54:57]
	v_mfma_f32_16x16x32_bf16 v[58:61], v[30:33], v[62:65], v[58:61]
	s_setprio 0
	s_barrier
	s_add_i32 s84, s65, s77
	v_lshl_add_u64 v[184:185], s[18:19], 0, v[190:191]
	s_mov_b32 m0, s84
	s_add_i32 s85, s84, 0x2000
	ds_read_b128 v[62:65], v220 offset:16384
	ds_read_b128 v[90:93], v220 offset:17408
	ds_read_b128 v[94:97], v220 offset:18432
	ds_read_b128 v[106:109], v220 offset:19456
	ds_read_b128 v[110:113], v220 offset:20480
	ds_read_b128 v[118:121], v220 offset:21504
	ds_read_b128 v[122:125], v220 offset:22528
	ds_read_b128 v[126:129], v220 offset:23552
	global_load_lds_dwordx4 v[184:185], off
	v_lshl_add_u64 v[130:131], v[184:185], 0, s[26:27]
	s_mov_b32 m0, s85
	s_add_i32 s86, s64, s77
	global_load_lds_dwordx4 v[130:131], off
	v_lshl_add_u64 v[130:131], v[184:185], 0, s[30:31]
	s_mov_b32 m0, s86
	s_add_i32 s87, s86, 0x2000
	global_load_lds_dwordx4 v[130:131], off
	v_lshl_add_u64 v[130:131], v[184:185], 0, s[34:35]
	s_mov_b32 m0, s87
	v_lshl_add_u64 v[250:251], s[6:7], 0, v[188:189]
	global_load_lds_dwordx4 v[130:131], off
	s_mov_b32 m0, s25
	v_lshl_add_u64 v[130:131], v[250:251], 0, s[26:27]
	global_load_lds_dwordx4 v[250:251], off
	s_mov_b32 m0, s92
	s_nop 0
	global_load_lds_dwordx4 v[130:131], off
	s_waitcnt vmcnt(8)
	s_waitcnt lgkmcnt(0)
	s_waitcnt lgkmcnt(0)
	v_mfma_f32_16x16x32_bf16 v[130:133], v[2:5], v[62:65], 0
	v_mfma_f32_16x16x32_bf16 v[140:143], v[2:5], v[94:97], 0
	v_mfma_f32_16x16x32_bf16 v[148:151], v[2:5], v[110:113], 0
	s_barrier
	s_setprio 1
	v_mfma_f32_16x16x32_bf16 v[2:5], v[2:5], v[122:125], 0
	v_mfma_f32_16x16x32_bf16 v[132:135], v[6:9], v[90:93], v[130:133]
	v_mfma_f32_16x16x32_bf16 v[140:143], v[6:9], v[106:109], v[140:143]
	v_mfma_f32_16x16x32_bf16 v[148:151], v[6:9], v[118:121], v[148:151]
	v_mfma_f32_16x16x32_bf16 v[2:5], v[6:9], v[126:129], v[2:5]
	v_mfma_f32_16x16x32_bf16 v[6:9], v[10:13], v[122:125], 0
	v_mfma_f32_16x16x32_bf16 v[136:139], v[10:13], v[62:65], 0
	v_mfma_f32_16x16x32_bf16 v[144:147], v[10:13], v[94:97], 0
	v_mfma_f32_16x16x32_bf16 v[152:155], v[10:13], v[110:113], 0
	v_mfma_f32_16x16x32_bf16 v[6:9], v[14:17], v[126:129], v[6:9]
	v_mfma_f32_16x16x32_bf16 v[136:139], v[14:17], v[90:93], v[136:139]
	v_mfma_f32_16x16x32_bf16 v[144:147], v[14:17], v[106:109], v[144:147]
	v_mfma_f32_16x16x32_bf16 v[152:155], v[14:17], v[118:121], v[152:155]
	s_setprio 0
	s_setprio 1
	v_mfma_f32_16x16x32_bf16 v[10:13], v[18:21], v[62:65], 0
	v_mfma_f32_16x16x32_bf16 v[156:159], v[22:25], v[90:93], v[10:13]
	v_mfma_f32_16x16x32_bf16 v[10:13], v[26:29], v[62:65], 0
	v_mfma_f32_16x16x32_bf16 v[160:163], v[30:33], v[90:93], v[10:13]
	v_mfma_f32_16x16x32_bf16 v[10:13], v[18:21], v[94:97], 0
	v_mfma_f32_16x16x32_bf16 v[164:167], v[22:25], v[106:109], v[10:13]
	v_mfma_f32_16x16x32_bf16 v[10:13], v[26:29], v[94:97], 0
	v_mfma_f32_16x16x32_bf16 v[168:171], v[30:33], v[106:109], v[10:13]
	v_mfma_f32_16x16x32_bf16 v[10:13], v[18:21], v[110:113], 0
	v_mfma_f32_16x16x32_bf16 v[172:175], v[22:25], v[118:121], v[10:13]
	v_mfma_f32_16x16x32_bf16 v[10:13], v[26:29], v[110:113], 0
	v_mfma_f32_16x16x32_bf16 v[176:179], v[30:33], v[118:121], v[10:13]
	v_mfma_f32_16x16x32_bf16 v[10:13], v[18:21], v[122:125], 0
	v_mfma_f32_16x16x32_bf16 v[180:183], v[22:25], v[126:129], v[10:13]
	v_mfma_f32_16x16x32_bf16 v[10:13], v[26:29], v[122:125], 0
	v_mfma_f32_16x16x32_bf16 v[196:199], v[30:33], v[126:129], v[10:13]
	s_setprio 0
	s_barrier
	s_add_i32 s33, 0, 0x18000
	s_add_i32 s89, 0, 0x1c000
	v_add_u32_e32 v130, s33, v215
	v_add_u32_e32 v131, s89, v215
	s_nop 0
	ds_read_b128 v[10:13], v130
	ds_read_b128 v[14:17], v130 offset:1024
	ds_read_b128 v[18:21], v130 offset:2048
	ds_read_b128 v[22:25], v130 offset:3072
	ds_read_b128 v[200:203], v131
	ds_read_b128 v[204:207], v131 offset:1024
	ds_read_b128 v[208:211], v131 offset:2048
	ds_read_b128 v[222:225], v131 offset:3072
	s_mov_b32 m0, s93
	v_lshl_add_u64 v[90:91], v[250:251], 0, s[30:31]
	ds_read_b128 v[26:29], v220 offset:32768
	ds_read_b128 v[30:33], v220 offset:33792
	ds_read_b128 v[62:65], v220 offset:34816
	ds_read_b128 v[226:229], v220 offset:35840
	ds_read_b128 v[230:233], v220 offset:36864
	ds_read_b128 v[234:237], v220 offset:37888
	ds_read_b128 v[238:241], v220 offset:38912
	ds_read_b128 v[242:245], v220 offset:39936
	global_load_lds_dwordx4 v[90:91], off
	v_lshl_add_u64 v[90:91], v[250:251], 0, s[34:35]
	s_mov_b32 m0, s94
	s_nop 0
	global_load_lds_dwordx4 v[90:91], off
	s_waitcnt vmcnt(8)
	s_waitcnt lgkmcnt(0)
	s_waitcnt lgkmcnt(0)
	v_mfma_f32_16x16x32_bf16 v[66:69], v[10:13], v[26:29], v[66:69]
	v_mfma_f32_16x16x32_bf16 v[126:129], v[14:17], v[30:33], v[66:69]
	v_mfma_f32_16x16x32_bf16 v[66:69], v[18:21], v[26:29], v[70:73]
	s_barrier
	s_setprio 1
	v_mfma_f32_16x16x32_bf16 v[122:125], v[22:25], v[30:33], v[66:69]
	v_mfma_f32_16x16x32_bf16 v[66:69], v[10:13], v[62:65], v[74:77]
	v_mfma_f32_16x16x32_bf16 v[110:113], v[14:17], v[226:229], v[66:69]
	v_mfma_f32_16x16x32_bf16 v[66:69], v[18:21], v[62:65], v[78:81]
	v_mfma_f32_16x16x32_bf16 v[106:109], v[22:25], v[226:229], v[66:69]
	v_mfma_f32_16x16x32_bf16 v[66:69], v[10:13], v[230:233], v[82:85]
	v_mfma_f32_16x16x32_bf16 v[94:97], v[14:17], v[234:237], v[66:69]
	v_mfma_f32_16x16x32_bf16 v[66:69], v[18:21], v[230:233], v[86:89]
	v_mfma_f32_16x16x32_bf16 v[90:93], v[22:25], v[234:237], v[66:69]
	v_mfma_f32_16x16x32_bf16 v[66:69], v[10:13], v[238:241], v[98:101]
	v_mfma_f32_16x16x32_bf16 v[78:81], v[14:17], v[242:245], v[66:69]
	v_mfma_f32_16x16x32_bf16 v[66:69], v[18:21], v[238:241], v[102:105]
	v_mfma_f32_16x16x32_bf16 v[74:77], v[22:25], v[242:245], v[66:69]
	s_setprio 0
	s_setprio 1
	v_mfma_f32_16x16x32_bf16 v[66:69], v[200:203], v[26:29], v[114:117]
	v_mfma_f32_16x16x32_bf16 v[26:29], v[208:211], v[26:29], v[34:37]
	v_mfma_f32_16x16x32_bf16 v[114:117], v[222:225], v[30:33], v[26:29]
	v_mfma_f32_16x16x32_bf16 v[26:29], v[200:203], v[62:65], v[38:41]
	v_mfma_f32_16x16x32_bf16 v[102:105], v[204:207], v[226:229], v[26:29]
	v_mfma_f32_16x16x32_bf16 v[26:29], v[208:211], v[62:65], v[42:45]
	v_mfma_f32_16x16x32_bf16 v[98:101], v[222:225], v[226:229], v[26:29]
	v_mfma_f32_16x16x32_bf16 v[26:29], v[200:203], v[230:233], v[46:49]
	v_mfma_f32_16x16x32_bf16 v[86:89], v[204:207], v[234:237], v[26:29]
	v_mfma_f32_16x16x32_bf16 v[26:29], v[208:211], v[230:233], v[50:53]
	v_mfma_f32_16x16x32_bf16 v[82:85], v[222:225], v[234:237], v[26:29]
	v_mfma_f32_16x16x32_bf16 v[26:29], v[200:203], v[238:241], v[54:57]
	v_mfma_f32_16x16x32_bf16 v[70:73], v[204:207], v[242:245], v[26:29]
	v_mfma_f32_16x16x32_bf16 v[26:29], v[208:211], v[238:241], v[58:61]
	v_mfma_f32_16x16x32_bf16 v[118:121], v[204:207], v[30:33], v[66:69]
	v_mfma_f32_16x16x32_bf16 v[66:69], v[222:225], v[242:245], v[26:29]
	s_setprio 0
	s_barrier
	s_add_i32 s33, s33, s77
	s_nop 2
	v_lshl_add_u64 v[26:27], v[184:185], 0, s[46:47]
	s_mov_b32 m0, s33
	s_add_i32 s88, s33, 0x2000
	ds_read_b128 v[34:37], v220 offset:49152
	ds_read_b128 v[38:41], v220 offset:50176
	ds_read_b128 v[226:229], v220 offset:51200
	ds_read_b128 v[230:233], v220 offset:52224
	ds_read_b128 v[234:237], v220 offset:53248
	ds_read_b128 v[238:241], v220 offset:54272
	ds_read_b128 v[242:245], v220 offset:55296
	ds_read_b128 v[246:249], v220 offset:56320
	global_load_lds_dwordx4 v[26:27], off
	v_lshl_add_u64 v[26:27], v[184:185], 0, s[48:49]
	s_mov_b32 m0, s88
	s_add_i32 s89, s89, s77
	global_load_lds_dwordx4 v[26:27], off
	v_lshl_add_u64 v[26:27], v[184:185], 0, s[54:55]
	s_mov_b32 m0, s89
	s_add_i32 s90, s89, 0x2000
	global_load_lds_dwordx4 v[26:27], off
	v_lshl_add_u64 v[26:27], v[184:185], 0, s[56:57]
	s_mov_b32 m0, s90
	s_nop 0
	global_load_lds_dwordx4 v[26:27], off
	v_lshl_add_u64 v[26:27], v[250:251], 0, s[46:47]
	s_mov_b32 m0, s13
	s_nop 0
	global_load_lds_dwordx4 v[26:27], off
	v_lshl_add_u64 v[26:27], v[250:251], 0, s[48:49]
	s_mov_b32 m0, s14
	s_nop 0
	global_load_lds_dwordx4 v[26:27], off
	s_waitcnt vmcnt(8)
	s_waitcnt lgkmcnt(0)
	s_waitcnt lgkmcnt(0)
	v_mfma_f32_16x16x32_bf16 v[26:29], v[10:13], v[34:37], v[132:135]
	v_mfma_f32_16x16x32_bf16 v[62:65], v[14:17], v[38:41], v[26:29]
	v_mfma_f32_16x16x32_bf16 v[26:29], v[18:21], v[34:37], v[136:139]
	s_barrier
	s_setprio 1
	v_mfma_f32_16x16x32_bf16 v[58:61], v[22:25], v[38:41], v[26:29]
	v_mfma_f32_16x16x32_bf16 v[26:29], v[10:13], v[226:229], v[140:143]
	v_mfma_f32_16x16x32_bf16 v[46:49], v[14:17], v[230:233], v[26:29]
	v_mfma_f32_16x16x32_bf16 v[26:29], v[18:21], v[226:229], v[144:147]
	v_mfma_f32_16x16x32_bf16 v[42:45], v[22:25], v[230:233], v[26:29]
	v_mfma_f32_16x16x32_bf16 v[26:29], v[10:13], v[234:237], v[148:151]
	v_mfma_f32_16x16x32_bf16 v[2:5], v[10:13], v[242:245], v[2:5]
	v_mfma_f32_16x16x32_bf16 v[30:33], v[14:17], v[238:241], v[26:29]
	v_mfma_f32_16x16x32_bf16 v[26:29], v[18:21], v[234:237], v[152:155]
	v_mfma_f32_16x16x32_bf16 v[14:17], v[14:17], v[246:249], v[2:5]
	v_mfma_f32_16x16x32_bf16 v[2:5], v[18:21], v[242:245], v[6:9]
	v_mfma_f32_16x16x32_bf16 v[26:29], v[22:25], v[238:241], v[26:29]
	v_mfma_f32_16x16x32_bf16 v[10:13], v[22:25], v[246:249], v[2:5]
	s_setprio 0
	s_setprio 1
	v_mfma_f32_16x16x32_bf16 v[2:5], v[200:203], v[34:37], v[156:159]
	v_mfma_f32_16x16x32_bf16 v[54:57], v[204:207], v[38:41], v[2:5]
	v_mfma_f32_16x16x32_bf16 v[2:5], v[208:211], v[34:37], v[160:163]
	v_mfma_f32_16x16x32_bf16 v[50:53], v[222:225], v[38:41], v[2:5]
	v_mfma_f32_16x16x32_bf16 v[2:5], v[200:203], v[226:229], v[164:167]
	v_mfma_f32_16x16x32_bf16 v[38:41], v[204:207], v[230:233], v[2:5]
	v_mfma_f32_16x16x32_bf16 v[2:5], v[208:211], v[226:229], v[168:171]
	v_mfma_f32_16x16x32_bf16 v[34:37], v[222:225], v[230:233], v[2:5]
	v_mfma_f32_16x16x32_bf16 v[2:5], v[200:203], v[234:237], v[172:175]
	v_mfma_f32_16x16x32_bf16 v[22:25], v[204:207], v[238:241], v[2:5]
	v_mfma_f32_16x16x32_bf16 v[2:5], v[208:211], v[234:237], v[176:179]
	v_mfma_f32_16x16x32_bf16 v[18:21], v[222:225], v[238:241], v[2:5]
	v_mfma_f32_16x16x32_bf16 v[2:5], v[200:203], v[242:245], v[180:183]
	v_mfma_f32_16x16x32_bf16 v[6:9], v[204:207], v[246:249], v[2:5]
	v_mfma_f32_16x16x32_bf16 v[2:5], v[208:211], v[242:245], v[196:199]
	v_mfma_f32_16x16x32_bf16 v[2:5], v[222:225], v[246:249], v[2:5]
	s_setprio 0
	s_barrier
	s_cmp_lt_i32 s76, 3
	s_cbranch_scc1 .LBB0_1467
	s_add_u32 s6, s38, 0x40180
	s_addc_u32 s7, s39, 0
	s_add_u32 s36, s28, 0x200
	s_addc_u32 s37, s29, 0
	s_mov_b32 s91, 4
.LBB0_1466:
	ds_read_b128 v[132:135], v218
	ds_read_b128 v[136:139], v218 offset:1024
	ds_read_b128 v[140:143], v218 offset:2048
	ds_read_b128 v[144:147], v218 offset:3072
	ds_read_b128 v[148:151], v219
	ds_read_b128 v[152:155], v219 offset:1024
	ds_read_b128 v[156:159], v219 offset:2048
	ds_read_b128 v[160:163], v219 offset:3072
	s_add_u32 s18, s6, 0xfffc0080
	s_addc_u32 s19, s7, -1
	s_cmp_eq_u32 s76, s91
	s_cselect_b32 s19, s11, s19
	s_cselect_b32 s18, s44, s18
	s_cselect_b32 s21, s50, s37
	s_cselect_b32 s20, s51, s36
	s_mov_b32 m0, s73
	v_lshl_add_u64 v[184:185], s[6:7], 0, v[192:193]
	ds_read_b128 v[164:167], v220
	ds_read_b128 v[168:171], v220 offset:1024
	ds_read_b128 v[172:175], v220 offset:2048
	ds_read_b128 v[176:179], v220 offset:3072
	ds_read_b128 v[180:183], v220 offset:4096
	ds_read_b128 v[196:199], v220 offset:5120
	ds_read_b128 v[200:203], v220 offset:6144
	ds_read_b128 v[204:207], v220 offset:7168
	global_load_lds_dwordx4 v[184:185], off
	v_lshl_add_u64 v[184:185], v[184:185], 0, s[26:27]
	s_mov_b32 m0, s75
	s_nop 0
	global_load_lds_dwordx4 v[184:185], off
	s_waitcnt vmcnt(8)
	s_waitcnt lgkmcnt(0)
	s_waitcnt lgkmcnt(0)
	v_mfma_f32_16x16x32_bf16 v[126:129], v[132:135], v[164:167], v[126:129]
	v_mfma_f32_16x16x32_bf16 v[122:125], v[140:143], v[164:167], v[122:125]
	v_mfma_f32_16x16x32_bf16 v[110:113], v[132:135], v[172:175], v[110:113]
	s_barrier
	s_setprio 1
	v_mfma_f32_16x16x32_bf16 v[106:109], v[140:143], v[172:175], v[106:109]
	v_mfma_f32_16x16x32_bf16 v[94:97], v[132:135], v[180:183], v[94:97]
	v_mfma_f32_16x16x32_bf16 v[90:93], v[140:143], v[180:183], v[90:93]
	v_mfma_f32_16x16x32_bf16 v[78:81], v[132:135], v[200:203], v[78:81]
	v_mfma_f32_16x16x32_bf16 v[74:77], v[140:143], v[200:203], v[74:77]
	v_mfma_f32_16x16x32_bf16 v[126:129], v[136:139], v[168:171], v[126:129]
	v_mfma_f32_16x16x32_bf16 v[122:125], v[144:147], v[168:171], v[122:125]
	v_mfma_f32_16x16x32_bf16 v[110:113], v[136:139], v[176:179], v[110:113]
	v_mfma_f32_16x16x32_bf16 v[106:109], v[144:147], v[176:179], v[106:109]
	v_mfma_f32_16x16x32_bf16 v[94:97], v[136:139], v[196:199], v[94:97]
	v_mfma_f32_16x16x32_bf16 v[90:93], v[144:147], v[196:199], v[90:93]
	v_mfma_f32_16x16x32_bf16 v[78:81], v[136:139], v[204:207], v[78:81]
	v_mfma_f32_16x16x32_bf16 v[74:77], v[144:147], v[204:207], v[74:77]
	s_setprio 0
	s_setprio 1
	v_mfma_f32_16x16x32_bf16 v[118:121], v[148:151], v[164:167], v[118:121]
	v_mfma_f32_16x16x32_bf16 v[114:117], v[156:159], v[164:167], v[114:117]
	v_mfma_f32_16x16x32_bf16 v[102:105], v[148:151], v[172:175], v[102:105]
	v_mfma_f32_16x16x32_bf16 v[98:101], v[156:159], v[172:175], v[98:101]
	v_mfma_f32_16x16x32_bf16 v[86:89], v[148:151], v[180:183], v[86:89]
	v_mfma_f32_16x16x32_bf16 v[82:85], v[156:159], v[180:183], v[82:85]
	v_mfma_f32_16x16x32_bf16 v[70:73], v[148:151], v[200:203], v[70:73]
	v_mfma_f32_16x16x32_bf16 v[66:69], v[156:159], v[200:203], v[66:69]
	v_mfma_f32_16x16x32_bf16 v[118:121], v[152:155], v[168:171], v[118:121]
	v_mfma_f32_16x16x32_bf16 v[114:117], v[160:163], v[168:171], v[114:117]
	v_mfma_f32_16x16x32_bf16 v[102:105], v[152:155], v[176:179], v[102:105]
	v_mfma_f32_16x16x32_bf16 v[98:101], v[160:163], v[176:179], v[98:101]
	v_mfma_f32_16x16x32_bf16 v[86:89], v[152:155], v[196:199], v[86:89]
	v_mfma_f32_16x16x32_bf16 v[82:85], v[160:163], v[196:199], v[82:85]
	v_mfma_f32_16x16x32_bf16 v[70:73], v[152:155], v[204:207], v[70:73]
	v_mfma_f32_16x16x32_bf16 v[66:69], v[160:163], v[204:207], v[66:69]
	s_setprio 0
	s_barrier
	s_mov_b32 m0, s84
	v_lshl_add_u64 v[184:185], s[20:21], 0, v[190:191]
	ds_read_b128 v[164:167], v220 offset:16384
	ds_read_b128 v[168:171], v220 offset:17408
	ds_read_b128 v[172:175], v220 offset:18432
	ds_read_b128 v[176:179], v220 offset:19456
	ds_read_b128 v[180:183], v220 offset:20480
	ds_read_b128 v[196:199], v220 offset:21504
	ds_read_b128 v[200:203], v220 offset:22528
	ds_read_b128 v[204:207], v220 offset:23552
	global_load_lds_dwordx4 v[184:185], off
	v_lshl_add_u64 v[208:209], v[184:185], 0, s[26:27]
	s_mov_b32 m0, s85
	s_nop 0
	global_load_lds_dwordx4 v[208:209], off
	v_lshl_add_u64 v[208:209], v[184:185], 0, s[30:31]
	s_mov_b32 m0, s86
	s_nop 0
	global_load_lds_dwordx4 v[208:209], off
	v_lshl_add_u64 v[208:209], v[184:185], 0, s[34:35]
	s_mov_b32 m0, s87
	s_nop 0
	global_load_lds_dwordx4 v[208:209], off
	v_lshl_add_u64 v[208:209], s[18:19], 0, v[188:189]
	s_mov_b32 m0, s25
	v_lshl_add_u64 v[210:211], v[208:209], 0, s[26:27]
	global_load_lds_dwordx4 v[208:209], off
	s_mov_b32 m0, s92
	s_nop 0
	global_load_lds_dwordx4 v[210:211], off
	s_waitcnt vmcnt(8)
	s_waitcnt lgkmcnt(0)
	s_waitcnt lgkmcnt(0)
	v_mfma_f32_16x16x32_bf16 v[62:65], v[132:135], v[164:167], v[62:65]
	v_mfma_f32_16x16x32_bf16 v[58:61], v[140:143], v[164:167], v[58:61]
	v_mfma_f32_16x16x32_bf16 v[46:49], v[132:135], v[172:175], v[46:49]
	s_barrier
	s_setprio 1
	v_mfma_f32_16x16x32_bf16 v[42:45], v[140:143], v[172:175], v[42:45]
	v_mfma_f32_16x16x32_bf16 v[30:33], v[132:135], v[180:183], v[30:33]
	v_mfma_f32_16x16x32_bf16 v[26:29], v[140:143], v[180:183], v[26:29]
	v_mfma_f32_16x16x32_bf16 v[14:17], v[132:135], v[200:203], v[14:17]
	v_mfma_f32_16x16x32_bf16 v[10:13], v[140:143], v[200:203], v[10:13]
	v_mfma_f32_16x16x32_bf16 v[62:65], v[136:139], v[168:171], v[62:65]
	v_mfma_f32_16x16x32_bf16 v[58:61], v[144:147], v[168:171], v[58:61]
	v_mfma_f32_16x16x32_bf16 v[46:49], v[136:139], v[176:179], v[46:49]
	v_mfma_f32_16x16x32_bf16 v[42:45], v[144:147], v[176:179], v[42:45]
	v_mfma_f32_16x16x32_bf16 v[30:33], v[136:139], v[196:199], v[30:33]
	v_mfma_f32_16x16x32_bf16 v[26:29], v[144:147], v[196:199], v[26:29]
	v_mfma_f32_16x16x32_bf16 v[14:17], v[136:139], v[204:207], v[14:17]
	v_mfma_f32_16x16x32_bf16 v[10:13], v[144:147], v[204:207], v[10:13]
	s_setprio 0
	s_setprio 1
	v_mfma_f32_16x16x32_bf16 v[54:57], v[148:151], v[164:167], v[54:57]
	v_mfma_f32_16x16x32_bf16 v[50:53], v[156:159], v[164:167], v[50:53]
	v_mfma_f32_16x16x32_bf16 v[38:41], v[148:151], v[172:175], v[38:41]
	v_mfma_f32_16x16x32_bf16 v[34:37], v[156:159], v[172:175], v[34:37]
	v_mfma_f32_16x16x32_bf16 v[22:25], v[148:151], v[180:183], v[22:25]
	v_mfma_f32_16x16x32_bf16 v[18:21], v[156:159], v[180:183], v[18:21]
	v_mfma_f32_16x16x32_bf16 v[6:9], v[148:151], v[200:203], v[6:9]
	v_mfma_f32_16x16x32_bf16 v[2:5], v[156:159], v[200:203], v[2:5]
	v_mfma_f32_16x16x32_bf16 v[54:57], v[152:155], v[168:171], v[54:57]
	v_mfma_f32_16x16x32_bf16 v[50:53], v[160:163], v[168:171], v[50:53]
	v_mfma_f32_16x16x32_bf16 v[38:41], v[152:155], v[176:179], v[38:41]
	v_mfma_f32_16x16x32_bf16 v[34:37], v[160:163], v[176:179], v[34:37]
	v_mfma_f32_16x16x32_bf16 v[22:25], v[152:155], v[196:199], v[22:25]
	v_mfma_f32_16x16x32_bf16 v[18:21], v[160:163], v[196:199], v[18:21]
	v_mfma_f32_16x16x32_bf16 v[6:9], v[152:155], v[204:207], v[6:9]
	v_mfma_f32_16x16x32_bf16 v[2:5], v[160:163], v[204:207], v[2:5]
	s_setprio 0
	s_barrier
	ds_read_b128 v[132:135], v130
	ds_read_b128 v[136:139], v130 offset:1024
	ds_read_b128 v[140:143], v130 offset:2048
	ds_read_b128 v[144:147], v130 offset:3072
	ds_read_b128 v[148:151], v131
	ds_read_b128 v[152:155], v131 offset:1024
	ds_read_b128 v[156:159], v131 offset:2048
	ds_read_b128 v[160:163], v131 offset:3072
	s_mov_b32 m0, s93
	v_lshl_add_u64 v[210:211], v[208:209], 0, s[30:31]
	ds_read_b128 v[164:167], v220 offset:32768
	ds_read_b128 v[168:171], v220 offset:33792
	ds_read_b128 v[172:175], v220 offset:34816
	ds_read_b128 v[176:179], v220 offset:35840
	ds_read_b128 v[180:183], v220 offset:36864
	ds_read_b128 v[196:199], v220 offset:37888
	ds_read_b128 v[200:203], v220 offset:38912
	ds_read_b128 v[204:207], v220 offset:39936
	global_load_lds_dwordx4 v[210:211], off
	v_lshl_add_u64 v[210:211], v[208:209], 0, s[34:35]
	s_mov_b32 m0, s94
	s_nop 0
	global_load_lds_dwordx4 v[210:211], off
	s_waitcnt vmcnt(8)
	s_waitcnt lgkmcnt(0)
	s_waitcnt lgkmcnt(0)
	v_mfma_f32_16x16x32_bf16 v[126:129], v[132:135], v[164:167], v[126:129]
	v_mfma_f32_16x16x32_bf16 v[122:125], v[140:143], v[164:167], v[122:125]
	v_mfma_f32_16x16x32_bf16 v[110:113], v[132:135], v[172:175], v[110:113]
	s_barrier
	s_setprio 1
	v_mfma_f32_16x16x32_bf16 v[106:109], v[140:143], v[172:175], v[106:109]
	v_mfma_f32_16x16x32_bf16 v[94:97], v[132:135], v[180:183], v[94:97]
	v_mfma_f32_16x16x32_bf16 v[90:93], v[140:143], v[180:183], v[90:93]
	v_mfma_f32_16x16x32_bf16 v[78:81], v[132:135], v[200:203], v[78:81]
	v_mfma_f32_16x16x32_bf16 v[74:77], v[140:143], v[200:203], v[74:77]
	v_mfma_f32_16x16x32_bf16 v[126:129], v[136:139], v[168:171], v[126:129]
	v_mfma_f32_16x16x32_bf16 v[122:125], v[144:147], v[168:171], v[122:125]
	v_mfma_f32_16x16x32_bf16 v[110:113], v[136:139], v[176:179], v[110:113]
	v_mfma_f32_16x16x32_bf16 v[106:109], v[144:147], v[176:179], v[106:109]
	v_mfma_f32_16x16x32_bf16 v[94:97], v[136:139], v[196:199], v[94:97]
	v_mfma_f32_16x16x32_bf16 v[90:93], v[144:147], v[196:199], v[90:93]
	v_mfma_f32_16x16x32_bf16 v[78:81], v[136:139], v[204:207], v[78:81]
	v_mfma_f32_16x16x32_bf16 v[74:77], v[144:147], v[204:207], v[74:77]
	s_setprio 0
	s_setprio 1
	v_mfma_f32_16x16x32_bf16 v[118:121], v[148:151], v[164:167], v[118:121]
	v_mfma_f32_16x16x32_bf16 v[114:117], v[156:159], v[164:167], v[114:117]
	v_mfma_f32_16x16x32_bf16 v[102:105], v[148:151], v[172:175], v[102:105]
	v_mfma_f32_16x16x32_bf16 v[98:101], v[156:159], v[172:175], v[98:101]
	v_mfma_f32_16x16x32_bf16 v[86:89], v[148:151], v[180:183], v[86:89]
	v_mfma_f32_16x16x32_bf16 v[82:85], v[156:159], v[180:183], v[82:85]
	v_mfma_f32_16x16x32_bf16 v[70:73], v[148:151], v[200:203], v[70:73]
	v_mfma_f32_16x16x32_bf16 v[66:69], v[156:159], v[200:203], v[66:69]
	v_mfma_f32_16x16x32_bf16 v[118:121], v[152:155], v[168:171], v[118:121]
	v_mfma_f32_16x16x32_bf16 v[114:117], v[160:163], v[168:171], v[114:117]
	v_mfma_f32_16x16x32_bf16 v[102:105], v[152:155], v[176:179], v[102:105]
	v_mfma_f32_16x16x32_bf16 v[98:101], v[160:163], v[176:179], v[98:101]
	v_mfma_f32_16x16x32_bf16 v[86:89], v[152:155], v[196:199], v[86:89]
	v_mfma_f32_16x16x32_bf16 v[82:85], v[160:163], v[196:199], v[82:85]
	v_mfma_f32_16x16x32_bf16 v[70:73], v[152:155], v[204:207], v[70:73]
	v_mfma_f32_16x16x32_bf16 v[66:69], v[160:163], v[204:207], v[66:69]
	s_setprio 0
	s_barrier
	s_mov_b32 m0, s33
	v_lshl_add_u64 v[210:211], v[184:185], 0, s[46:47]
	ds_read_b128 v[164:167], v220 offset:49152
	ds_read_b128 v[168:171], v220 offset:50176
	ds_read_b128 v[172:175], v220 offset:51200
	ds_read_b128 v[176:179], v220 offset:52224
	ds_read_b128 v[180:183], v220 offset:53248
	ds_read_b128 v[196:199], v220 offset:54272
	ds_read_b128 v[200:203], v220 offset:55296
	ds_read_b128 v[204:207], v220 offset:56320
	global_load_lds_dwordx4 v[210:211], off
	v_lshl_add_u64 v[210:211], v[184:185], 0, s[48:49]
	s_mov_b32 m0, s88
	s_nop 0
	global_load_lds_dwordx4 v[210:211], off
	v_lshl_add_u64 v[210:211], v[184:185], 0, s[54:55]
	s_mov_b32 m0, s89
	v_lshl_add_u64 v[184:185], v[184:185], 0, s[56:57]
	global_load_lds_dwordx4 v[210:211], off
	s_mov_b32 m0, s90
	s_nop 0
	global_load_lds_dwordx4 v[184:185], off
	v_lshl_add_u64 v[184:185], v[208:209], 0, s[46:47]
	s_mov_b32 m0, s13
	s_nop 0
	global_load_lds_dwordx4 v[184:185], off
	v_lshl_add_u64 v[184:185], v[208:209], 0, s[48:49]
	s_mov_b32 m0, s14
	s_nop 0
	global_load_lds_dwordx4 v[184:185], off
	s_waitcnt vmcnt(8)
	s_waitcnt lgkmcnt(0)
	s_waitcnt lgkmcnt(0)
	v_mfma_f32_16x16x32_bf16 v[62:65], v[132:135], v[164:167], v[62:65]
	v_mfma_f32_16x16x32_bf16 v[58:61], v[140:143], v[164:167], v[58:61]
	v_mfma_f32_16x16x32_bf16 v[46:49], v[132:135], v[172:175], v[46:49]
	s_barrier
	s_setprio 1
	v_mfma_f32_16x16x32_bf16 v[42:45], v[140:143], v[172:175], v[42:45]
	v_mfma_f32_16x16x32_bf16 v[30:33], v[132:135], v[180:183], v[30:33]
	v_mfma_f32_16x16x32_bf16 v[26:29], v[140:143], v[180:183], v[26:29]
	v_mfma_f32_16x16x32_bf16 v[14:17], v[132:135], v[200:203], v[14:17]
	v_mfma_f32_16x16x32_bf16 v[10:13], v[140:143], v[200:203], v[10:13]
	v_mfma_f32_16x16x32_bf16 v[62:65], v[136:139], v[168:171], v[62:65]
	v_mfma_f32_16x16x32_bf16 v[58:61], v[144:147], v[168:171], v[58:61]
	v_mfma_f32_16x16x32_bf16 v[46:49], v[136:139], v[176:179], v[46:49]
	v_mfma_f32_16x16x32_bf16 v[42:45], v[144:147], v[176:179], v[42:45]
	v_mfma_f32_16x16x32_bf16 v[30:33], v[136:139], v[196:199], v[30:33]
	v_mfma_f32_16x16x32_bf16 v[26:29], v[144:147], v[196:199], v[26:29]
	v_mfma_f32_16x16x32_bf16 v[14:17], v[136:139], v[204:207], v[14:17]
	v_mfma_f32_16x16x32_bf16 v[10:13], v[144:147], v[204:207], v[10:13]
	s_setprio 0
	s_setprio 1
	v_mfma_f32_16x16x32_bf16 v[54:57], v[148:151], v[164:167], v[54:57]
	v_mfma_f32_16x16x32_bf16 v[50:53], v[156:159], v[164:167], v[50:53]
	v_mfma_f32_16x16x32_bf16 v[38:41], v[148:151], v[172:175], v[38:41]
	v_mfma_f32_16x16x32_bf16 v[34:37], v[156:159], v[172:175], v[34:37]
	v_mfma_f32_16x16x32_bf16 v[22:25], v[148:151], v[180:183], v[22:25]
	v_mfma_f32_16x16x32_bf16 v[18:21], v[156:159], v[180:183], v[18:21]
	v_mfma_f32_16x16x32_bf16 v[6:9], v[148:151], v[200:203], v[6:9]
	v_mfma_f32_16x16x32_bf16 v[2:5], v[156:159], v[200:203], v[2:5]
	v_mfma_f32_16x16x32_bf16 v[54:57], v[152:155], v[168:171], v[54:57]
	v_mfma_f32_16x16x32_bf16 v[50:53], v[160:163], v[168:171], v[50:53]
	v_mfma_f32_16x16x32_bf16 v[38:41], v[152:155], v[176:179], v[38:41]
	v_mfma_f32_16x16x32_bf16 v[34:37], v[160:163], v[176:179], v[34:37]
	v_mfma_f32_16x16x32_bf16 v[22:25], v[152:155], v[196:199], v[22:25]
	v_mfma_f32_16x16x32_bf16 v[18:21], v[160:163], v[196:199], v[18:21]
	v_mfma_f32_16x16x32_bf16 v[6:9], v[152:155], v[204:207], v[6:9]
	v_mfma_f32_16x16x32_bf16 v[2:5], v[160:163], v[204:207], v[2:5]
	s_setprio 0
	s_barrier
	s_add_i32 s18, s91, 2
	s_add_u32 s6, s6, 0x100
	s_addc_u32 s7, s7, 0
	s_add_u32 s36, s36, 0x100
	s_addc_u32 s37, s37, 0
	s_cmp_ge_i32 s91, s76
	s_mov_b32 s91, s18
	s_cbranch_scc0 .LBB0_1466

.LBB0_1717:
	s_add_u32 s50, s6, 0x200
	s_addc_u32 s51, s7, 0
	s_ashr_i32 s73, s72, 31
	s_lshl_b64 s[12:13], s[72:73], 19
	s_add_u32 s78, s42, s12
	s_addc_u32 s79, s43, s13
	s_and_b64 s[12:13], s[0:1], exec
	s_cselect_b32 s73, s79, s15
	s_cselect_b32 s93, s78, s14
	s_ashr_i32 s67, s66, 31
	s_lshl_b64 s[12:13], s[66:67], 19
	v_readlane_b32 s18, v255, 15
	v_readlane_b32 s19, v255, 16
	s_add_u32 s74, s18, s12
	s_addc_u32 s75, s19, s13
	s_and_b64 s[12:13], s[0:1], exec
	s_cselect_b32 s67, s75, s7
	s_cselect_b32 s94, s74, s6
	v_lshl_add_u64 v[140:141], s[14:15], 0, v[130:131]
	s_add_i32 s95, s11, 0xc000
	v_lshl_add_u64 v[66:67], v[140:141], 0, s[38:39]
	s_mov_b32 m0, s95
	s_add_i32 s96, s11, 0xe000
	global_load_lds_dwordx4 v[66:67], off
	v_lshl_add_u64 v[66:67], v[140:141], 0, s[40:41]
	s_mov_b32 m0, s96
	s_nop 0
	global_load_lds_dwordx4 v[66:67], off
	s_waitcnt vmcnt(8)
	s_waitcnt lgkmcnt(0)
	s_waitcnt lgkmcnt(0)
	v_mfma_f32_16x16x32_bf16 v[86:89], v[10:13], v[50:53], 0
	v_mfma_f32_16x16x32_bf16 v[90:93], v[14:17], v[54:57], v[86:89]
	v_mfma_f32_16x16x32_bf16 v[86:89], v[2:5], v[58:61], 0
	s_barrier
	s_setprio 1
	v_mfma_f32_16x16x32_bf16 v[66:69], v[2:5], v[34:37], 0
	v_mfma_f32_16x16x32_bf16 v[70:73], v[10:13], v[34:37], 0
	v_mfma_f32_16x16x32_bf16 v[74:77], v[2:5], v[42:45], 0
	v_mfma_f32_16x16x32_bf16 v[78:81], v[10:13], v[42:45], 0
	v_mfma_f32_16x16x32_bf16 v[82:85], v[2:5], v[50:53], 0
	v_mfma_f32_16x16x32_bf16 v[94:97], v[6:9], v[62:65], v[86:89]
	v_mfma_f32_16x16x32_bf16 v[86:89], v[10:13], v[58:61], 0
	v_mfma_f32_16x16x32_bf16 v[66:69], v[6:9], v[38:41], v[66:69]
	v_mfma_f32_16x16x32_bf16 v[70:73], v[14:17], v[38:41], v[70:73]
	v_mfma_f32_16x16x32_bf16 v[74:77], v[6:9], v[46:49], v[74:77]
	v_mfma_f32_16x16x32_bf16 v[78:81], v[14:17], v[46:49], v[78:81]
	v_mfma_f32_16x16x32_bf16 v[82:85], v[6:9], v[54:57], v[82:85]
	v_mfma_f32_16x16x32_bf16 v[106:109], v[14:17], v[62:65], v[86:89]
	s_setprio 0
	s_setprio 1
	v_mfma_f32_16x16x32_bf16 v[86:89], v[18:21], v[34:37], 0
	v_mfma_f32_16x16x32_bf16 v[34:37], v[26:29], v[34:37], 0
	v_mfma_f32_16x16x32_bf16 v[110:113], v[22:25], v[38:41], v[86:89]
	v_mfma_f32_16x16x32_bf16 v[34:37], v[30:33], v[38:41], v[34:37]
	v_mfma_f32_16x16x32_bf16 v[38:41], v[18:21], v[42:45], 0
	v_mfma_f32_16x16x32_bf16 v[42:45], v[26:29], v[42:45], 0
	v_mfma_f32_16x16x32_bf16 v[38:41], v[22:25], v[46:49], v[38:41]
	v_mfma_f32_16x16x32_bf16 v[42:45], v[30:33], v[46:49], v[42:45]
	v_mfma_f32_16x16x32_bf16 v[46:49], v[18:21], v[50:53], 0
	v_mfma_f32_16x16x32_bf16 v[50:53], v[26:29], v[50:53], 0
	v_mfma_f32_16x16x32_bf16 v[46:49], v[22:25], v[54:57], v[46:49]
	v_mfma_f32_16x16x32_bf16 v[50:53], v[30:33], v[54:57], v[50:53]
	v_mfma_f32_16x16x32_bf16 v[54:57], v[18:21], v[58:61], 0
	v_mfma_f32_16x16x32_bf16 v[58:61], v[26:29], v[58:61], 0
	v_mfma_f32_16x16x32_bf16 v[54:57], v[22:25], v[62:65], v[54:57]
	v_mfma_f32_16x16x32_bf16 v[58:61], v[30:33], v[62:65], v[58:61]
	s_setprio 0
	s_barrier
	v_lshl_add_u64 v[184:185], s[6:7], 0, v[132:133]
	s_add_i32 s97, s89, s52
	v_lshl_add_u64 v[150:151], v[184:185], 0, s[46:47]
	s_mov_b32 m0, s97
	s_add_i32 vcc_lo, s97, 0x2000
	ds_read_b128 v[62:65], v147 offset:16384
	ds_read_b128 v[86:89], v147 offset:17408
	ds_read_b128 v[98:101], v147 offset:18432
	ds_read_b128 v[102:105], v147 offset:19456
	ds_read_b128 v[114:117], v147 offset:20480
	ds_read_b128 v[118:121], v147 offset:21504
	ds_read_b128 v[122:125], v147 offset:22528
	ds_read_b128 v[126:129], v147 offset:23552
	global_load_lds_dwordx4 v[150:151], off
	v_lshl_add_u64 v[150:151], v[184:185], 0, s[48:49]
	s_mov_b32 m0, vcc_lo
	s_add_i32 s33, s90, s52
	global_load_lds_dwordx4 v[150:151], off
	v_lshl_add_u64 v[150:151], v[184:185], 0, s[54:55]
	s_mov_b32 m0, s33
	s_add_i32 vcc_hi, s33, 0x2000
	global_load_lds_dwordx4 v[150:151], off
	v_lshl_add_u64 v[150:151], v[184:185], 0, s[56:57]
	s_mov_b32 m0, vcc_hi
	s_nop 0
	global_load_lds_dwordx4 v[150:151], off
	v_lshl_add_u64 v[150:151], v[140:141], 0, s[46:47]
	s_mov_b32 m0, s11
	s_nop 0
	global_load_lds_dwordx4 v[150:151], off
	v_lshl_add_u64 v[150:151], v[140:141], 0, s[48:49]
	s_mov_b32 m0, s77
	s_nop 0
	global_load_lds_dwordx4 v[150:151], off
	s_waitcnt vmcnt(8)
	s_waitcnt lgkmcnt(0)
	s_waitcnt lgkmcnt(0)
	v_mfma_f32_16x16x32_bf16 v[150:153], v[2:5], v[62:65], 0
	v_mfma_f32_16x16x32_bf16 v[160:163], v[2:5], v[98:101], 0
	v_mfma_f32_16x16x32_bf16 v[168:171], v[2:5], v[114:117], 0
	s_barrier
	s_setprio 1
	v_mfma_f32_16x16x32_bf16 v[2:5], v[2:5], v[122:125], 0
	v_mfma_f32_16x16x32_bf16 v[152:155], v[6:9], v[86:89], v[150:153]
	v_mfma_f32_16x16x32_bf16 v[160:163], v[6:9], v[102:105], v[160:163]
	v_mfma_f32_16x16x32_bf16 v[168:171], v[6:9], v[118:121], v[168:171]
	v_mfma_f32_16x16x32_bf16 v[2:5], v[6:9], v[126:129], v[2:5]
	v_mfma_f32_16x16x32_bf16 v[6:9], v[10:13], v[122:125], 0
	v_mfma_f32_16x16x32_bf16 v[156:159], v[10:13], v[62:65], 0
	v_mfma_f32_16x16x32_bf16 v[164:167], v[10:13], v[98:101], 0
	v_mfma_f32_16x16x32_bf16 v[172:175], v[10:13], v[114:117], 0
	v_mfma_f32_16x16x32_bf16 v[10:13], v[14:17], v[126:129], v[6:9]
	v_mfma_f32_16x16x32_bf16 v[156:159], v[14:17], v[86:89], v[156:159]
	v_mfma_f32_16x16x32_bf16 v[164:167], v[14:17], v[102:105], v[164:167]
	v_mfma_f32_16x16x32_bf16 v[172:175], v[14:17], v[118:121], v[172:175]
	s_setprio 0
	s_setprio 1
	v_mfma_f32_16x16x32_bf16 v[6:9], v[18:21], v[62:65], 0
	v_mfma_f32_16x16x32_bf16 v[14:17], v[22:25], v[86:89], v[6:9]
	v_mfma_f32_16x16x32_bf16 v[6:9], v[26:29], v[62:65], 0
	v_mfma_f32_16x16x32_bf16 v[176:179], v[30:33], v[86:89], v[6:9]
	v_mfma_f32_16x16x32_bf16 v[6:9], v[18:21], v[98:101], 0
	v_mfma_f32_16x16x32_bf16 v[180:183], v[22:25], v[102:105], v[6:9]
	v_mfma_f32_16x16x32_bf16 v[6:9], v[26:29], v[98:101], 0
	v_mfma_f32_16x16x32_bf16 v[188:191], v[30:33], v[102:105], v[6:9]
	v_mfma_f32_16x16x32_bf16 v[6:9], v[18:21], v[114:117], 0
	v_mfma_f32_16x16x32_bf16 v[192:195], v[22:25], v[118:121], v[6:9]
	v_mfma_f32_16x16x32_bf16 v[6:9], v[26:29], v[114:117], 0
	v_mfma_f32_16x16x32_bf16 v[196:199], v[30:33], v[118:121], v[6:9]
	v_mfma_f32_16x16x32_bf16 v[6:9], v[18:21], v[122:125], 0
	v_mfma_f32_16x16x32_bf16 v[200:203], v[22:25], v[126:129], v[6:9]
	v_mfma_f32_16x16x32_bf16 v[6:9], v[26:29], v[122:125], 0
	v_mfma_f32_16x16x32_bf16 v[204:207], v[30:33], v[126:129], v[6:9]
	s_setprio 0
	s_barrier
	s_add_i32 s12, 0, 0x18000
	s_add_i32 s3, 0, 0x1c000
	v_add_u32_e32 v149, s12, v144
	v_add_u32_e32 v150, s3, v144
	s_nop 0
	ds_read_b128 v[6:9], v149
	ds_read_b128 v[26:29], v149 offset:1024
	ds_read_b128 v[30:33], v149 offset:2048
	ds_read_b128 v[208:211], v149 offset:3072
	ds_read_b128 v[212:215], v150
	ds_read_b128 v[216:219], v150 offset:1024
	ds_read_b128 v[220:223], v150 offset:2048
	ds_read_b128 v[224:227], v150 offset:3072
	s_mov_b32 m0, s80
	v_lshl_add_u64 v[62:63], v[140:141], 0, s[54:55]
	ds_read_b128 v[18:21], v147 offset:32768
	ds_read_b128 v[22:25], v147 offset:33792
	ds_read_b128 v[228:231], v147 offset:34816
	ds_read_b128 v[232:235], v147 offset:35840
	ds_read_b128 v[236:239], v147 offset:36864
	ds_read_b128 v[240:243], v147 offset:37888
	ds_read_b128 v[244:247], v147 offset:38912
	ds_read_b128 v[248:251], v147 offset:39936
	global_load_lds_dwordx4 v[62:63], off
	v_lshl_add_u64 v[62:63], v[140:141], 0, s[56:57]
	s_mov_b32 m0, s81
	s_nop 0
	global_load_lds_dwordx4 v[62:63], off
	s_waitcnt vmcnt(8)
	s_waitcnt lgkmcnt(0)
	s_waitcnt lgkmcnt(0)
	v_mfma_f32_16x16x32_bf16 v[62:65], v[6:9], v[18:21], v[66:69]
	v_mfma_f32_16x16x32_bf16 v[118:121], v[26:29], v[22:25], v[62:65]
	v_mfma_f32_16x16x32_bf16 v[62:65], v[30:33], v[18:21], v[70:73]
	s_barrier
	s_setprio 1
	v_mfma_f32_16x16x32_bf16 v[114:117], v[208:211], v[22:25], v[62:65]
	v_mfma_f32_16x16x32_bf16 v[62:65], v[6:9], v[228:231], v[74:77]
	v_mfma_f32_16x16x32_bf16 v[102:105], v[26:29], v[232:235], v[62:65]
	v_mfma_f32_16x16x32_bf16 v[62:65], v[30:33], v[228:231], v[78:81]
	v_mfma_f32_16x16x32_bf16 v[98:101], v[208:211], v[232:235], v[62:65]
	v_mfma_f32_16x16x32_bf16 v[62:65], v[6:9], v[236:239], v[82:85]
	v_mfma_f32_16x16x32_bf16 v[86:89], v[26:29], v[240:243], v[62:65]
	v_mfma_f32_16x16x32_bf16 v[62:65], v[30:33], v[236:239], v[90:93]
	v_mfma_f32_16x16x32_bf16 v[82:85], v[208:211], v[240:243], v[62:65]
	v_mfma_f32_16x16x32_bf16 v[62:65], v[6:9], v[244:247], v[94:97]
	v_mfma_f32_16x16x32_bf16 v[70:73], v[26:29], v[248:251], v[62:65]
	v_mfma_f32_16x16x32_bf16 v[62:65], v[30:33], v[244:247], v[106:109]
	v_mfma_f32_16x16x32_bf16 v[62:65], v[208:211], v[248:251], v[62:65]
	s_setprio 0
	s_setprio 1
	v_mfma_f32_16x16x32_bf16 v[66:69], v[212:215], v[18:21], v[110:113]
	v_mfma_f32_16x16x32_bf16 v[18:21], v[220:223], v[18:21], v[34:37]
	v_mfma_f32_16x16x32_bf16 v[122:125], v[224:227], v[22:25], v[18:21]
	v_mfma_f32_16x16x32_bf16 v[18:21], v[212:215], v[228:231], v[38:41]
	v_mfma_f32_16x16x32_bf16 v[110:113], v[216:219], v[232:235], v[18:21]
	v_mfma_f32_16x16x32_bf16 v[18:21], v[220:223], v[228:231], v[42:45]
	v_mfma_f32_16x16x32_bf16 v[106:109], v[224:227], v[232:235], v[18:21]
	v_mfma_f32_16x16x32_bf16 v[18:21], v[212:215], v[236:239], v[46:49]
	v_mfma_f32_16x16x32_bf16 v[94:97], v[216:219], v[240:243], v[18:21]
	v_mfma_f32_16x16x32_bf16 v[18:21], v[220:223], v[236:239], v[50:53]
	v_mfma_f32_16x16x32_bf16 v[90:93], v[224:227], v[240:243], v[18:21]
	v_mfma_f32_16x16x32_bf16 v[18:21], v[212:215], v[244:247], v[54:57]
	v_mfma_f32_16x16x32_bf16 v[78:81], v[216:219], v[248:251], v[18:21]
	v_mfma_f32_16x16x32_bf16 v[18:21], v[220:223], v[244:247], v[58:61]
	v_mfma_f32_16x16x32_bf16 v[126:129], v[216:219], v[22:25], v[66:69]
	v_mfma_f32_16x16x32_bf16 v[74:77], v[224:227], v[248:251], v[18:21]
	s_setprio 0
	s_barrier
	s_add_i32 s12, s12, s52
	s_nop 2
	v_lshl_add_u64 v[18:19], v[184:185], 0, s[58:59]
	s_mov_b32 m0, s12
	s_add_i32 s13, s12, 0x2000
	ds_read_b128 v[42:45], v147 offset:49152
	ds_read_b128 v[46:49], v147 offset:50176
	ds_read_b128 v[228:231], v147 offset:51200
	ds_read_b128 v[232:235], v147 offset:52224
	ds_read_b128 v[236:239], v147 offset:53248
	ds_read_b128 v[240:243], v147 offset:54272
	ds_read_b128 v[244:247], v147 offset:55296
	ds_read_b128 v[248:251], v147 offset:56320
	global_load_lds_dwordx4 v[18:19], off
	v_lshl_add_u64 v[18:19], v[184:185], 0, s[60:61]
	s_mov_b32 m0, s13
	s_add_i32 s3, s3, s52
	global_load_lds_dwordx4 v[18:19], off
	v_lshl_add_u64 v[18:19], v[184:185], 0, s[62:63]
	s_mov_b32 m0, s3
	s_add_i32 s36, s3, 0x2000
	global_load_lds_dwordx4 v[18:19], off
	v_lshl_add_u64 v[18:19], v[184:185], 0, s[64:65]
	s_mov_b32 m0, s36
	s_nop 0
	global_load_lds_dwordx4 v[18:19], off
	v_lshl_add_u64 v[18:19], v[140:141], 0, s[58:59]
	s_mov_b32 m0, s86
	s_nop 0
	global_load_lds_dwordx4 v[18:19], off
	v_lshl_add_u64 v[18:19], v[140:141], 0, s[60:61]
	s_mov_b32 m0, s87
	s_nop 0
	global_load_lds_dwordx4 v[18:19], off
	s_waitcnt vmcnt(8)
	s_waitcnt lgkmcnt(0)
	s_waitcnt lgkmcnt(0)
	v_mfma_f32_16x16x32_bf16 v[18:21], v[6:9], v[42:45], v[152:155]
	v_mfma_f32_16x16x32_bf16 v[54:57], v[26:29], v[46:49], v[18:21]
	v_mfma_f32_16x16x32_bf16 v[18:21], v[30:33], v[42:45], v[156:159]
	s_barrier
	s_setprio 1
	v_mfma_f32_16x16x32_bf16 v[50:53], v[208:211], v[46:49], v[18:21]
	v_mfma_f32_16x16x32_bf16 v[18:21], v[6:9], v[228:231], v[160:163]
	v_mfma_f32_16x16x32_bf16 v[38:41], v[26:29], v[232:235], v[18:21]
	v_mfma_f32_16x16x32_bf16 v[18:21], v[30:33], v[228:231], v[164:167]
	v_mfma_f32_16x16x32_bf16 v[34:37], v[208:211], v[232:235], v[18:21]
	v_mfma_f32_16x16x32_bf16 v[18:21], v[6:9], v[236:239], v[168:171]
	v_mfma_f32_16x16x32_bf16 v[2:5], v[6:9], v[244:247], v[2:5]
	v_mfma_f32_16x16x32_bf16 v[22:25], v[26:29], v[240:243], v[18:21]
	v_mfma_f32_16x16x32_bf16 v[18:21], v[30:33], v[236:239], v[172:175]
	v_mfma_f32_16x16x32_bf16 v[6:9], v[26:29], v[248:251], v[2:5]
	v_mfma_f32_16x16x32_bf16 v[2:5], v[30:33], v[244:247], v[10:13]
	v_mfma_f32_16x16x32_bf16 v[18:21], v[208:211], v[240:243], v[18:21]
	v_mfma_f32_16x16x32_bf16 v[2:5], v[208:211], v[248:251], v[2:5]
	s_setprio 0
	s_setprio 1
	v_mfma_f32_16x16x32_bf16 v[10:13], v[212:215], v[42:45], v[14:17]
	v_mfma_f32_16x16x32_bf16 v[66:69], v[216:219], v[46:49], v[10:13]
	v_mfma_f32_16x16x32_bf16 v[10:13], v[220:223], v[42:45], v[176:179]
	v_mfma_f32_16x16x32_bf16 v[58:61], v[224:227], v[46:49], v[10:13]
	v_mfma_f32_16x16x32_bf16 v[10:13], v[212:215], v[228:231], v[180:183]
	v_mfma_f32_16x16x32_bf16 v[46:49], v[216:219], v[232:235], v[10:13]
	v_mfma_f32_16x16x32_bf16 v[10:13], v[220:223], v[228:231], v[188:191]
	v_mfma_f32_16x16x32_bf16 v[42:45], v[224:227], v[232:235], v[10:13]
	v_mfma_f32_16x16x32_bf16 v[10:13], v[212:215], v[236:239], v[192:195]
	v_mfma_f32_16x16x32_bf16 v[30:33], v[216:219], v[240:243], v[10:13]
	v_mfma_f32_16x16x32_bf16 v[10:13], v[220:223], v[236:239], v[196:199]
	v_mfma_f32_16x16x32_bf16 v[26:29], v[224:227], v[240:243], v[10:13]
	v_mfma_f32_16x16x32_bf16 v[10:13], v[212:215], v[244:247], v[200:203]
	v_mfma_f32_16x16x32_bf16 v[14:17], v[216:219], v[248:251], v[10:13]
	v_mfma_f32_16x16x32_bf16 v[10:13], v[220:223], v[244:247], v[204:207]
	v_mfma_f32_16x16x32_bf16 v[10:13], v[224:227], v[248:251], v[10:13]
	s_setprio 0
	s_barrier
	v_lshl_add_u64 v[140:141], s[14:15], 0, v[134:135]
	s_mov_b32 s37, 0
	s_mov_b64 s[6:7], 0
.LBB0_1718:
	ds_read_b128 v[152:155], v145
	ds_read_b128 v[156:159], v145 offset:1024
	ds_read_b128 v[160:163], v145 offset:2048
	ds_read_b128 v[164:167], v145 offset:3072
	ds_read_b128 v[168:171], v146
	ds_read_b128 v[172:175], v146 offset:1024
	ds_read_b128 v[176:179], v146 offset:2048
	ds_read_b128 v[180:183], v146 offset:3072
	s_add_u32 s18, s14, s6
	s_addc_u32 s19, s15, s7
	s_add_u32 s18, s18, 0x200
	s_addc_u32 s19, s19, 0
	s_add_u32 s20, s50, s6
	s_addc_u32 s21, s51, s7
	s_cmpk_eq_i32 s6, 0x600
	s_cselect_b32 s19, s73, s19
	s_cselect_b32 s18, s93, s18
	s_cselect_b32 s21, s67, s21
	s_cselect_b32 s20, s94, s20
	v_lshl_add_u64 v[184:185], v[140:141], 0, s[6:7]
	s_mov_b32 m0, s95
	v_lshl_add_u64 v[220:221], v[184:185], 0, s[62:63]
	ds_read_b128 v[188:191], v147
	ds_read_b128 v[192:195], v147 offset:1024
	ds_read_b128 v[196:199], v147 offset:2048
	ds_read_b128 v[200:203], v147 offset:3072
	ds_read_b128 v[204:207], v147 offset:4096
	ds_read_b128 v[208:211], v147 offset:5120
	ds_read_b128 v[212:215], v147 offset:6144
	ds_read_b128 v[216:219], v147 offset:7168
	global_load_lds_dwordx4 v[220:221], off
	v_lshl_add_u64 v[184:185], v[184:185], 0, s[64:65]
	s_mov_b32 m0, s96
	s_nop 0
	global_load_lds_dwordx4 v[184:185], off
	s_waitcnt vmcnt(8)
	s_waitcnt lgkmcnt(0)
	s_waitcnt lgkmcnt(0)
	v_mfma_f32_16x16x32_bf16 v[118:121], v[152:155], v[188:191], v[118:121]
	v_mfma_f32_16x16x32_bf16 v[114:117], v[160:163], v[188:191], v[114:117]
	v_mfma_f32_16x16x32_bf16 v[102:105], v[152:155], v[196:199], v[102:105]
	s_barrier
	s_setprio 1
	v_mfma_f32_16x16x32_bf16 v[98:101], v[160:163], v[196:199], v[98:101]
	v_mfma_f32_16x16x32_bf16 v[86:89], v[152:155], v[204:207], v[86:89]
	v_mfma_f32_16x16x32_bf16 v[82:85], v[160:163], v[204:207], v[82:85]
	v_mfma_f32_16x16x32_bf16 v[70:73], v[152:155], v[212:215], v[70:73]
	v_mfma_f32_16x16x32_bf16 v[62:65], v[160:163], v[212:215], v[62:65]
	v_mfma_f32_16x16x32_bf16 v[118:121], v[156:159], v[192:195], v[118:121]
	v_mfma_f32_16x16x32_bf16 v[114:117], v[164:167], v[192:195], v[114:117]
	v_mfma_f32_16x16x32_bf16 v[102:105], v[156:159], v[200:203], v[102:105]
	v_mfma_f32_16x16x32_bf16 v[98:101], v[164:167], v[200:203], v[98:101]
	v_mfma_f32_16x16x32_bf16 v[86:89], v[156:159], v[208:211], v[86:89]
	v_mfma_f32_16x16x32_bf16 v[82:85], v[164:167], v[208:211], v[82:85]
	v_mfma_f32_16x16x32_bf16 v[70:73], v[156:159], v[216:219], v[70:73]
	v_mfma_f32_16x16x32_bf16 v[62:65], v[164:167], v[216:219], v[62:65]
	s_setprio 0
	s_setprio 1
	v_mfma_f32_16x16x32_bf16 v[126:129], v[168:171], v[188:191], v[126:129]
	v_mfma_f32_16x16x32_bf16 v[122:125], v[176:179], v[188:191], v[122:125]
	v_mfma_f32_16x16x32_bf16 v[110:113], v[168:171], v[196:199], v[110:113]
	v_mfma_f32_16x16x32_bf16 v[106:109], v[176:179], v[196:199], v[106:109]
	v_mfma_f32_16x16x32_bf16 v[94:97], v[168:171], v[204:207], v[94:97]
	v_mfma_f32_16x16x32_bf16 v[90:93], v[176:179], v[204:207], v[90:93]
	v_mfma_f32_16x16x32_bf16 v[78:81], v[168:171], v[212:215], v[78:81]
	v_mfma_f32_16x16x32_bf16 v[74:77], v[176:179], v[212:215], v[74:77]
	v_mfma_f32_16x16x32_bf16 v[126:129], v[172:175], v[192:195], v[126:129]
	v_mfma_f32_16x16x32_bf16 v[122:125], v[180:183], v[192:195], v[122:125]
	v_mfma_f32_16x16x32_bf16 v[110:113], v[172:175], v[200:203], v[110:113]
	v_mfma_f32_16x16x32_bf16 v[106:109], v[180:183], v[200:203], v[106:109]
	v_mfma_f32_16x16x32_bf16 v[94:97], v[172:175], v[208:211], v[94:97]
	v_mfma_f32_16x16x32_bf16 v[90:93], v[180:183], v[208:211], v[90:93]
	v_mfma_f32_16x16x32_bf16 v[78:81], v[172:175], v[216:219], v[78:81]
	v_mfma_f32_16x16x32_bf16 v[74:77], v[180:183], v[216:219], v[74:77]
	s_setprio 0
	s_barrier
	s_mov_b32 m0, s97
	v_lshl_add_u64 v[184:185], s[20:21], 0, v[132:133]
	ds_read_b128 v[188:191], v147 offset:16384
	ds_read_b128 v[192:195], v147 offset:17408
	ds_read_b128 v[196:199], v147 offset:18432
	ds_read_b128 v[200:203], v147 offset:19456
	ds_read_b128 v[204:207], v147 offset:20480
	ds_read_b128 v[208:211], v147 offset:21504
	ds_read_b128 v[212:215], v147 offset:22528
	ds_read_b128 v[216:219], v147 offset:23552
	global_load_lds_dwordx4 v[184:185], off
	v_lshl_add_u64 v[220:221], v[184:185], 0, s[16:17]
	s_mov_b32 m0, vcc_lo
	s_nop 0
	global_load_lds_dwordx4 v[220:221], off
	v_lshl_add_u64 v[220:221], v[184:185], 0, s[24:25]
	s_mov_b32 m0, s33
	s_nop 0
	global_load_lds_dwordx4 v[220:221], off
	v_lshl_add_u64 v[220:221], v[184:185], 0, s[26:27]
	s_mov_b32 m0, vcc_hi
	s_nop 0
	global_load_lds_dwordx4 v[220:221], off
	v_lshl_add_u64 v[220:221], s[18:19], 0, v[130:131]
	s_mov_b32 m0, s11
	v_lshl_add_u64 v[222:223], v[220:221], 0, s[16:17]
	global_load_lds_dwordx4 v[220:221], off
	s_mov_b32 m0, s77
	s_nop 0
	global_load_lds_dwordx4 v[222:223], off
	s_waitcnt vmcnt(8)
	s_waitcnt lgkmcnt(0)
	s_waitcnt lgkmcnt(0)
	v_mfma_f32_16x16x32_bf16 v[54:57], v[152:155], v[188:191], v[54:57]
	v_mfma_f32_16x16x32_bf16 v[50:53], v[160:163], v[188:191], v[50:53]
	v_mfma_f32_16x16x32_bf16 v[38:41], v[152:155], v[196:199], v[38:41]
	s_barrier
	s_setprio 1
	v_mfma_f32_16x16x32_bf16 v[34:37], v[160:163], v[196:199], v[34:37]
	v_mfma_f32_16x16x32_bf16 v[22:25], v[152:155], v[204:207], v[22:25]
	v_mfma_f32_16x16x32_bf16 v[18:21], v[160:163], v[204:207], v[18:21]
	v_mfma_f32_16x16x32_bf16 v[6:9], v[152:155], v[212:215], v[6:9]
	v_mfma_f32_16x16x32_bf16 v[2:5], v[160:163], v[212:215], v[2:5]
	v_mfma_f32_16x16x32_bf16 v[54:57], v[156:159], v[192:195], v[54:57]
	v_mfma_f32_16x16x32_bf16 v[50:53], v[164:167], v[192:195], v[50:53]
	v_mfma_f32_16x16x32_bf16 v[38:41], v[156:159], v[200:203], v[38:41]
	v_mfma_f32_16x16x32_bf16 v[34:37], v[164:167], v[200:203], v[34:37]
	v_mfma_f32_16x16x32_bf16 v[22:25], v[156:159], v[208:211], v[22:25]
	v_mfma_f32_16x16x32_bf16 v[18:21], v[164:167], v[208:211], v[18:21]
	v_mfma_f32_16x16x32_bf16 v[6:9], v[156:159], v[216:219], v[6:9]
	v_mfma_f32_16x16x32_bf16 v[2:5], v[164:167], v[216:219], v[2:5]
	s_setprio 0
	s_setprio 1
	v_mfma_f32_16x16x32_bf16 v[66:69], v[168:171], v[188:191], v[66:69]
	v_mfma_f32_16x16x32_bf16 v[58:61], v[176:179], v[188:191], v[58:61]
	v_mfma_f32_16x16x32_bf16 v[46:49], v[168:171], v[196:199], v[46:49]
	v_mfma_f32_16x16x32_bf16 v[42:45], v[176:179], v[196:199], v[42:45]
	v_mfma_f32_16x16x32_bf16 v[30:33], v[168:171], v[204:207], v[30:33]
	v_mfma_f32_16x16x32_bf16 v[26:29], v[176:179], v[204:207], v[26:29]
	v_mfma_f32_16x16x32_bf16 v[14:17], v[168:171], v[212:215], v[14:17]
	v_mfma_f32_16x16x32_bf16 v[10:13], v[176:179], v[212:215], v[10:13]
	v_mfma_f32_16x16x32_bf16 v[66:69], v[172:175], v[192:195], v[66:69]
	v_mfma_f32_16x16x32_bf16 v[58:61], v[180:183], v[192:195], v[58:61]
	v_mfma_f32_16x16x32_bf16 v[46:49], v[172:175], v[200:203], v[46:49]
	v_mfma_f32_16x16x32_bf16 v[42:45], v[180:183], v[200:203], v[42:45]
	v_mfma_f32_16x16x32_bf16 v[30:33], v[172:175], v[208:211], v[30:33]
	v_mfma_f32_16x16x32_bf16 v[26:29], v[180:183], v[208:211], v[26:29]
	v_mfma_f32_16x16x32_bf16 v[14:17], v[172:175], v[216:219], v[14:17]
	v_mfma_f32_16x16x32_bf16 v[10:13], v[180:183], v[216:219], v[10:13]
	s_setprio 0
	s_barrier
	ds_read_b128 v[152:155], v149
	ds_read_b128 v[156:159], v149 offset:1024
	ds_read_b128 v[160:163], v149 offset:2048
	ds_read_b128 v[164:167], v149 offset:3072
	ds_read_b128 v[168:171], v150
	ds_read_b128 v[172:175], v150 offset:1024
	ds_read_b128 v[176:179], v150 offset:2048
	ds_read_b128 v[180:183], v150 offset:3072
	s_mov_b32 m0, s80
	v_lshl_add_u64 v[222:223], v[220:221], 0, s[24:25]
	ds_read_b128 v[188:191], v147 offset:32768
	ds_read_b128 v[192:195], v147 offset:33792
	ds_read_b128 v[196:199], v147 offset:34816
	ds_read_b128 v[200:203], v147 offset:35840
	ds_read_b128 v[204:207], v147 offset:36864
	ds_read_b128 v[208:211], v147 offset:37888
	ds_read_b128 v[212:215], v147 offset:38912
	ds_read_b128 v[216:219], v147 offset:39936
	global_load_lds_dwordx4 v[222:223], off
	v_lshl_add_u64 v[222:223], v[220:221], 0, s[26:27]
	s_mov_b32 m0, s81
	s_nop 0
	global_load_lds_dwordx4 v[222:223], off
	s_waitcnt vmcnt(8)
	s_waitcnt lgkmcnt(0)
	s_waitcnt lgkmcnt(0)
	v_mfma_f32_16x16x32_bf16 v[118:121], v[152:155], v[188:191], v[118:121]
	v_mfma_f32_16x16x32_bf16 v[114:117], v[160:163], v[188:191], v[114:117]
	v_mfma_f32_16x16x32_bf16 v[102:105], v[152:155], v[196:199], v[102:105]
	s_barrier
	s_setprio 1
	v_mfma_f32_16x16x32_bf16 v[98:101], v[160:163], v[196:199], v[98:101]
	v_mfma_f32_16x16x32_bf16 v[86:89], v[152:155], v[204:207], v[86:89]
	v_mfma_f32_16x16x32_bf16 v[82:85], v[160:163], v[204:207], v[82:85]
	v_mfma_f32_16x16x32_bf16 v[70:73], v[152:155], v[212:215], v[70:73]
	v_mfma_f32_16x16x32_bf16 v[62:65], v[160:163], v[212:215], v[62:65]
	v_mfma_f32_16x16x32_bf16 v[118:121], v[156:159], v[192:195], v[118:121]
	v_mfma_f32_16x16x32_bf16 v[114:117], v[164:167], v[192:195], v[114:117]
	v_mfma_f32_16x16x32_bf16 v[102:105], v[156:159], v[200:203], v[102:105]
	v_mfma_f32_16x16x32_bf16 v[98:101], v[164:167], v[200:203], v[98:101]
	v_mfma_f32_16x16x32_bf16 v[86:89], v[156:159], v[208:211], v[86:89]
	v_mfma_f32_16x16x32_bf16 v[82:85], v[164:167], v[208:211], v[82:85]
	v_mfma_f32_16x16x32_bf16 v[70:73], v[156:159], v[216:219], v[70:73]
	v_mfma_f32_16x16x32_bf16 v[62:65], v[164:167], v[216:219], v[62:65]
	s_setprio 0
	s_setprio 1
	v_mfma_f32_16x16x32_bf16 v[126:129], v[168:171], v[188:191], v[126:129]
	v_mfma_f32_16x16x32_bf16 v[122:125], v[176:179], v[188:191], v[122:125]
	v_mfma_f32_16x16x32_bf16 v[110:113], v[168:171], v[196:199], v[110:113]
	v_mfma_f32_16x16x32_bf16 v[106:109], v[176:179], v[196:199], v[106:109]
	v_mfma_f32_16x16x32_bf16 v[94:97], v[168:171], v[204:207], v[94:97]
	v_mfma_f32_16x16x32_bf16 v[90:93], v[176:179], v[204:207], v[90:93]
	v_mfma_f32_16x16x32_bf16 v[78:81], v[168:171], v[212:215], v[78:81]
	v_mfma_f32_16x16x32_bf16 v[74:77], v[176:179], v[212:215], v[74:77]
	v_mfma_f32_16x16x32_bf16 v[126:129], v[172:175], v[192:195], v[126:129]
	v_mfma_f32_16x16x32_bf16 v[122:125], v[180:183], v[192:195], v[122:125]
	v_mfma_f32_16x16x32_bf16 v[110:113], v[172:175], v[200:203], v[110:113]
	v_mfma_f32_16x16x32_bf16 v[106:109], v[180:183], v[200:203], v[106:109]
	v_mfma_f32_16x16x32_bf16 v[94:97], v[172:175], v[208:211], v[94:97]
	v_mfma_f32_16x16x32_bf16 v[90:93], v[180:183], v[208:211], v[90:93]
	v_mfma_f32_16x16x32_bf16 v[78:81], v[172:175], v[216:219], v[78:81]
	v_mfma_f32_16x16x32_bf16 v[74:77], v[180:183], v[216:219], v[74:77]
	s_setprio 0
	s_barrier
	s_mov_b32 m0, s12
	v_lshl_add_u64 v[222:223], v[184:185], 0, s[30:31]
	ds_read_b128 v[188:191], v147 offset:49152
	ds_read_b128 v[192:195], v147 offset:50176
	ds_read_b128 v[196:199], v147 offset:51200
	ds_read_b128 v[200:203], v147 offset:52224
	ds_read_b128 v[204:207], v147 offset:53248
	ds_read_b128 v[208:211], v147 offset:54272
	ds_read_b128 v[212:215], v147 offset:55296
	ds_read_b128 v[216:219], v147 offset:56320
	global_load_lds_dwordx4 v[222:223], off
	v_lshl_add_u64 v[222:223], v[184:185], 0, s[34:35]
	s_mov_b32 m0, s13
	s_nop 0
	global_load_lds_dwordx4 v[222:223], off
	v_lshl_add_u64 v[222:223], v[184:185], 0, s[38:39]
	s_mov_b32 m0, s3
	v_lshl_add_u64 v[184:185], v[184:185], 0, s[40:41]
	global_load_lds_dwordx4 v[222:223], off
	s_mov_b32 m0, s36
	s_nop 0
	global_load_lds_dwordx4 v[184:185], off
	v_lshl_add_u64 v[184:185], v[220:221], 0, s[30:31]
	s_mov_b32 m0, s86
	s_nop 0
	global_load_lds_dwordx4 v[184:185], off
	v_lshl_add_u64 v[184:185], v[220:221], 0, s[34:35]
	s_mov_b32 m0, s87
	s_nop 0
	global_load_lds_dwordx4 v[184:185], off
	s_waitcnt vmcnt(8)
	s_waitcnt lgkmcnt(0)
	s_waitcnt lgkmcnt(0)
	v_mfma_f32_16x16x32_bf16 v[54:57], v[152:155], v[188:191], v[54:57]
	v_mfma_f32_16x16x32_bf16 v[50:53], v[160:163], v[188:191], v[50:53]
	v_mfma_f32_16x16x32_bf16 v[38:41], v[152:155], v[196:199], v[38:41]
	s_barrier
	s_setprio 1
	v_mfma_f32_16x16x32_bf16 v[34:37], v[160:163], v[196:199], v[34:37]
	v_mfma_f32_16x16x32_bf16 v[22:25], v[152:155], v[204:207], v[22:25]
	v_mfma_f32_16x16x32_bf16 v[18:21], v[160:163], v[204:207], v[18:21]
	v_mfma_f32_16x16x32_bf16 v[6:9], v[152:155], v[212:215], v[6:9]
	v_mfma_f32_16x16x32_bf16 v[2:5], v[160:163], v[212:215], v[2:5]
	v_mfma_f32_16x16x32_bf16 v[54:57], v[156:159], v[192:195], v[54:57]
	v_mfma_f32_16x16x32_bf16 v[50:53], v[164:167], v[192:195], v[50:53]
	v_mfma_f32_16x16x32_bf16 v[38:41], v[156:159], v[200:203], v[38:41]
	v_mfma_f32_16x16x32_bf16 v[34:37], v[164:167], v[200:203], v[34:37]
	v_mfma_f32_16x16x32_bf16 v[22:25], v[156:159], v[208:211], v[22:25]
	v_mfma_f32_16x16x32_bf16 v[18:21], v[164:167], v[208:211], v[18:21]
	v_mfma_f32_16x16x32_bf16 v[6:9], v[156:159], v[216:219], v[6:9]
	v_mfma_f32_16x16x32_bf16 v[2:5], v[164:167], v[216:219], v[2:5]
	s_setprio 0
	s_setprio 1
	v_mfma_f32_16x16x32_bf16 v[66:69], v[168:171], v[188:191], v[66:69]
	v_mfma_f32_16x16x32_bf16 v[58:61], v[176:179], v[188:191], v[58:61]
	v_mfma_f32_16x16x32_bf16 v[46:49], v[168:171], v[196:199], v[46:49]
	v_mfma_f32_16x16x32_bf16 v[42:45], v[176:179], v[196:199], v[42:45]
	v_mfma_f32_16x16x32_bf16 v[30:33], v[168:171], v[204:207], v[30:33]
	v_mfma_f32_16x16x32_bf16 v[26:29], v[176:179], v[204:207], v[26:29]
	v_mfma_f32_16x16x32_bf16 v[14:17], v[168:171], v[212:215], v[14:17]
	v_mfma_f32_16x16x32_bf16 v[10:13], v[176:179], v[212:215], v[10:13]
	v_mfma_f32_16x16x32_bf16 v[66:69], v[172:175], v[192:195], v[66:69]
	v_mfma_f32_16x16x32_bf16 v[58:61], v[180:183], v[192:195], v[58:61]
	v_mfma_f32_16x16x32_bf16 v[46:49], v[172:175], v[200:203], v[46:49]
	v_mfma_f32_16x16x32_bf16 v[42:45], v[180:183], v[200:203], v[42:45]
	v_mfma_f32_16x16x32_bf16 v[30:33], v[172:175], v[208:211], v[30:33]
	v_mfma_f32_16x16x32_bf16 v[26:29], v[180:183], v[208:211], v[26:29]
	v_mfma_f32_16x16x32_bf16 v[14:17], v[172:175], v[216:219], v[14:17]
	v_mfma_f32_16x16x32_bf16 v[10:13], v[180:183], v[216:219], v[10:13]
	s_setprio 0
	s_barrier
	s_add_i32 s37, s37, 2
	s_add_u32 s6, s6, 0x100
	s_addc_u32 s7, s7, 0
	s_cmp_gt_u32 s37, 13
	s_cbranch_scc0 .LBB0_1718
	s_and_b64 vcc, exec, s[44:45]
	s_cbranch_vccz .LBB0_1721
	s_barrier

.LBB0_2127:
	ds_read_b128 v[2:5], v223
	ds_read_b128 v[6:9], v223 offset:1024
	ds_read_b128 v[10:13], v223 offset:2048
	ds_read_b128 v[14:17], v223 offset:3072
	ds_read_b128 v[18:21], v224
	ds_read_b128 v[22:25], v224 offset:1024
	ds_read_b128 v[26:29], v224 offset:2048
	ds_read_b128 v[30:33], v224 offset:3072
	s_add_u32 s17, s26, 0x100
	s_addc_u32 s33, s27, 0
	s_add_u32 s40, s20, 0x100
	s_addc_u32 s58, s21, 0
	s_cmp_eq_u32 s74, 2
	s_cselect_b32 s37, s35, s33
	s_cselect_b32 s36, s34, s17
	s_cselect_b32 s59, s39, s58
	s_cselect_b32 s58, s38, s40
	v_lshl_add_u64 v[66:67], s[26:27], 0, v[194:195]
	s_add_i32 s17, s78, 0xc000
	v_lshl_add_u64 v[68:69], v[66:67], 0, s[50:51]
	s_mov_b32 m0, s17
	s_add_i32 s40, s78, 0xe000
	ds_read_b128 v[34:37], v225
	ds_read_b128 v[38:41], v225 offset:1024
	ds_read_b128 v[42:45], v225 offset:2048
	ds_read_b128 v[46:49], v225 offset:3072
	ds_read_b128 v[50:53], v225 offset:4096
	ds_read_b128 v[54:57], v225 offset:5120
	ds_read_b128 v[58:61], v225 offset:6144
	ds_read_b128 v[62:65], v225 offset:7168
	global_load_lds_dwordx4 v[68:69], off
	v_lshl_add_u64 v[66:67], v[66:67], 0, s[52:53]
	s_mov_b32 m0, s40
	s_nop 0
	global_load_lds_dwordx4 v[66:67], off
	s_waitcnt vmcnt(8)
	s_waitcnt lgkmcnt(0)
	s_waitcnt lgkmcnt(0)
	v_mfma_f32_16x16x32_bf16 v[90:93], v[2:5], v[58:61], 0
	v_mfma_f32_16x16x32_bf16 v[66:69], v[2:5], v[34:37], 0
	v_mfma_f32_16x16x32_bf16 v[70:73], v[10:13], v[34:37], 0
	s_barrier
	s_setprio 1
	v_mfma_f32_16x16x32_bf16 v[74:77], v[2:5], v[42:45], 0
	v_mfma_f32_16x16x32_bf16 v[78:81], v[10:13], v[42:45], 0
	v_mfma_f32_16x16x32_bf16 v[82:85], v[2:5], v[50:53], 0
	v_mfma_f32_16x16x32_bf16 v[86:89], v[10:13], v[50:53], 0
	v_mfma_f32_16x16x32_bf16 v[98:101], v[6:9], v[62:65], v[90:93]
	v_mfma_f32_16x16x32_bf16 v[90:93], v[10:13], v[58:61], 0
	v_mfma_f32_16x16x32_bf16 v[66:69], v[6:9], v[38:41], v[66:69]
	v_mfma_f32_16x16x32_bf16 v[70:73], v[14:17], v[38:41], v[70:73]
	v_mfma_f32_16x16x32_bf16 v[74:77], v[6:9], v[46:49], v[74:77]
	v_mfma_f32_16x16x32_bf16 v[78:81], v[14:17], v[46:49], v[78:81]
	v_mfma_f32_16x16x32_bf16 v[82:85], v[6:9], v[54:57], v[82:85]
	v_mfma_f32_16x16x32_bf16 v[86:89], v[14:17], v[54:57], v[86:89]
	v_mfma_f32_16x16x32_bf16 v[102:105], v[14:17], v[62:65], v[90:93]
	s_setprio 0
	s_setprio 1
	v_mfma_f32_16x16x32_bf16 v[90:93], v[18:21], v[34:37], 0
	v_mfma_f32_16x16x32_bf16 v[34:37], v[26:29], v[34:37], 0
	v_mfma_f32_16x16x32_bf16 v[114:117], v[22:25], v[38:41], v[90:93]
	v_mfma_f32_16x16x32_bf16 v[34:37], v[30:33], v[38:41], v[34:37]
	v_mfma_f32_16x16x32_bf16 v[38:41], v[18:21], v[42:45], 0
	v_mfma_f32_16x16x32_bf16 v[42:45], v[26:29], v[42:45], 0
	v_mfma_f32_16x16x32_bf16 v[38:41], v[22:25], v[46:49], v[38:41]
	v_mfma_f32_16x16x32_bf16 v[42:45], v[30:33], v[46:49], v[42:45]
	v_mfma_f32_16x16x32_bf16 v[46:49], v[18:21], v[50:53], 0
	v_mfma_f32_16x16x32_bf16 v[50:53], v[26:29], v[50:53], 0
	v_mfma_f32_16x16x32_bf16 v[46:49], v[22:25], v[54:57], v[46:49]
	v_mfma_f32_16x16x32_bf16 v[50:53], v[30:33], v[54:57], v[50:53]
	v_mfma_f32_16x16x32_bf16 v[54:57], v[18:21], v[58:61], 0
	v_mfma_f32_16x16x32_bf16 v[58:61], v[26:29], v[58:61], 0
	v_mfma_f32_16x16x32_bf16 v[54:57], v[22:25], v[62:65], v[54:57]
	v_mfma_f32_16x16x32_bf16 v[58:61], v[30:33], v[62:65], v[58:61]
	s_setprio 0
	s_barrier
	s_add_i32 s60, s86, s75
	v_lshl_add_u64 v[192:193], s[58:59], 0, v[196:197]
	s_mov_b32 m0, s60
	s_add_i32 s61, s60, 0x2000
	ds_read_b128 v[62:65], v225 offset:16384
	ds_read_b128 v[90:93], v225 offset:17408
	ds_read_b128 v[94:97], v225 offset:18432
	ds_read_b128 v[106:109], v225 offset:19456
	ds_read_b128 v[110:113], v225 offset:20480
	ds_read_b128 v[118:121], v225 offset:21504
	ds_read_b128 v[122:125], v225 offset:22528
	ds_read_b128 v[126:129], v225 offset:23552
	global_load_lds_dwordx4 v[192:193], off
	v_lshl_add_u64 v[130:131], v[192:193], 0, s[18:19]
	s_mov_b32 m0, s61
	s_add_i32 s62, s87, s75
	global_load_lds_dwordx4 v[130:131], off
	v_lshl_add_u64 v[130:131], v[192:193], 0, s[22:23]
	s_mov_b32 m0, s62
	s_add_i32 s63, s62, 0x2000
	global_load_lds_dwordx4 v[130:131], off
	v_lshl_add_u64 v[130:131], v[192:193], 0, s[24:25]
	s_mov_b32 m0, s63
	v_lshl_add_u64 v[248:249], s[36:37], 0, v[194:195]
	global_load_lds_dwordx4 v[130:131], off
	s_mov_b32 m0, s78
	v_lshl_add_u64 v[130:131], v[248:249], 0, s[18:19]
	global_load_lds_dwordx4 v[248:249], off
	s_mov_b32 m0, s79
	s_nop 0
	global_load_lds_dwordx4 v[130:131], off
	s_waitcnt vmcnt(8)
	s_waitcnt lgkmcnt(0)
	s_waitcnt lgkmcnt(0)
	v_mfma_f32_16x16x32_bf16 v[130:133], v[2:5], v[62:65], 0
	v_mfma_f32_16x16x32_bf16 v[140:143], v[2:5], v[94:97], 0
	v_mfma_f32_16x16x32_bf16 v[148:151], v[2:5], v[110:113], 0
	s_barrier
	s_setprio 1
	v_mfma_f32_16x16x32_bf16 v[2:5], v[2:5], v[122:125], 0
	v_mfma_f32_16x16x32_bf16 v[132:135], v[6:9], v[90:93], v[130:133]
	v_mfma_f32_16x16x32_bf16 v[140:143], v[6:9], v[106:109], v[140:143]
	v_mfma_f32_16x16x32_bf16 v[148:151], v[6:9], v[118:121], v[148:151]
	v_mfma_f32_16x16x32_bf16 v[2:5], v[6:9], v[126:129], v[2:5]
	v_mfma_f32_16x16x32_bf16 v[6:9], v[10:13], v[122:125], 0
	v_mfma_f32_16x16x32_bf16 v[136:139], v[10:13], v[62:65], 0
	v_mfma_f32_16x16x32_bf16 v[144:147], v[10:13], v[94:97], 0
	v_mfma_f32_16x16x32_bf16 v[152:155], v[10:13], v[110:113], 0
	v_mfma_f32_16x16x32_bf16 v[6:9], v[14:17], v[126:129], v[6:9]
	v_mfma_f32_16x16x32_bf16 v[136:139], v[14:17], v[90:93], v[136:139]
	v_mfma_f32_16x16x32_bf16 v[144:147], v[14:17], v[106:109], v[144:147]
	v_mfma_f32_16x16x32_bf16 v[152:155], v[14:17], v[118:121], v[152:155]
	s_setprio 0
	s_setprio 1
	v_mfma_f32_16x16x32_bf16 v[10:13], v[18:21], v[62:65], 0
	v_mfma_f32_16x16x32_bf16 v[156:159], v[22:25], v[90:93], v[10:13]
	v_mfma_f32_16x16x32_bf16 v[10:13], v[26:29], v[62:65], 0
	v_mfma_f32_16x16x32_bf16 v[160:163], v[30:33], v[90:93], v[10:13]
	v_mfma_f32_16x16x32_bf16 v[10:13], v[18:21], v[94:97], 0
	v_mfma_f32_16x16x32_bf16 v[164:167], v[22:25], v[106:109], v[10:13]
	v_mfma_f32_16x16x32_bf16 v[10:13], v[26:29], v[94:97], 0
	v_mfma_f32_16x16x32_bf16 v[168:171], v[30:33], v[106:109], v[10:13]
	v_mfma_f32_16x16x32_bf16 v[10:13], v[18:21], v[110:113], 0
	v_mfma_f32_16x16x32_bf16 v[172:175], v[22:25], v[118:121], v[10:13]
	v_mfma_f32_16x16x32_bf16 v[10:13], v[26:29], v[110:113], 0
	v_mfma_f32_16x16x32_bf16 v[176:179], v[30:33], v[118:121], v[10:13]
	v_mfma_f32_16x16x32_bf16 v[10:13], v[18:21], v[122:125], 0
	v_mfma_f32_16x16x32_bf16 v[180:183], v[22:25], v[126:129], v[10:13]
	v_mfma_f32_16x16x32_bf16 v[10:13], v[26:29], v[122:125], 0
	v_mfma_f32_16x16x32_bf16 v[184:187], v[30:33], v[126:129], v[10:13]
	s_setprio 0
	s_barrier
	s_add_i32 s33, 0, 0x18000
	s_add_i32 s65, 0, 0x1c000
	v_add_u32_e32 v130, s33, v218
	v_add_u32_e32 v131, s65, v218
	s_nop 0
	ds_read_b128 v[10:13], v130
	ds_read_b128 v[14:17], v130 offset:1024
	ds_read_b128 v[18:21], v130 offset:2048
	ds_read_b128 v[22:25], v130 offset:3072
	ds_read_b128 v[188:191], v131
	ds_read_b128 v[200:203], v131 offset:1024
	ds_read_b128 v[204:207], v131 offset:2048
	ds_read_b128 v[208:211], v131 offset:3072
	s_mov_b32 m0, s80
	v_lshl_add_u64 v[90:91], v[248:249], 0, s[22:23]
	ds_read_b128 v[26:29], v225 offset:32768
	ds_read_b128 v[30:33], v225 offset:33792
	ds_read_b128 v[62:65], v225 offset:34816
	ds_read_b128 v[212:215], v225 offset:35840
	ds_read_b128 v[228:231], v225 offset:36864
	ds_read_b128 v[232:235], v225 offset:37888
	ds_read_b128 v[236:239], v225 offset:38912
	ds_read_b128 v[240:243], v225 offset:39936
	global_load_lds_dwordx4 v[90:91], off
	v_lshl_add_u64 v[90:91], v[248:249], 0, s[24:25]
	s_mov_b32 m0, s81
	s_nop 0
	global_load_lds_dwordx4 v[90:91], off
	s_waitcnt vmcnt(8)
	s_waitcnt lgkmcnt(0)
	s_waitcnt lgkmcnt(0)
	v_mfma_f32_16x16x32_bf16 v[66:69], v[10:13], v[26:29], v[66:69]
	v_mfma_f32_16x16x32_bf16 v[126:129], v[14:17], v[30:33], v[66:69]
	v_mfma_f32_16x16x32_bf16 v[66:69], v[18:21], v[26:29], v[70:73]
	s_barrier
	s_setprio 1
	v_mfma_f32_16x16x32_bf16 v[122:125], v[22:25], v[30:33], v[66:69]
	v_mfma_f32_16x16x32_bf16 v[66:69], v[10:13], v[62:65], v[74:77]
	v_mfma_f32_16x16x32_bf16 v[110:113], v[14:17], v[212:215], v[66:69]
	v_mfma_f32_16x16x32_bf16 v[66:69], v[18:21], v[62:65], v[78:81]
	v_mfma_f32_16x16x32_bf16 v[106:109], v[22:25], v[212:215], v[66:69]
	v_mfma_f32_16x16x32_bf16 v[66:69], v[10:13], v[228:231], v[82:85]
	v_mfma_f32_16x16x32_bf16 v[94:97], v[14:17], v[232:235], v[66:69]
	v_mfma_f32_16x16x32_bf16 v[66:69], v[18:21], v[228:231], v[86:89]
	v_mfma_f32_16x16x32_bf16 v[90:93], v[22:25], v[232:235], v[66:69]
	v_mfma_f32_16x16x32_bf16 v[66:69], v[10:13], v[236:239], v[98:101]
	v_mfma_f32_16x16x32_bf16 v[78:81], v[14:17], v[240:243], v[66:69]
	v_mfma_f32_16x16x32_bf16 v[66:69], v[18:21], v[236:239], v[102:105]
	v_mfma_f32_16x16x32_bf16 v[74:77], v[22:25], v[240:243], v[66:69]
	s_setprio 0
	s_setprio 1
	v_mfma_f32_16x16x32_bf16 v[66:69], v[188:191], v[26:29], v[114:117]
	v_mfma_f32_16x16x32_bf16 v[26:29], v[204:207], v[26:29], v[34:37]
	v_mfma_f32_16x16x32_bf16 v[114:117], v[208:211], v[30:33], v[26:29]
	v_mfma_f32_16x16x32_bf16 v[26:29], v[188:191], v[62:65], v[38:41]
	v_mfma_f32_16x16x32_bf16 v[102:105], v[200:203], v[212:215], v[26:29]
	v_mfma_f32_16x16x32_bf16 v[26:29], v[204:207], v[62:65], v[42:45]
	v_mfma_f32_16x16x32_bf16 v[98:101], v[208:211], v[212:215], v[26:29]
	v_mfma_f32_16x16x32_bf16 v[26:29], v[188:191], v[228:231], v[46:49]
	v_mfma_f32_16x16x32_bf16 v[86:89], v[200:203], v[232:235], v[26:29]
	v_mfma_f32_16x16x32_bf16 v[26:29], v[204:207], v[228:231], v[50:53]
	v_mfma_f32_16x16x32_bf16 v[82:85], v[208:211], v[232:235], v[26:29]
	v_mfma_f32_16x16x32_bf16 v[26:29], v[188:191], v[236:239], v[54:57]
	v_mfma_f32_16x16x32_bf16 v[70:73], v[200:203], v[240:243], v[26:29]
	v_mfma_f32_16x16x32_bf16 v[26:29], v[204:207], v[236:239], v[58:61]
	v_mfma_f32_16x16x32_bf16 v[118:121], v[200:203], v[30:33], v[66:69]
	v_mfma_f32_16x16x32_bf16 v[62:65], v[208:211], v[240:243], v[26:29]
	s_setprio 0
	s_barrier
	s_add_i32 s33, s33, s75
	s_nop 2
	v_lshl_add_u64 v[26:27], v[192:193], 0, s[46:47]
	s_mov_b32 m0, s33
	s_add_i32 s64, s33, 0x2000
	ds_read_b128 v[34:37], v225 offset:49152
	ds_read_b128 v[38:41], v225 offset:50176
	ds_read_b128 v[212:215], v225 offset:51200
	ds_read_b128 v[228:231], v225 offset:52224
	ds_read_b128 v[232:235], v225 offset:53248
	ds_read_b128 v[236:239], v225 offset:54272
	ds_read_b128 v[240:243], v225 offset:55296
	ds_read_b128 v[244:247], v225 offset:56320
	global_load_lds_dwordx4 v[26:27], off
	v_lshl_add_u64 v[26:27], v[192:193], 0, s[48:49]
	s_mov_b32 m0, s64
	s_add_i32 s65, s65, s75
	global_load_lds_dwordx4 v[26:27], off
	v_lshl_add_u64 v[26:27], v[192:193], 0, s[50:51]
	s_mov_b32 m0, s65
	s_add_i32 s66, s65, 0x2000
	global_load_lds_dwordx4 v[26:27], off
	v_lshl_add_u64 v[26:27], v[192:193], 0, s[52:53]
	s_mov_b32 m0, s66
	s_nop 0
	global_load_lds_dwordx4 v[26:27], off
	v_lshl_add_u64 v[26:27], v[248:249], 0, s[46:47]
	s_mov_b32 m0, s90
	s_nop 0
	global_load_lds_dwordx4 v[26:27], off
	v_lshl_add_u64 v[26:27], v[248:249], 0, s[48:49]
	s_mov_b32 m0, s91
	s_nop 0
	global_load_lds_dwordx4 v[26:27], off
	s_waitcnt vmcnt(8)
	s_waitcnt lgkmcnt(0)
	s_waitcnt lgkmcnt(0)
	v_mfma_f32_16x16x32_bf16 v[26:29], v[10:13], v[34:37], v[132:135]
	v_mfma_f32_16x16x32_bf16 v[66:69], v[14:17], v[38:41], v[26:29]
	v_mfma_f32_16x16x32_bf16 v[26:29], v[18:21], v[34:37], v[136:139]
	s_barrier
	s_setprio 1
	v_mfma_f32_16x16x32_bf16 v[58:61], v[22:25], v[38:41], v[26:29]
	v_mfma_f32_16x16x32_bf16 v[26:29], v[10:13], v[212:215], v[140:143]
	v_mfma_f32_16x16x32_bf16 v[46:49], v[14:17], v[228:231], v[26:29]
	v_mfma_f32_16x16x32_bf16 v[26:29], v[18:21], v[212:215], v[144:147]
	v_mfma_f32_16x16x32_bf16 v[42:45], v[22:25], v[228:231], v[26:29]
	v_mfma_f32_16x16x32_bf16 v[26:29], v[10:13], v[232:235], v[148:151]
	v_mfma_f32_16x16x32_bf16 v[2:5], v[10:13], v[240:243], v[2:5]
	v_mfma_f32_16x16x32_bf16 v[30:33], v[14:17], v[236:239], v[26:29]
	v_mfma_f32_16x16x32_bf16 v[26:29], v[18:21], v[232:235], v[152:155]
	v_mfma_f32_16x16x32_bf16 v[14:17], v[14:17], v[244:247], v[2:5]
	v_mfma_f32_16x16x32_bf16 v[2:5], v[18:21], v[240:243], v[6:9]
	v_mfma_f32_16x16x32_bf16 v[26:29], v[22:25], v[236:239], v[26:29]
	v_mfma_f32_16x16x32_bf16 v[10:13], v[22:25], v[244:247], v[2:5]
	s_setprio 0
	s_setprio 1
	v_mfma_f32_16x16x32_bf16 v[2:5], v[188:191], v[34:37], v[156:159]
	v_mfma_f32_16x16x32_bf16 v[54:57], v[200:203], v[38:41], v[2:5]
	v_mfma_f32_16x16x32_bf16 v[2:5], v[204:207], v[34:37], v[160:163]
	v_mfma_f32_16x16x32_bf16 v[50:53], v[208:211], v[38:41], v[2:5]
	v_mfma_f32_16x16x32_bf16 v[2:5], v[188:191], v[212:215], v[164:167]
	v_mfma_f32_16x16x32_bf16 v[38:41], v[200:203], v[228:231], v[2:5]
	v_mfma_f32_16x16x32_bf16 v[2:5], v[204:207], v[212:215], v[168:171]
	v_mfma_f32_16x16x32_bf16 v[34:37], v[208:211], v[228:231], v[2:5]
	v_mfma_f32_16x16x32_bf16 v[2:5], v[188:191], v[232:235], v[172:175]
	v_mfma_f32_16x16x32_bf16 v[22:25], v[200:203], v[236:239], v[2:5]
	v_mfma_f32_16x16x32_bf16 v[2:5], v[204:207], v[232:235], v[176:179]
	v_mfma_f32_16x16x32_bf16 v[18:21], v[208:211], v[236:239], v[2:5]
	v_mfma_f32_16x16x32_bf16 v[2:5], v[188:191], v[240:243], v[180:183]
	v_mfma_f32_16x16x32_bf16 v[6:9], v[200:203], v[244:247], v[2:5]
	v_mfma_f32_16x16x32_bf16 v[2:5], v[204:207], v[240:243], v[184:187]
	v_mfma_f32_16x16x32_bf16 v[2:5], v[208:211], v[244:247], v[2:5]
	s_setprio 0
	s_barrier
	s_cmp_lt_i32 s74, 3
	s_cbranch_scc1 .LBB0_2130
	s_add_u32 s58, s26, 0xb0180
	s_addc_u32 s59, s27, 0
	s_add_u32 s36, s20, 0x200
	s_addc_u32 s37, s21, 0
	s_mov_b32 s67, 4
.LBB0_2129:
	ds_read_b128 v[132:135], v223
	ds_read_b128 v[136:139], v223 offset:1024
	ds_read_b128 v[140:143], v223 offset:2048
	ds_read_b128 v[144:147], v223 offset:3072
	ds_read_b128 v[148:151], v224
	ds_read_b128 v[152:155], v224 offset:1024
	ds_read_b128 v[156:159], v224 offset:2048
	ds_read_b128 v[160:163], v224 offset:3072
	s_add_u32 s84, s58, 0xfff50080
	s_addc_u32 s85, s59, -1
	s_cmp_eq_u32 s74, s67
	s_cselect_b32 vcc_hi, s35, s85
	s_cselect_b32 vcc_lo, s34, s84
	s_cselect_b32 s85, s39, s37
	s_cselect_b32 s84, s38, s36
	s_mov_b32 m0, s17
	v_lshl_add_u64 v[192:193], s[58:59], 0, v[198:199]
	ds_read_b128 v[164:167], v225
	ds_read_b128 v[168:171], v225 offset:1024
	ds_read_b128 v[172:175], v225 offset:2048
	ds_read_b128 v[176:179], v225 offset:3072
	ds_read_b128 v[180:183], v225 offset:4096
	ds_read_b128 v[184:187], v225 offset:5120
	ds_read_b128 v[188:191], v225 offset:6144
	ds_read_b128 v[200:203], v225 offset:7168
	global_load_lds_dwordx4 v[192:193], off
	v_lshl_add_u64 v[192:193], v[192:193], 0, s[18:19]
	s_mov_b32 m0, s40
	s_nop 0
	global_load_lds_dwordx4 v[192:193], off
	s_waitcnt vmcnt(8)
	s_waitcnt lgkmcnt(0)
	s_waitcnt lgkmcnt(0)
	v_mfma_f32_16x16x32_bf16 v[126:129], v[132:135], v[164:167], v[126:129]
	v_mfma_f32_16x16x32_bf16 v[122:125], v[140:143], v[164:167], v[122:125]
	v_mfma_f32_16x16x32_bf16 v[110:113], v[132:135], v[172:175], v[110:113]
	s_barrier
	s_setprio 1
	v_mfma_f32_16x16x32_bf16 v[106:109], v[140:143], v[172:175], v[106:109]
	v_mfma_f32_16x16x32_bf16 v[94:97], v[132:135], v[180:183], v[94:97]
	v_mfma_f32_16x16x32_bf16 v[90:93], v[140:143], v[180:183], v[90:93]
	v_mfma_f32_16x16x32_bf16 v[78:81], v[132:135], v[188:191], v[78:81]
	v_mfma_f32_16x16x32_bf16 v[74:77], v[140:143], v[188:191], v[74:77]
	v_mfma_f32_16x16x32_bf16 v[126:129], v[136:139], v[168:171], v[126:129]
	v_mfma_f32_16x16x32_bf16 v[122:125], v[144:147], v[168:171], v[122:125]
	v_mfma_f32_16x16x32_bf16 v[110:113], v[136:139], v[176:179], v[110:113]
	v_mfma_f32_16x16x32_bf16 v[106:109], v[144:147], v[176:179], v[106:109]
	v_mfma_f32_16x16x32_bf16 v[94:97], v[136:139], v[184:187], v[94:97]
	v_mfma_f32_16x16x32_bf16 v[90:93], v[144:147], v[184:187], v[90:93]
	v_mfma_f32_16x16x32_bf16 v[78:81], v[136:139], v[200:203], v[78:81]
	v_mfma_f32_16x16x32_bf16 v[74:77], v[144:147], v[200:203], v[74:77]
	s_setprio 0
	s_setprio 1
	v_mfma_f32_16x16x32_bf16 v[118:121], v[148:151], v[164:167], v[118:121]
	v_mfma_f32_16x16x32_bf16 v[114:117], v[156:159], v[164:167], v[114:117]
	v_mfma_f32_16x16x32_bf16 v[102:105], v[148:151], v[172:175], v[102:105]
	v_mfma_f32_16x16x32_bf16 v[98:101], v[156:159], v[172:175], v[98:101]
	v_mfma_f32_16x16x32_bf16 v[86:89], v[148:151], v[180:183], v[86:89]
	v_mfma_f32_16x16x32_bf16 v[82:85], v[156:159], v[180:183], v[82:85]
	v_mfma_f32_16x16x32_bf16 v[70:73], v[148:151], v[188:191], v[70:73]
	v_mfma_f32_16x16x32_bf16 v[62:65], v[156:159], v[188:191], v[62:65]
	v_mfma_f32_16x16x32_bf16 v[118:121], v[152:155], v[168:171], v[118:121]
	v_mfma_f32_16x16x32_bf16 v[114:117], v[160:163], v[168:171], v[114:117]
	v_mfma_f32_16x16x32_bf16 v[102:105], v[152:155], v[176:179], v[102:105]
	v_mfma_f32_16x16x32_bf16 v[98:101], v[160:163], v[176:179], v[98:101]
	v_mfma_f32_16x16x32_bf16 v[86:89], v[152:155], v[184:187], v[86:89]
	v_mfma_f32_16x16x32_bf16 v[82:85], v[160:163], v[184:187], v[82:85]
	v_mfma_f32_16x16x32_bf16 v[70:73], v[152:155], v[200:203], v[70:73]
	v_mfma_f32_16x16x32_bf16 v[62:65], v[160:163], v[200:203], v[62:65]
	s_setprio 0
	s_barrier
	s_mov_b32 m0, s60
	v_lshl_add_u64 v[192:193], s[84:85], 0, v[196:197]
	ds_read_b128 v[164:167], v225 offset:16384
	ds_read_b128 v[168:171], v225 offset:17408
	ds_read_b128 v[172:175], v225 offset:18432
	ds_read_b128 v[176:179], v225 offset:19456
	ds_read_b128 v[180:183], v225 offset:20480
	ds_read_b128 v[184:187], v225 offset:21504
	ds_read_b128 v[188:191], v225 offset:22528
	ds_read_b128 v[200:203], v225 offset:23552
	global_load_lds_dwordx4 v[192:193], off
	v_lshl_add_u64 v[204:205], v[192:193], 0, s[18:19]
	s_mov_b32 m0, s61
	s_nop 0
	global_load_lds_dwordx4 v[204:205], off
	v_lshl_add_u64 v[204:205], v[192:193], 0, s[22:23]
	s_mov_b32 m0, s62
	s_nop 0
	global_load_lds_dwordx4 v[204:205], off
	v_lshl_add_u64 v[204:205], v[192:193], 0, s[24:25]
	s_mov_b32 m0, s63
	s_nop 0
	global_load_lds_dwordx4 v[204:205], off
	v_lshl_add_u64 v[204:205], vcc, 0, v[194:195]
	s_mov_b32 m0, s78
	v_lshl_add_u64 v[206:207], v[204:205], 0, s[18:19]
	global_load_lds_dwordx4 v[204:205], off
	s_mov_b32 m0, s79
	s_nop 0
	global_load_lds_dwordx4 v[206:207], off
	s_waitcnt vmcnt(8)
	s_waitcnt lgkmcnt(0)
	s_waitcnt lgkmcnt(0)
	v_mfma_f32_16x16x32_bf16 v[66:69], v[132:135], v[164:167], v[66:69]
	v_mfma_f32_16x16x32_bf16 v[58:61], v[140:143], v[164:167], v[58:61]
	v_mfma_f32_16x16x32_bf16 v[46:49], v[132:135], v[172:175], v[46:49]
	s_barrier
	s_setprio 1
	v_mfma_f32_16x16x32_bf16 v[42:45], v[140:143], v[172:175], v[42:45]
	v_mfma_f32_16x16x32_bf16 v[30:33], v[132:135], v[180:183], v[30:33]
	v_mfma_f32_16x16x32_bf16 v[26:29], v[140:143], v[180:183], v[26:29]
	v_mfma_f32_16x16x32_bf16 v[14:17], v[132:135], v[188:191], v[14:17]
	v_mfma_f32_16x16x32_bf16 v[10:13], v[140:143], v[188:191], v[10:13]
	v_mfma_f32_16x16x32_bf16 v[66:69], v[136:139], v[168:171], v[66:69]
	v_mfma_f32_16x16x32_bf16 v[58:61], v[144:147], v[168:171], v[58:61]
	v_mfma_f32_16x16x32_bf16 v[46:49], v[136:139], v[176:179], v[46:49]
	v_mfma_f32_16x16x32_bf16 v[42:45], v[144:147], v[176:179], v[42:45]
	v_mfma_f32_16x16x32_bf16 v[30:33], v[136:139], v[184:187], v[30:33]
	v_mfma_f32_16x16x32_bf16 v[26:29], v[144:147], v[184:187], v[26:29]
	v_mfma_f32_16x16x32_bf16 v[14:17], v[136:139], v[200:203], v[14:17]
	v_mfma_f32_16x16x32_bf16 v[10:13], v[144:147], v[200:203], v[10:13]
	s_setprio 0
	s_setprio 1
	v_mfma_f32_16x16x32_bf16 v[54:57], v[148:151], v[164:167], v[54:57]
	v_mfma_f32_16x16x32_bf16 v[50:53], v[156:159], v[164:167], v[50:53]
	v_mfma_f32_16x16x32_bf16 v[38:41], v[148:151], v[172:175], v[38:41]
	v_mfma_f32_16x16x32_bf16 v[34:37], v[156:159], v[172:175], v[34:37]
	v_mfma_f32_16x16x32_bf16 v[22:25], v[148:151], v[180:183], v[22:25]
	v_mfma_f32_16x16x32_bf16 v[18:21], v[156:159], v[180:183], v[18:21]
	v_mfma_f32_16x16x32_bf16 v[6:9], v[148:151], v[188:191], v[6:9]
	v_mfma_f32_16x16x32_bf16 v[2:5], v[156:159], v[188:191], v[2:5]
	v_mfma_f32_16x16x32_bf16 v[54:57], v[152:155], v[168:171], v[54:57]
	v_mfma_f32_16x16x32_bf16 v[50:53], v[160:163], v[168:171], v[50:53]
	v_mfma_f32_16x16x32_bf16 v[38:41], v[152:155], v[176:179], v[38:41]
	v_mfma_f32_16x16x32_bf16 v[34:37], v[160:163], v[176:179], v[34:37]
	v_mfma_f32_16x16x32_bf16 v[22:25], v[152:155], v[184:187], v[22:25]
	v_mfma_f32_16x16x32_bf16 v[18:21], v[160:163], v[184:187], v[18:21]
	v_mfma_f32_16x16x32_bf16 v[6:9], v[152:155], v[200:203], v[6:9]
	v_mfma_f32_16x16x32_bf16 v[2:5], v[160:163], v[200:203], v[2:5]
	s_setprio 0
	s_barrier
	ds_read_b128 v[132:135], v130
	ds_read_b128 v[136:139], v130 offset:1024
	ds_read_b128 v[140:143], v130 offset:2048
	ds_read_b128 v[144:147], v130 offset:3072
	ds_read_b128 v[148:151], v131
	ds_read_b128 v[152:155], v131 offset:1024
	ds_read_b128 v[156:159], v131 offset:2048
	ds_read_b128 v[160:163], v131 offset:3072
	s_mov_b32 m0, s80
	v_lshl_add_u64 v[206:207], v[204:205], 0, s[22:23]
	ds_read_b128 v[164:167], v225 offset:32768
	ds_read_b128 v[168:171], v225 offset:33792
	ds_read_b128 v[172:175], v225 offset:34816
	ds_read_b128 v[176:179], v225 offset:35840
	ds_read_b128 v[180:183], v225 offset:36864
	ds_read_b128 v[184:187], v225 offset:37888
	ds_read_b128 v[188:191], v225 offset:38912
	ds_read_b128 v[200:203], v225 offset:39936
	global_load_lds_dwordx4 v[206:207], off
	v_lshl_add_u64 v[206:207], v[204:205], 0, s[24:25]
	s_mov_b32 m0, s81
	s_nop 0
	global_load_lds_dwordx4 v[206:207], off
	s_waitcnt vmcnt(8)
	s_waitcnt lgkmcnt(0)
	s_waitcnt lgkmcnt(0)
	v_mfma_f32_16x16x32_bf16 v[126:129], v[132:135], v[164:167], v[126:129]
	v_mfma_f32_16x16x32_bf16 v[122:125], v[140:143], v[164:167], v[122:125]
	v_mfma_f32_16x16x32_bf16 v[110:113], v[132:135], v[172:175], v[110:113]
	s_barrier
	s_setprio 1
	v_mfma_f32_16x16x32_bf16 v[106:109], v[140:143], v[172:175], v[106:109]
	v_mfma_f32_16x16x32_bf16 v[94:97], v[132:135], v[180:183], v[94:97]
	v_mfma_f32_16x16x32_bf16 v[90:93], v[140:143], v[180:183], v[90:93]
	v_mfma_f32_16x16x32_bf16 v[78:81], v[132:135], v[188:191], v[78:81]
	v_mfma_f32_16x16x32_bf16 v[74:77], v[140:143], v[188:191], v[74:77]
	v_mfma_f32_16x16x32_bf16 v[126:129], v[136:139], v[168:171], v[126:129]
	v_mfma_f32_16x16x32_bf16 v[122:125], v[144:147], v[168:171], v[122:125]
	v_mfma_f32_16x16x32_bf16 v[110:113], v[136:139], v[176:179], v[110:113]
	v_mfma_f32_16x16x32_bf16 v[106:109], v[144:147], v[176:179], v[106:109]
	v_mfma_f32_16x16x32_bf16 v[94:97], v[136:139], v[184:187], v[94:97]
	v_mfma_f32_16x16x32_bf16 v[90:93], v[144:147], v[184:187], v[90:93]
	v_mfma_f32_16x16x32_bf16 v[78:81], v[136:139], v[200:203], v[78:81]
	v_mfma_f32_16x16x32_bf16 v[74:77], v[144:147], v[200:203], v[74:77]
	s_setprio 0
	s_setprio 1
	v_mfma_f32_16x16x32_bf16 v[118:121], v[148:151], v[164:167], v[118:121]
	v_mfma_f32_16x16x32_bf16 v[114:117], v[156:159], v[164:167], v[114:117]
	v_mfma_f32_16x16x32_bf16 v[102:105], v[148:151], v[172:175], v[102:105]
	v_mfma_f32_16x16x32_bf16 v[98:101], v[156:159], v[172:175], v[98:101]
	v_mfma_f32_16x16x32_bf16 v[86:89], v[148:151], v[180:183], v[86:89]
	v_mfma_f32_16x16x32_bf16 v[82:85], v[156:159], v[180:183], v[82:85]
	v_mfma_f32_16x16x32_bf16 v[70:73], v[148:151], v[188:191], v[70:73]
	v_mfma_f32_16x16x32_bf16 v[62:65], v[156:159], v[188:191], v[62:65]
	v_mfma_f32_16x16x32_bf16 v[118:121], v[152:155], v[168:171], v[118:121]
	v_mfma_f32_16x16x32_bf16 v[114:117], v[160:163], v[168:171], v[114:117]
	v_mfma_f32_16x16x32_bf16 v[102:105], v[152:155], v[176:179], v[102:105]
	v_mfma_f32_16x16x32_bf16 v[98:101], v[160:163], v[176:179], v[98:101]
	v_mfma_f32_16x16x32_bf16 v[86:89], v[152:155], v[184:187], v[86:89]
	v_mfma_f32_16x16x32_bf16 v[82:85], v[160:163], v[184:187], v[82:85]
	v_mfma_f32_16x16x32_bf16 v[70:73], v[152:155], v[200:203], v[70:73]
	v_mfma_f32_16x16x32_bf16 v[62:65], v[160:163], v[200:203], v[62:65]
	s_setprio 0
	s_barrier
	s_mov_b32 m0, s33
	v_lshl_add_u64 v[206:207], v[192:193], 0, s[46:47]
	ds_read_b128 v[164:167], v225 offset:49152
	ds_read_b128 v[168:171], v225 offset:50176
	ds_read_b128 v[172:175], v225 offset:51200
	ds_read_b128 v[176:179], v225 offset:52224
	ds_read_b128 v[180:183], v225 offset:53248
	ds_read_b128 v[184:187], v225 offset:54272
	ds_read_b128 v[188:191], v225 offset:55296
	ds_read_b128 v[200:203], v225 offset:56320
	global_load_lds_dwordx4 v[206:207], off
	v_lshl_add_u64 v[206:207], v[192:193], 0, s[48:49]
	s_mov_b32 m0, s64
	s_nop 0
	global_load_lds_dwordx4 v[206:207], off
	v_lshl_add_u64 v[206:207], v[192:193], 0, s[50:51]
	s_mov_b32 m0, s65
	v_lshl_add_u64 v[192:193], v[192:193], 0, s[52:53]
	global_load_lds_dwordx4 v[206:207], off
	s_mov_b32 m0, s66
	s_nop 0
	global_load_lds_dwordx4 v[192:193], off
	v_lshl_add_u64 v[192:193], v[204:205], 0, s[46:47]
	s_mov_b32 m0, s90
	s_nop 0
	global_load_lds_dwordx4 v[192:193], off
	v_lshl_add_u64 v[192:193], v[204:205], 0, s[48:49]
	s_mov_b32 m0, s91
	s_nop 0
	global_load_lds_dwordx4 v[192:193], off
	s_waitcnt vmcnt(8)
	s_waitcnt lgkmcnt(0)
	s_waitcnt lgkmcnt(0)
	v_mfma_f32_16x16x32_bf16 v[66:69], v[132:135], v[164:167], v[66:69]
	v_mfma_f32_16x16x32_bf16 v[58:61], v[140:143], v[164:167], v[58:61]
	v_mfma_f32_16x16x32_bf16 v[46:49], v[132:135], v[172:175], v[46:49]
	s_barrier
	s_setprio 1
	v_mfma_f32_16x16x32_bf16 v[42:45], v[140:143], v[172:175], v[42:45]
	v_mfma_f32_16x16x32_bf16 v[30:33], v[132:135], v[180:183], v[30:33]
	v_mfma_f32_16x16x32_bf16 v[26:29], v[140:143], v[180:183], v[26:29]
	v_mfma_f32_16x16x32_bf16 v[14:17], v[132:135], v[188:191], v[14:17]
	v_mfma_f32_16x16x32_bf16 v[10:13], v[140:143], v[188:191], v[10:13]
	v_mfma_f32_16x16x32_bf16 v[66:69], v[136:139], v[168:171], v[66:69]
	v_mfma_f32_16x16x32_bf16 v[58:61], v[144:147], v[168:171], v[58:61]
	v_mfma_f32_16x16x32_bf16 v[46:49], v[136:139], v[176:179], v[46:49]
	v_mfma_f32_16x16x32_bf16 v[42:45], v[144:147], v[176:179], v[42:45]
	v_mfma_f32_16x16x32_bf16 v[30:33], v[136:139], v[184:187], v[30:33]
	v_mfma_f32_16x16x32_bf16 v[26:29], v[144:147], v[184:187], v[26:29]
	v_mfma_f32_16x16x32_bf16 v[14:17], v[136:139], v[200:203], v[14:17]
	v_mfma_f32_16x16x32_bf16 v[10:13], v[144:147], v[200:203], v[10:13]
	s_setprio 0
	s_setprio 1
	v_mfma_f32_16x16x32_bf16 v[54:57], v[148:151], v[164:167], v[54:57]
	v_mfma_f32_16x16x32_bf16 v[50:53], v[156:159], v[164:167], v[50:53]
	v_mfma_f32_16x16x32_bf16 v[38:41], v[148:151], v[172:175], v[38:41]
	v_mfma_f32_16x16x32_bf16 v[34:37], v[156:159], v[172:175], v[34:37]
	v_mfma_f32_16x16x32_bf16 v[22:25], v[148:151], v[180:183], v[22:25]
	v_mfma_f32_16x16x32_bf16 v[18:21], v[156:159], v[180:183], v[18:21]
	v_mfma_f32_16x16x32_bf16 v[6:9], v[148:151], v[188:191], v[6:9]
	v_mfma_f32_16x16x32_bf16 v[2:5], v[156:159], v[188:191], v[2:5]
	v_mfma_f32_16x16x32_bf16 v[54:57], v[152:155], v[168:171], v[54:57]
	v_mfma_f32_16x16x32_bf16 v[50:53], v[160:163], v[168:171], v[50:53]
	v_mfma_f32_16x16x32_bf16 v[38:41], v[152:155], v[176:179], v[38:41]
	v_mfma_f32_16x16x32_bf16 v[34:37], v[160:163], v[176:179], v[34:37]
	v_mfma_f32_16x16x32_bf16 v[22:25], v[152:155], v[184:187], v[22:25]
	v_mfma_f32_16x16x32_bf16 v[18:21], v[160:163], v[184:187], v[18:21]
	v_mfma_f32_16x16x32_bf16 v[6:9], v[152:155], v[200:203], v[6:9]
	v_mfma_f32_16x16x32_bf16 v[2:5], v[160:163], v[200:203], v[2:5]
	s_setprio 0
	s_barrier
	s_add_i32 s84, s67, 2
	s_add_u32 s58, s58, 0x100
	s_addc_u32 s59, s59, 0
	s_add_u32 s36, s36, 0x100
	s_addc_u32 s37, s37, 0
	s_cmp_ge_i32 s67, s74
	s_mov_b32 s67, s84
	s_cbranch_scc0 .LBB0_2129
